# v23
# speedup vs baseline: 1.0021x; 1.0021x over previous
; #define WAIT_V(n) asm volatile("s_waitcnt vmcnt(" #n ")" ::: "memory")
; #define WAIT_L(n) asm volatile("s_waitcnt lgkmcnt(" #n ")" ::: "memory")
; #define BAR __builtin_amdgcn_s_barrier()
; #define SCHED __builtin_amdgcn_sched_barrier(0)
; __device__ __forceinline__ void mainloop_8phase(const u16* __restrict__ A, const u16* __restrict__ Bt, int K,
;                                                 f32x4 (&acc)[2][2][4][2], int wid_s, int ld) {
;     ...
;     LDB(B0, 0, 0); SCHED; LDA(At, 0, 0); STAGE(SA(1, 1), A, brow + G_HALF, t + 1);
;     WAIT_L(8); BAR; WAIT_L(0); MMA(0, 0, At, B0); BAR; SCHED;
;     LDB(B1, 0, 1); STAGE(SB(0, 0), Bt, bcol, t + 2);
;     BAR; WAIT_L(0); MMA(0, 1, At, B1); BAR;
;     LDA(At, 0, 1); STAGE(SA(0, 0), A, brow, t + 2);
;     BAR; WAIT_L(0); MMA(1, 0, At, B0); BAR; SCHED;
;     STAGE(SB(0, 1), Bt, bcol + G_HALF, t + 2);
;     WAIT_V(6); BAR; MMA(1, 1, At, B1); BAR;
.LBB0_58:
	ds_read_b128 v[156:159], v155
	ds_read_b128 v[160:163], v155 offset:1024
	ds_read_b128 v[164:167], v155 offset:2048
	ds_read_b128 v[168:171], v155 offset:3072
	s_add_i32 s6, s1, 0xffffff00
	s_add_i32 m0, s100, 0xc000
	ds_read_b128 v[172:175], v133
	ds_read_b128 v[176:179], v133 offset:1024
	ds_read_b128 v[180:183], v132
	ds_read_b128 v[184:187], v132 offset:1024
	ds_read_b128 v[188:191], v131
	ds_read_b128 v[192:195], v131 offset:1024
	ds_read_b128 v[196:199], v130
	buffer_load_dwordx4 v137, s[88:91], s6 offen lds
	s_add_i32 m0, s100, 0xe000
	ds_read_b128 v[200:203], v130 offset:1024
	buffer_load_dwordx4 v136, s[88:91], s6 offen lds
	s_waitcnt lgkmcnt(8)
	s_barrier
	s_waitcnt lgkmcnt(1)
	v_mfma_f32_16x16x32_bf16 v[126:129], v[172:175], v[156:159], v[126:129]
	v_mfma_f32_16x16x32_bf16 v[122:125], v[172:175], v[164:167], v[122:125]
	v_mfma_f32_16x16x32_bf16 v[118:121], v[180:183], v[156:159], v[118:121]
	v_mfma_f32_16x16x32_bf16 v[114:117], v[180:183], v[164:167], v[114:117]
	v_mfma_f32_16x16x32_bf16 v[110:113], v[188:191], v[156:159], v[110:113]
	v_mfma_f32_16x16x32_bf16 v[106:109], v[188:191], v[164:167], v[106:109]
	v_mfma_f32_16x16x32_bf16 v[102:105], v[196:199], v[156:159], v[102:105]
	v_mfma_f32_16x16x32_bf16 v[98:101], v[196:199], v[164:167], v[98:101]
	v_mfma_f32_16x16x32_bf16 v[126:129], v[176:179], v[160:163], v[126:129]
	v_mfma_f32_16x16x32_bf16 v[122:125], v[176:179], v[168:171], v[122:125]
	v_mfma_f32_16x16x32_bf16 v[118:121], v[184:187], v[160:163], v[118:121]
	v_mfma_f32_16x16x32_bf16 v[114:117], v[184:187], v[168:171], v[114:117]
	v_mfma_f32_16x16x32_bf16 v[110:113], v[192:195], v[160:163], v[110:113]
	v_mfma_f32_16x16x32_bf16 v[106:109], v[192:195], v[168:171], v[106:109]
	s_waitcnt lgkmcnt(0)
	v_mfma_f32_16x16x32_bf16 v[102:105], v[200:203], v[160:163], v[102:105]
	v_mfma_f32_16x16x32_bf16 v[98:101], v[200:203], v[168:171], v[98:101]
	s_barrier
	s_add_i32 s15, s1, 0xfff7ff80
	s_mov_b32 s6, s90
	s_add_i32 m0, s100, 0x10000
	ds_read_b128 v[204:207], v147
	ds_read_b128 v[208:211], v147 offset:1024
	ds_read_b128 v[212:215], v147 offset:2048
	buffer_load_dwordx4 v137, s[4:7], s15 offen lds
	s_add_i32 m0, s100, 0x12000
	ds_read_b128 v[216:219], v147 offset:3072
	buffer_load_dwordx4 v136, s[4:7], s15 offen lds
	s_barrier
	s_waitcnt lgkmcnt(1)
	v_mfma_f32_16x16x32_bf16 v[94:97], v[172:175], v[204:207], v[94:97]
	v_mfma_f32_16x16x32_bf16 v[90:93], v[172:175], v[212:215], v[90:93]
	v_mfma_f32_16x16x32_bf16 v[86:89], v[180:183], v[204:207], v[86:89]
	v_mfma_f32_16x16x32_bf16 v[82:85], v[180:183], v[212:215], v[82:85]
	v_mfma_f32_16x16x32_bf16 v[78:81], v[188:191], v[204:207], v[78:81]
	v_mfma_f32_16x16x32_bf16 v[74:77], v[188:191], v[212:215], v[74:77]
	v_mfma_f32_16x16x32_bf16 v[70:73], v[196:199], v[204:207], v[70:73]
	v_mfma_f32_16x16x32_bf16 v[66:69], v[196:199], v[212:215], v[66:69]
	v_mfma_f32_16x16x32_bf16 v[94:97], v[176:179], v[208:211], v[94:97]
	s_waitcnt lgkmcnt(0)
	v_mfma_f32_16x16x32_bf16 v[90:93], v[176:179], v[216:219], v[90:93]
	v_mfma_f32_16x16x32_bf16 v[86:89], v[184:187], v[208:211], v[86:89]
	v_mfma_f32_16x16x32_bf16 v[82:85], v[184:187], v[216:219], v[82:85]
	v_mfma_f32_16x16x32_bf16 v[78:81], v[192:195], v[208:211], v[78:81]
	v_mfma_f32_16x16x32_bf16 v[74:77], v[192:195], v[216:219], v[74:77]
	v_mfma_f32_16x16x32_bf16 v[70:73], v[200:203], v[208:211], v[70:73]
	v_mfma_f32_16x16x32_bf16 v[66:69], v[200:203], v[216:219], v[66:69]
	s_mov_b32 m0, s100
	s_barrier
	ds_read_b128 v[172:175], v133 offset:16384
	ds_read_b128 v[176:179], v133 offset:17408
	ds_read_b128 v[180:183], v132 offset:16384
	ds_read_b128 v[184:187], v132 offset:17408
	ds_read_b128 v[188:191], v131 offset:16384
	ds_read_b128 v[192:195], v131 offset:17408
	ds_read_b128 v[196:199], v130 offset:16384
	buffer_load_dwordx4 v137, s[88:91], s15 offen lds
	s_add_i32 m0, s100, 0x2000
	ds_read_b128 v[200:203], v130 offset:17408
	buffer_load_dwordx4 v136, s[88:91], s15 offen lds
	s_barrier
	s_waitcnt lgkmcnt(1)
	v_mfma_f32_16x16x32_bf16 v[62:65], v[172:175], v[156:159], v[62:65]
	v_mfma_f32_16x16x32_bf16 v[58:61], v[172:175], v[164:167], v[58:61]
	v_mfma_f32_16x16x32_bf16 v[54:57], v[180:183], v[156:159], v[54:57]
	v_mfma_f32_16x16x32_bf16 v[50:53], v[180:183], v[164:167], v[50:53]
	v_mfma_f32_16x16x32_bf16 v[46:49], v[188:191], v[156:159], v[46:49]
	v_mfma_f32_16x16x32_bf16 v[42:45], v[188:191], v[164:167], v[42:45]
	v_mfma_f32_16x16x32_bf16 v[38:41], v[196:199], v[156:159], v[38:41]
	v_mfma_f32_16x16x32_bf16 v[34:37], v[196:199], v[164:167], v[34:37]
	v_mfma_f32_16x16x32_bf16 v[62:65], v[176:179], v[160:163], v[62:65]
	v_mfma_f32_16x16x32_bf16 v[58:61], v[176:179], v[168:171], v[58:61]
	v_mfma_f32_16x16x32_bf16 v[54:57], v[184:187], v[160:163], v[54:57]
	v_mfma_f32_16x16x32_bf16 v[50:53], v[184:187], v[168:171], v[50:53]
	v_mfma_f32_16x16x32_bf16 v[46:49], v[192:195], v[160:163], v[46:49]
	v_mfma_f32_16x16x32_bf16 v[42:45], v[192:195], v[168:171], v[42:45]
	s_waitcnt lgkmcnt(0)
	v_mfma_f32_16x16x32_bf16 v[38:41], v[200:203], v[160:163], v[38:41]
	v_mfma_f32_16x16x32_bf16 v[34:37], v[200:203], v[168:171], v[34:37]
	s_barrier
	s_add_i32 m0, s100, 0x14000
	s_add_i32 s15, s1, 0xffffff80
	buffer_load_dwordx4 v137, s[4:7], s15 offen lds
	s_add_i32 m0, s100, 0x16000
	s_nop 0
	buffer_load_dwordx4 v136, s[4:7], s15 offen lds
	s_waitcnt vmcnt(6)
	s_barrier
; #define WAIT_V(n) asm volatile("s_waitcnt vmcnt(" #n ")" ::: "memory")
; #define WAIT_L(n) asm volatile("s_waitcnt lgkmcnt(" #n ")" ::: "memory")
; #define BAR __builtin_amdgcn_s_barrier()
; #define SCHED __builtin_amdgcn_sched_barrier(0)
; __device__ __forceinline__ void mainloop_8phase(const u16* __restrict__ A, const u16* __restrict__ Bt, int K,
;                                                 f32x4 (&acc)[2][2][4][2], int wid_s, int ld) {
;     ...
;     WAIT_V(6); BAR; MMA(1, 1, At, B1); BAR;
;     LDB(B0, 1, 0); SCHED; LDA(At, 1, 0); STAGE(SA(0, 1), A, brow + G_HALF, t + 2);
;     WAIT_L(8); BAR; WAIT_L(0); MMA(0, 0, At, B0); BAR; SCHED;
;     LDB(B1, 1, 1); STAGE(SB(1, 0), Bt, bcol, t + 3);
;     BAR; WAIT_L(0); MMA(0, 1, At, B1); BAR;
;     LDA(At, 1, 1); STAGE(SA(1, 0), A, brow, t + 3);
;     BAR; WAIT_L(0); MMA(1, 0, At, B0); BAR; SCHED;
	v_mfma_f32_16x16x32_bf16 v[30:33], v[172:175], v[204:207], v[30:33]
	v_mfma_f32_16x16x32_bf16 v[26:29], v[172:175], v[212:215], v[26:29]
	v_mfma_f32_16x16x32_bf16 v[22:25], v[180:183], v[204:207], v[22:25]
	v_mfma_f32_16x16x32_bf16 v[18:21], v[180:183], v[212:215], v[18:21]
	v_mfma_f32_16x16x32_bf16 v[14:17], v[188:191], v[204:207], v[14:17]
	v_mfma_f32_16x16x32_bf16 v[10:13], v[188:191], v[212:215], v[10:13]
	v_mfma_f32_16x16x32_bf16 v[6:9], v[196:199], v[204:207], v[6:9]
	v_mfma_f32_16x16x32_bf16 v[2:5], v[196:199], v[212:215], v[2:5]
	v_mfma_f32_16x16x32_bf16 v[30:33], v[176:179], v[208:211], v[30:33]
	v_mfma_f32_16x16x32_bf16 v[26:29], v[176:179], v[216:219], v[26:29]
	v_mfma_f32_16x16x32_bf16 v[22:25], v[184:187], v[208:211], v[22:25]
	v_mfma_f32_16x16x32_bf16 v[18:21], v[184:187], v[216:219], v[18:21]
	v_mfma_f32_16x16x32_bf16 v[14:17], v[192:195], v[208:211], v[14:17]
	v_mfma_f32_16x16x32_bf16 v[10:13], v[192:195], v[216:219], v[10:13]
	v_mfma_f32_16x16x32_bf16 v[6:9], v[200:203], v[208:211], v[6:9]
	v_mfma_f32_16x16x32_bf16 v[2:5], v[200:203], v[216:219], v[2:5]
	s_barrier
	ds_read_b128 v[156:159], v135
	ds_read_b128 v[160:163], v135 offset:1024
	ds_read_b128 v[164:167], v135 offset:2048
	ds_read_b128 v[168:171], v135 offset:3072
	s_add_i32 m0, s100, 0x4000
	ds_read_b128 v[172:175], v133 offset:32768
	ds_read_b128 v[176:179], v133 offset:33792
	ds_read_b128 v[180:183], v132 offset:32768
	ds_read_b128 v[184:187], v132 offset:33792
	ds_read_b128 v[188:191], v131 offset:32768
	ds_read_b128 v[192:195], v131 offset:33792
	ds_read_b128 v[196:199], v130 offset:32768
	buffer_load_dwordx4 v137, s[88:91], s15 offen lds
	s_add_i32 m0, s100, 0x6000
	ds_read_b128 v[200:203], v130 offset:33792
	buffer_load_dwordx4 v136, s[88:91], s15 offen lds
	s_waitcnt lgkmcnt(8)
	s_barrier
	s_waitcnt lgkmcnt(1)
	v_mfma_f32_16x16x32_bf16 v[126:129], v[172:175], v[156:159], v[126:129]
	v_mfma_f32_16x16x32_bf16 v[122:125], v[172:175], v[164:167], v[122:125]
	v_mfma_f32_16x16x32_bf16 v[118:121], v[180:183], v[156:159], v[118:121]
	v_mfma_f32_16x16x32_bf16 v[114:117], v[180:183], v[164:167], v[114:117]
	v_mfma_f32_16x16x32_bf16 v[110:113], v[188:191], v[156:159], v[110:113]
	v_mfma_f32_16x16x32_bf16 v[106:109], v[188:191], v[164:167], v[106:109]
	v_mfma_f32_16x16x32_bf16 v[102:105], v[196:199], v[156:159], v[102:105]
	v_mfma_f32_16x16x32_bf16 v[98:101], v[196:199], v[164:167], v[98:101]
	v_mfma_f32_16x16x32_bf16 v[126:129], v[176:179], v[160:163], v[126:129]
	v_mfma_f32_16x16x32_bf16 v[122:125], v[176:179], v[168:171], v[122:125]
	v_mfma_f32_16x16x32_bf16 v[118:121], v[184:187], v[160:163], v[118:121]
	v_mfma_f32_16x16x32_bf16 v[114:117], v[184:187], v[168:171], v[114:117]
	v_mfma_f32_16x16x32_bf16 v[110:113], v[192:195], v[160:163], v[110:113]
	v_mfma_f32_16x16x32_bf16 v[106:109], v[192:195], v[168:171], v[106:109]
	s_waitcnt lgkmcnt(0)
	v_mfma_f32_16x16x32_bf16 v[102:105], v[200:203], v[160:163], v[102:105]
	v_mfma_f32_16x16x32_bf16 v[98:101], v[200:203], v[168:171], v[98:101]
	s_barrier
	s_add_i32 s15, s1, 0xfff80000
	s_add_i32 m0, s100, 0x18000
	ds_read_b128 v[204:207], v134
	ds_read_b128 v[208:211], v134 offset:1024
	ds_read_b128 v[212:215], v134 offset:2048
	buffer_load_dwordx4 v137, s[4:7], s15 offen lds
	s_add_i32 m0, s100, 0x1a000
	ds_read_b128 v[216:219], v134 offset:3072
	buffer_load_dwordx4 v136, s[4:7], s15 offen lds
	s_barrier
	s_waitcnt lgkmcnt(1)
	v_mfma_f32_16x16x32_bf16 v[94:97], v[172:175], v[204:207], v[94:97]
	v_mfma_f32_16x16x32_bf16 v[90:93], v[172:175], v[212:215], v[90:93]
	v_mfma_f32_16x16x32_bf16 v[86:89], v[180:183], v[204:207], v[86:89]
	v_mfma_f32_16x16x32_bf16 v[82:85], v[180:183], v[212:215], v[82:85]
	v_mfma_f32_16x16x32_bf16 v[78:81], v[188:191], v[204:207], v[78:81]
	v_mfma_f32_16x16x32_bf16 v[74:77], v[188:191], v[212:215], v[74:77]
	v_mfma_f32_16x16x32_bf16 v[70:73], v[196:199], v[204:207], v[70:73]
	v_mfma_f32_16x16x32_bf16 v[66:69], v[196:199], v[212:215], v[66:69]
	v_mfma_f32_16x16x32_bf16 v[94:97], v[176:179], v[208:211], v[94:97]
	s_waitcnt lgkmcnt(0)
	v_mfma_f32_16x16x32_bf16 v[90:93], v[176:179], v[216:219], v[90:93]
	v_mfma_f32_16x16x32_bf16 v[86:89], v[184:187], v[208:211], v[86:89]
	v_mfma_f32_16x16x32_bf16 v[82:85], v[184:187], v[216:219], v[82:85]
	v_mfma_f32_16x16x32_bf16 v[78:81], v[192:195], v[208:211], v[78:81]
	v_mfma_f32_16x16x32_bf16 v[74:77], v[192:195], v[216:219], v[74:77]
	v_mfma_f32_16x16x32_bf16 v[70:73], v[200:203], v[208:211], v[70:73]
	v_mfma_f32_16x16x32_bf16 v[66:69], v[200:203], v[216:219], v[66:69]
	s_add_i32 m0, s100, 0x8000
	s_barrier
	ds_read_b128 v[172:175], v133 offset:49152
	ds_read_b128 v[176:179], v133 offset:50176
	ds_read_b128 v[180:183], v132 offset:49152
	ds_read_b128 v[184:187], v132 offset:50176
	ds_read_b128 v[188:191], v131 offset:49152
	ds_read_b128 v[192:195], v131 offset:50176
	ds_read_b128 v[196:199], v130 offset:49152
	buffer_load_dwordx4 v137, s[88:91], s15 offen lds
	s_add_i32 m0, s100, 0xa000
	ds_read_b128 v[200:203], v130 offset:50176
	buffer_load_dwordx4 v136, s[88:91], s15 offen lds
	s_barrier
	s_waitcnt lgkmcnt(1)
	v_mfma_f32_16x16x32_bf16 v[62:65], v[172:175], v[156:159], v[62:65]
	v_mfma_f32_16x16x32_bf16 v[58:61], v[172:175], v[164:167], v[58:61]
	v_mfma_f32_16x16x32_bf16 v[54:57], v[180:183], v[156:159], v[54:57]
	v_mfma_f32_16x16x32_bf16 v[50:53], v[180:183], v[164:167], v[50:53]
	v_mfma_f32_16x16x32_bf16 v[46:49], v[188:191], v[156:159], v[46:49]
	v_mfma_f32_16x16x32_bf16 v[42:45], v[188:191], v[164:167], v[42:45]
	v_mfma_f32_16x16x32_bf16 v[38:41], v[196:199], v[156:159], v[38:41]
	v_mfma_f32_16x16x32_bf16 v[34:37], v[196:199], v[164:167], v[34:37]
	v_mfma_f32_16x16x32_bf16 v[62:65], v[176:179], v[160:163], v[62:65]
	v_mfma_f32_16x16x32_bf16 v[58:61], v[176:179], v[168:171], v[58:61]
	v_mfma_f32_16x16x32_bf16 v[54:57], v[184:187], v[160:163], v[54:57]
	v_mfma_f32_16x16x32_bf16 v[50:53], v[184:187], v[168:171], v[50:53]
	v_mfma_f32_16x16x32_bf16 v[46:49], v[192:195], v[160:163], v[46:49]
	v_mfma_f32_16x16x32_bf16 v[42:45], v[192:195], v[168:171], v[42:45]
	s_waitcnt lgkmcnt(0)
	v_mfma_f32_16x16x32_bf16 v[38:41], v[200:203], v[160:163], v[38:41]
	v_mfma_f32_16x16x32_bf16 v[34:37], v[200:203], v[168:171], v[34:37]
	s_barrier
; #define WAIT_V(n) asm volatile("s_waitcnt vmcnt(" #n ")" ::: "memory")
; #define WAIT_L(n) asm volatile("s_waitcnt lgkmcnt(" #n ")" ::: "memory")
; #define BAR __builtin_amdgcn_s_barrier()
; __device__ __forceinline__ void mainloop_8phase(const u16* __restrict__ A, const u16* __restrict__ Bt, int K,
;                                                 f32x4 (&acc)[2][2][4][2], int wid_s, int ld) {
;     ...
;     STAGE(SB(1, 1), Bt, bcol + G_HALF, t + 3);
;     WAIT_V(6); BAR; MMA(1, 1, At, B1); BAR;
;   }
;   { LDB(B0, 0, 0); LDA(At, 0, 0); STAGE(SA(1, 1), A, brow + G_HALF, nt - 1);
;     BAR; WAIT_L(0); MMA(0, 0, At, B0); BAR;
;     LDB(B1, 0, 1); BAR; WAIT_L(0); MMA(0, 1, At, B1); BAR;
;     LDA(At, 0, 1); WAIT_V(4); BAR; WAIT_L(0); MMA(1, 0, At, B0); MMA(1, 1, At, B1); BAR; }
	s_add_i32 m0, s100, 0x1c000
	s_nop 0
	buffer_load_dwordx4 v137, s[4:7], s1 offen lds
	s_add_i32 m0, s100, 0x1e000
	s_nop 0
	buffer_load_dwordx4 v136, s[4:7], s1 offen lds
	s_waitcnt vmcnt(6)
	s_barrier
	v_mfma_f32_16x16x32_bf16 v[30:33], v[172:175], v[204:207], v[30:33]
	v_mfma_f32_16x16x32_bf16 v[26:29], v[172:175], v[212:215], v[26:29]
	v_mfma_f32_16x16x32_bf16 v[22:25], v[180:183], v[204:207], v[22:25]
	v_mfma_f32_16x16x32_bf16 v[18:21], v[180:183], v[212:215], v[18:21]
	v_mfma_f32_16x16x32_bf16 v[14:17], v[188:191], v[204:207], v[14:17]
	v_mfma_f32_16x16x32_bf16 v[10:13], v[188:191], v[212:215], v[10:13]
	v_mfma_f32_16x16x32_bf16 v[6:9], v[196:199], v[204:207], v[6:9]
	v_mfma_f32_16x16x32_bf16 v[2:5], v[196:199], v[212:215], v[2:5]
	v_mfma_f32_16x16x32_bf16 v[30:33], v[176:179], v[208:211], v[30:33]
	v_mfma_f32_16x16x32_bf16 v[26:29], v[176:179], v[216:219], v[26:29]
	v_mfma_f32_16x16x32_bf16 v[22:25], v[184:187], v[208:211], v[22:25]
	v_mfma_f32_16x16x32_bf16 v[18:21], v[184:187], v[216:219], v[18:21]
	v_mfma_f32_16x16x32_bf16 v[14:17], v[192:195], v[208:211], v[14:17]
	v_mfma_f32_16x16x32_bf16 v[10:13], v[192:195], v[216:219], v[10:13]
	v_mfma_f32_16x16x32_bf16 v[6:9], v[200:203], v[208:211], v[6:9]
	v_mfma_f32_16x16x32_bf16 v[2:5], v[200:203], v[216:219], v[2:5]
	s_add_i32 s0, s0, 2
	s_addk_i32 s1, 0x100
	s_cmp_lt_u32 s0, 28
	s_barrier
	s_cbranch_scc1 .LBB0_58
	v_readfirstlane_b32 s0, v145
	s_mov_b32 m0, s0
	s_mov_b32 s1, 0x80f80
	v_readfirstlane_b32 s0, v144
	ds_read_b128 v[138:141], v155
	ds_read_b128 v[148:151], v155 offset:1024
	ds_read_b128 v[156:159], v155 offset:2048
	ds_read_b128 v[152:155], v155 offset:3072
	ds_read_b128 v[160:163], v133
	ds_read_b128 v[164:167], v133 offset:1024
	ds_read_b128 v[168:171], v132
	ds_read_b128 v[172:175], v132 offset:1024
	ds_read_b128 v[176:179], v131
	ds_read_b128 v[180:183], v131 offset:1024
	ds_read_b128 v[184:187], v130
	ds_read_b128 v[188:191], v130 offset:1024
	buffer_load_dwordx4 v137, s[88:91], s1 offen lds
	s_mov_b32 m0, s0
	s_nop 0
	buffer_load_dwordx4 v136, s[88:91], s1 offen lds
	s_barrier
	s_waitcnt lgkmcnt(0)
	v_mfma_f32_16x16x32_bf16 v[126:129], v[160:163], v[138:141], v[126:129]
	v_mfma_f32_16x16x32_bf16 v[122:125], v[160:163], v[156:159], v[122:125]
	v_mfma_f32_16x16x32_bf16 v[118:121], v[168:171], v[138:141], v[118:121]
	v_mfma_f32_16x16x32_bf16 v[114:117], v[168:171], v[156:159], v[114:117]
	v_mfma_f32_16x16x32_bf16 v[102:105], v[184:187], v[138:141], v[102:105]
	v_mfma_f32_16x16x32_bf16 v[98:101], v[184:187], v[156:159], v[98:101]
	v_mfma_f32_16x16x32_bf16 v[126:129], v[164:167], v[148:151], v[126:129]
	v_mfma_f32_16x16x32_bf16 v[122:125], v[164:167], v[152:155], v[122:125]
	v_mfma_f32_16x16x32_bf16 v[118:121], v[172:175], v[148:151], v[118:121]
	v_mfma_f32_16x16x32_bf16 v[114:117], v[172:175], v[152:155], v[114:117]
	v_mfma_f32_16x16x32_bf16 v[110:113], v[176:179], v[138:141], v[110:113]
	v_mfma_f32_16x16x32_bf16 v[106:109], v[176:179], v[156:159], v[106:109]
	v_mfma_f32_16x16x32_bf16 v[102:105], v[188:191], v[148:151], v[102:105]
	v_mfma_f32_16x16x32_bf16 v[98:101], v[188:191], v[152:155], v[98:101]
	v_mfma_f32_16x16x32_bf16 v[142:145], v[180:183], v[148:151], v[110:113]
	v_mfma_f32_16x16x32_bf16 v[192:195], v[180:183], v[152:155], v[106:109]
	s_barrier
	s_nop 0
	ds_read_b128 v[106:109], v147
	ds_read_b128 v[110:113], v147 offset:1024
	ds_read_b128 v[196:199], v147 offset:2048
	ds_read_b128 v[200:203], v147 offset:3072
	s_barrier
	s_waitcnt lgkmcnt(0)
	v_mfma_f32_16x16x32_bf16 v[86:89], v[168:171], v[106:109], v[86:89]
	v_mfma_f32_16x16x32_bf16 v[82:85], v[168:171], v[196:199], v[82:85]
	v_mfma_f32_16x16x32_bf16 v[70:73], v[184:187], v[106:109], v[70:73]
	v_mfma_f32_16x16x32_bf16 v[66:69], v[184:187], v[196:199], v[66:69]
	v_mfma_f32_16x16x32_bf16 v[94:97], v[160:163], v[106:109], v[94:97]
	v_mfma_f32_16x16x32_bf16 v[90:93], v[160:163], v[196:199], v[90:93]
	v_mfma_f32_16x16x32_bf16 v[86:89], v[172:175], v[110:113], v[86:89]
	v_mfma_f32_16x16x32_bf16 v[82:85], v[172:175], v[200:203], v[82:85]
	v_mfma_f32_16x16x32_bf16 v[78:81], v[176:179], v[106:109], v[78:81]
	v_mfma_f32_16x16x32_bf16 v[74:77], v[176:179], v[196:199], v[74:77]
	v_mfma_f32_16x16x32_bf16 v[70:73], v[188:191], v[110:113], v[70:73]
	v_mfma_f32_16x16x32_bf16 v[66:69], v[188:191], v[200:203], v[66:69]
	v_mfma_f32_16x16x32_bf16 v[204:207], v[164:167], v[110:113], v[94:97]
	v_mfma_f32_16x16x32_bf16 v[160:163], v[164:167], v[200:203], v[90:93]
	v_mfma_f32_16x16x32_bf16 v[164:167], v[180:183], v[110:113], v[78:81]
	v_mfma_f32_16x16x32_bf16 v[168:171], v[180:183], v[200:203], v[74:77]
	s_barrier
	s_nop 0
	ds_read_b128 v[74:77], v133 offset:16384
	ds_read_b128 v[78:81], v133 offset:17408
	ds_read_b128 v[90:93], v132 offset:16384
	ds_read_b128 v[94:97], v132 offset:17408
	ds_read_b128 v[172:175], v131 offset:16384
	ds_read_b128 v[176:179], v131 offset:17408
	ds_read_b128 v[180:183], v130 offset:16384
	ds_read_b128 v[184:187], v130 offset:17408
	s_waitcnt vmcnt(4)
	s_barrier
; #define WAIT_V(n) asm volatile("s_waitcnt vmcnt(" #n ")" ::: "memory")
; #define WAIT_L(n) asm volatile("s_waitcnt lgkmcnt(" #n ")" ::: "memory")
; #define BAR __builtin_amdgcn_s_barrier()
; __device__ __forceinline__ void mainloop_8phase(const u16* __restrict__ A, const u16* __restrict__ Bt, int K,
;                                                 f32x4 (&acc)[2][2][4][2], int wid_s, int ld) {
;     ...
;     LDA(At, 0, 1); WAIT_V(4); BAR; WAIT_L(0); MMA(1, 0, At, B0); MMA(1, 1, At, B1); BAR; }
;   { LDB(B0, 1, 0); LDA(At, 1, 0); WAIT_V(2); BAR; WAIT_L(0); MMA(0, 0, At, B0); BAR;
	s_waitcnt lgkmcnt(0)
	v_mfma_f32_16x16x32_bf16 v[62:65], v[74:77], v[138:141], v[62:65]
	v_mfma_f32_16x16x32_bf16 v[58:61], v[74:77], v[156:159], v[58:61]
	v_mfma_f32_16x16x32_bf16 v[54:57], v[90:93], v[138:141], v[54:57]
	v_mfma_f32_16x16x32_bf16 v[50:53], v[90:93], v[156:159], v[50:53]
	v_mfma_f32_16x16x32_bf16 v[38:41], v[180:183], v[138:141], v[38:41]
	v_mfma_f32_16x16x32_bf16 v[34:37], v[180:183], v[156:159], v[34:37]
	v_mfma_f32_16x16x32_bf16 v[62:65], v[78:81], v[148:151], v[62:65]
	v_mfma_f32_16x16x32_bf16 v[58:61], v[78:81], v[152:155], v[58:61]
	v_mfma_f32_16x16x32_bf16 v[54:57], v[94:97], v[148:151], v[54:57]
	v_mfma_f32_16x16x32_bf16 v[50:53], v[94:97], v[152:155], v[50:53]
	v_mfma_f32_16x16x32_bf16 v[46:49], v[172:175], v[138:141], v[46:49]
	v_mfma_f32_16x16x32_bf16 v[42:45], v[172:175], v[156:159], v[42:45]
	v_mfma_f32_16x16x32_bf16 v[38:41], v[184:187], v[148:151], v[38:41]
	v_mfma_f32_16x16x32_bf16 v[34:37], v[184:187], v[152:155], v[34:37]
	v_mfma_f32_16x16x32_bf16 v[188:191], v[176:179], v[148:151], v[46:49]
	v_mfma_f32_16x16x32_bf16 v[208:211], v[176:179], v[152:155], v[42:45]
	v_mfma_f32_16x16x32_bf16 v[22:25], v[90:93], v[106:109], v[22:25]
	v_mfma_f32_16x16x32_bf16 v[18:21], v[90:93], v[196:199], v[18:21]
	v_mfma_f32_16x16x32_bf16 v[6:9], v[180:183], v[106:109], v[6:9]
	v_mfma_f32_16x16x32_bf16 v[2:5], v[180:183], v[196:199], v[2:5]
	v_mfma_f32_16x16x32_bf16 v[30:33], v[74:77], v[106:109], v[30:33]
	v_mfma_f32_16x16x32_bf16 v[26:29], v[74:77], v[196:199], v[26:29]
	v_mfma_f32_16x16x32_bf16 v[22:25], v[94:97], v[110:113], v[22:25]
	v_mfma_f32_16x16x32_bf16 v[18:21], v[94:97], v[200:203], v[18:21]
	v_mfma_f32_16x16x32_bf16 v[14:17], v[172:175], v[106:109], v[14:17]
	v_mfma_f32_16x16x32_bf16 v[10:13], v[172:175], v[196:199], v[10:13]
	v_mfma_f32_16x16x32_bf16 v[6:9], v[184:187], v[110:113], v[6:9]
	v_mfma_f32_16x16x32_bf16 v[2:5], v[184:187], v[200:203], v[2:5]
	v_mfma_f32_16x16x32_bf16 v[136:139], v[78:81], v[110:113], v[30:33]
	v_mfma_f32_16x16x32_bf16 v[146:149], v[78:81], v[200:203], v[26:29]
	v_mfma_f32_16x16x32_bf16 v[150:153], v[176:179], v[110:113], v[14:17]
	v_mfma_f32_16x16x32_bf16 v[154:157], v[176:179], v[200:203], v[10:13]
	s_barrier
	s_nop 0
	ds_read_b128 v[10:13], v135
	ds_read_b128 v[14:17], v135 offset:1024
	ds_read_b128 v[172:175], v135 offset:2048
	ds_read_b128 v[176:179], v135 offset:3072
	ds_read_b128 v[26:29], v133 offset:32768
	ds_read_b128 v[30:33], v133 offset:33792
	ds_read_b128 v[42:45], v132 offset:32768
	ds_read_b128 v[46:49], v132 offset:33792
	ds_read_b128 v[180:183], v131 offset:32768
	ds_read_b128 v[184:187], v131 offset:33792
	ds_read_b128 v[196:199], v130 offset:32768
	ds_read_b128 v[200:203], v130 offset:33792
	s_waitcnt vmcnt(2)
	s_barrier
	s_waitcnt lgkmcnt(0)
	v_mfma_f32_16x16x32_bf16 v[74:77], v[26:29], v[10:13], v[126:129]
	v_mfma_f32_16x16x32_bf16 v[126:129], v[30:33], v[14:17], v[74:77]
	v_mfma_f32_16x16x32_bf16 v[74:77], v[26:29], v[172:175], v[122:125]
	v_mfma_f32_16x16x32_bf16 v[122:125], v[30:33], v[176:179], v[74:77]
	v_mfma_f32_16x16x32_bf16 v[74:77], v[42:45], v[10:13], v[118:121]
	v_mfma_f32_16x16x32_bf16 v[110:113], v[46:49], v[14:17], v[74:77]
	v_mfma_f32_16x16x32_bf16 v[74:77], v[42:45], v[172:175], v[114:117]
	v_mfma_f32_16x16x32_bf16 v[106:109], v[46:49], v[176:179], v[74:77]
	v_mfma_f32_16x16x32_bf16 v[74:77], v[180:183], v[10:13], v[142:145]
	v_mfma_f32_16x16x32_bf16 v[94:97], v[184:187], v[14:17], v[74:77]
	v_mfma_f32_16x16x32_bf16 v[74:77], v[180:183], v[172:175], v[192:195]
	v_mfma_f32_16x16x32_bf16 v[90:93], v[184:187], v[176:179], v[74:77]
	v_mfma_f32_16x16x32_bf16 v[74:77], v[196:199], v[10:13], v[102:105]
	v_mfma_f32_16x16x32_bf16 v[78:81], v[200:203], v[14:17], v[74:77]
	v_mfma_f32_16x16x32_bf16 v[74:77], v[196:199], v[172:175], v[98:101]
	v_mfma_f32_16x16x32_bf16 v[74:77], v[200:203], v[176:179], v[74:77]
	s_barrier
; #define WAIT_V(n) asm volatile("s_waitcnt vmcnt(" #n ")" ::: "memory")
; #define WAIT_L(n) asm volatile("s_waitcnt lgkmcnt(" #n ")" ::: "memory")
; #define BAR __builtin_amdgcn_s_barrier()
; __device__ __forceinline__ void mainloop_8phase(const u16* __restrict__ A, const u16* __restrict__ Bt, int K,
;                                                 f32x4 (&acc)[2][2][4][2], int wid_s, int ld) {
;     ...
;     LDB(B1, 1, 1); WAIT_V(0); BAR; WAIT_L(0); MMA(0, 1, At, B1); BAR;
;     LDA(At, 1, 1); BAR; WAIT_L(0); MMA(1, 0, At, B0); MMA(1, 1, At, B1); BAR; }
;   if (wr == 0) BAR;
	ds_read_b128 v[140:143], v134
	ds_read_b128 v[192:195], v134 offset:1024
	ds_read_b128 v[212:215], v134 offset:2048
	ds_read_b128 v[216:219], v134 offset:3072
	s_waitcnt vmcnt(0)
	s_barrier
	s_waitcnt lgkmcnt(0)
	v_mfma_f32_16x16x32_bf16 v[98:101], v[26:29], v[140:143], v[204:207]
	v_mfma_f32_16x16x32_bf16 v[26:29], v[26:29], v[212:215], v[160:163]
	v_mfma_f32_16x16x32_bf16 v[114:117], v[30:33], v[216:219], v[26:29]
	v_mfma_f32_16x16x32_bf16 v[26:29], v[42:45], v[140:143], v[86:89]
	v_mfma_f32_16x16x32_bf16 v[102:105], v[46:49], v[192:195], v[26:29]
	v_mfma_f32_16x16x32_bf16 v[26:29], v[42:45], v[212:215], v[82:85]
	v_mfma_f32_16x16x32_bf16 v[118:121], v[30:33], v[192:195], v[98:101]
	v_mfma_f32_16x16x32_bf16 v[98:101], v[46:49], v[216:219], v[26:29]
	v_mfma_f32_16x16x32_bf16 v[26:29], v[180:183], v[140:143], v[164:167]
	v_mfma_f32_16x16x32_bf16 v[86:89], v[184:187], v[192:195], v[26:29]
	v_mfma_f32_16x16x32_bf16 v[26:29], v[180:183], v[212:215], v[168:171]
	v_mfma_f32_16x16x32_bf16 v[82:85], v[184:187], v[216:219], v[26:29]
	v_mfma_f32_16x16x32_bf16 v[26:29], v[196:199], v[140:143], v[70:73]
	v_mfma_f32_16x16x32_bf16 v[70:73], v[200:203], v[192:195], v[26:29]
	v_mfma_f32_16x16x32_bf16 v[26:29], v[196:199], v[212:215], v[66:69]
	v_mfma_f32_16x16x32_bf16 v[66:69], v[200:203], v[216:219], v[26:29]
	s_barrier
	ds_read_b128 v[158:161], v133 offset:49152
	ds_read_b128 v[162:165], v133 offset:50176
	ds_read_b128 v[166:169], v132 offset:49152
	ds_read_b128 v[132:135], v132 offset:50176
	ds_read_b128 v[180:183], v131 offset:49152
	ds_read_b128 v[184:187], v131 offset:50176
	ds_read_b128 v[196:199], v130 offset:49152
	ds_read_b128 v[200:203], v130 offset:50176
	s_barrier
	s_waitcnt lgkmcnt(0)
	v_mfma_f32_16x16x32_bf16 v[26:29], v[158:161], v[10:13], v[62:65]
	v_mfma_f32_16x16x32_bf16 v[62:65], v[162:165], v[14:17], v[26:29]
	v_mfma_f32_16x16x32_bf16 v[26:29], v[158:161], v[172:175], v[58:61]
	v_mfma_f32_16x16x32_bf16 v[58:61], v[162:165], v[176:179], v[26:29]
	v_mfma_f32_16x16x32_bf16 v[26:29], v[166:169], v[10:13], v[54:57]
	v_mfma_f32_16x16x32_bf16 v[46:49], v[132:135], v[14:17], v[26:29]
	v_mfma_f32_16x16x32_bf16 v[26:29], v[166:169], v[172:175], v[50:53]
	v_mfma_f32_16x16x32_bf16 v[42:45], v[132:135], v[176:179], v[26:29]
	v_mfma_f32_16x16x32_bf16 v[26:29], v[180:183], v[10:13], v[188:191]
	v_mfma_f32_16x16x32_bf16 v[10:13], v[196:199], v[10:13], v[38:41]
	v_mfma_f32_16x16x32_bf16 v[30:33], v[184:187], v[14:17], v[26:29]
	v_mfma_f32_16x16x32_bf16 v[26:29], v[180:183], v[172:175], v[208:211]
	v_mfma_f32_16x16x32_bf16 v[14:17], v[200:203], v[14:17], v[10:13]
	v_mfma_f32_16x16x32_bf16 v[10:13], v[196:199], v[172:175], v[34:37]
	v_mfma_f32_16x16x32_bf16 v[26:29], v[184:187], v[176:179], v[26:29]
	v_mfma_f32_16x16x32_bf16 v[10:13], v[200:203], v[176:179], v[10:13]
	v_mfma_f32_16x16x32_bf16 v[34:37], v[158:161], v[140:143], v[136:139]
	v_mfma_f32_16x16x32_bf16 v[54:57], v[162:165], v[192:195], v[34:37]
	v_mfma_f32_16x16x32_bf16 v[34:37], v[158:161], v[212:215], v[146:149]
	v_mfma_f32_16x16x32_bf16 v[18:21], v[166:169], v[212:215], v[18:21]
	v_mfma_f32_16x16x32_bf16 v[50:53], v[162:165], v[216:219], v[34:37]
	v_mfma_f32_16x16x32_bf16 v[22:25], v[166:169], v[140:143], v[22:25]
	v_mfma_f32_16x16x32_bf16 v[34:37], v[132:135], v[216:219], v[18:21]
	v_mfma_f32_16x16x32_bf16 v[18:21], v[180:183], v[140:143], v[150:153]
	v_mfma_f32_16x16x32_bf16 v[38:41], v[132:135], v[192:195], v[22:25]
	v_mfma_f32_16x16x32_bf16 v[22:25], v[184:187], v[192:195], v[18:21]
	v_mfma_f32_16x16x32_bf16 v[18:21], v[180:183], v[212:215], v[154:157]
	v_mfma_f32_16x16x32_bf16 v[6:9], v[196:199], v[140:143], v[6:9]
	v_mfma_f32_16x16x32_bf16 v[2:5], v[196:199], v[212:215], v[2:5]
	v_mfma_f32_16x16x32_bf16 v[18:21], v[184:187], v[216:219], v[18:21]
	v_mfma_f32_16x16x32_bf16 v[6:9], v[200:203], v[192:195], v[6:9]
	v_mfma_f32_16x16x32_bf16 v[2:5], v[200:203], v[216:219], v[2:5]
	s_movk_i32 s0, 0x100
	v_cmp_gt_u32_e32 vcc, s0, v0
	s_barrier
	s_and_saveexec_b64 s[0:1], vcc
	s_cbranch_execz .LBB0_61
	s_barrier

; #define WAIT_V(n) asm volatile("s_waitcnt vmcnt(" #n ")" ::: "memory")
; #define WAIT_L(n) asm volatile("s_waitcnt lgkmcnt(" #n ")" ::: "memory")
; #define BAR __builtin_amdgcn_s_barrier()
; #define SCHED __builtin_amdgcn_sched_barrier(0)
; __device__ __forceinline__ void mainloop_8phase(const u16* __restrict__ A, const u16* __restrict__ Bt, int K,
;                                                 f32x4 (&acc)[2][2][4][2], int wid_s, int ld) {
;     ...
;     LDB(B0, 0, 0); SCHED; LDA(At, 0, 0); STAGE(SA(1, 1), A, brow + G_HALF, t + 1);
;     WAIT_L(8); BAR; WAIT_L(0); MMA(0, 0, At, B0); BAR; SCHED;
;     LDB(B1, 0, 1); STAGE(SB(0, 0), Bt, bcol, t + 2);
;     BAR; WAIT_L(0); MMA(0, 1, At, B1); BAR;
;     LDA(At, 0, 1); STAGE(SA(0, 0), A, brow, t + 2);
;     BAR; WAIT_L(0); MMA(1, 0, At, B0); BAR; SCHED;
;     STAGE(SB(0, 1), Bt, bcol + G_HALF, t + 2);
;     WAIT_V(6); BAR; MMA(1, 1, At, B1); BAR;
.LBB0_162:
	ds_read_b128 v[156:159], v148
	ds_read_b128 v[160:163], v148 offset:1024
	ds_read_b128 v[164:167], v148 offset:2048
	ds_read_b128 v[168:171], v148 offset:3072
	s_add_i32 s6, s3, 0xffffff00
	s_add_i32 m0, s100, 0xc000
	ds_read_b128 v[172:175], v133
	ds_read_b128 v[176:179], v133 offset:1024
	ds_read_b128 v[180:183], v132
	ds_read_b128 v[184:187], v132 offset:1024
	ds_read_b128 v[188:191], v131
	ds_read_b128 v[192:195], v131 offset:1024
	ds_read_b128 v[196:199], v130
	buffer_load_dwordx4 v137, s[88:91], s6 offen lds
	s_add_i32 m0, s100, 0xe000
	ds_read_b128 v[200:203], v130 offset:1024
	buffer_load_dwordx4 v136, s[88:91], s6 offen lds
	s_waitcnt lgkmcnt(8)
	s_barrier
	s_waitcnt lgkmcnt(1)
	v_mfma_f32_16x16x32_bf16 v[126:129], v[172:175], v[156:159], v[126:129]
	v_mfma_f32_16x16x32_bf16 v[122:125], v[172:175], v[164:167], v[122:125]
	v_mfma_f32_16x16x32_bf16 v[118:121], v[180:183], v[156:159], v[118:121]
	v_mfma_f32_16x16x32_bf16 v[114:117], v[180:183], v[164:167], v[114:117]
	v_mfma_f32_16x16x32_bf16 v[110:113], v[188:191], v[156:159], v[110:113]
	v_mfma_f32_16x16x32_bf16 v[106:109], v[188:191], v[164:167], v[106:109]
	v_mfma_f32_16x16x32_bf16 v[102:105], v[196:199], v[156:159], v[102:105]
	v_mfma_f32_16x16x32_bf16 v[98:101], v[196:199], v[164:167], v[98:101]
	v_mfma_f32_16x16x32_bf16 v[126:129], v[176:179], v[160:163], v[126:129]
	v_mfma_f32_16x16x32_bf16 v[122:125], v[176:179], v[168:171], v[122:125]
	v_mfma_f32_16x16x32_bf16 v[118:121], v[184:187], v[160:163], v[118:121]
	v_mfma_f32_16x16x32_bf16 v[114:117], v[184:187], v[168:171], v[114:117]
	v_mfma_f32_16x16x32_bf16 v[110:113], v[192:195], v[160:163], v[110:113]
	v_mfma_f32_16x16x32_bf16 v[106:109], v[192:195], v[168:171], v[106:109]
	s_waitcnt lgkmcnt(0)
	v_mfma_f32_16x16x32_bf16 v[102:105], v[200:203], v[160:163], v[102:105]
	v_mfma_f32_16x16x32_bf16 v[98:101], v[200:203], v[168:171], v[98:101]
	s_barrier
	s_add_i32 s15, s3, 0xfff7ff80
	s_mov_b32 s6, s90
	s_add_i32 m0, s100, 0x10000
	ds_read_b128 v[204:207], v145
	ds_read_b128 v[208:211], v145 offset:1024
	ds_read_b128 v[212:215], v145 offset:2048
	buffer_load_dwordx4 v137, s[4:7], s15 offen lds
	s_add_i32 m0, s100, 0x12000
	ds_read_b128 v[216:219], v145 offset:3072
	buffer_load_dwordx4 v136, s[4:7], s15 offen lds
	s_barrier
	s_waitcnt lgkmcnt(1)
	v_mfma_f32_16x16x32_bf16 v[94:97], v[172:175], v[204:207], v[94:97]
	v_mfma_f32_16x16x32_bf16 v[90:93], v[172:175], v[212:215], v[90:93]
	v_mfma_f32_16x16x32_bf16 v[86:89], v[180:183], v[204:207], v[86:89]
	v_mfma_f32_16x16x32_bf16 v[82:85], v[180:183], v[212:215], v[82:85]
	v_mfma_f32_16x16x32_bf16 v[78:81], v[188:191], v[204:207], v[78:81]
	v_mfma_f32_16x16x32_bf16 v[74:77], v[188:191], v[212:215], v[74:77]
	v_mfma_f32_16x16x32_bf16 v[70:73], v[196:199], v[204:207], v[70:73]
	v_mfma_f32_16x16x32_bf16 v[66:69], v[196:199], v[212:215], v[66:69]
	v_mfma_f32_16x16x32_bf16 v[94:97], v[176:179], v[208:211], v[94:97]
	s_waitcnt lgkmcnt(0)
	v_mfma_f32_16x16x32_bf16 v[90:93], v[176:179], v[216:219], v[90:93]
	v_mfma_f32_16x16x32_bf16 v[86:89], v[184:187], v[208:211], v[86:89]
	v_mfma_f32_16x16x32_bf16 v[82:85], v[184:187], v[216:219], v[82:85]
	v_mfma_f32_16x16x32_bf16 v[78:81], v[192:195], v[208:211], v[78:81]
	v_mfma_f32_16x16x32_bf16 v[74:77], v[192:195], v[216:219], v[74:77]
	v_mfma_f32_16x16x32_bf16 v[70:73], v[200:203], v[208:211], v[70:73]
	v_mfma_f32_16x16x32_bf16 v[66:69], v[200:203], v[216:219], v[66:69]
	s_mov_b32 m0, s100
	s_barrier
	ds_read_b128 v[172:175], v133 offset:16384
	ds_read_b128 v[176:179], v133 offset:17408
	ds_read_b128 v[180:183], v132 offset:16384
	ds_read_b128 v[184:187], v132 offset:17408
	ds_read_b128 v[188:191], v131 offset:16384
	ds_read_b128 v[192:195], v131 offset:17408
	ds_read_b128 v[196:199], v130 offset:16384
	buffer_load_dwordx4 v137, s[88:91], s15 offen lds
	s_add_i32 m0, s100, 0x2000
	ds_read_b128 v[200:203], v130 offset:17408
	buffer_load_dwordx4 v136, s[88:91], s15 offen lds
	s_barrier
	s_waitcnt lgkmcnt(1)
	v_mfma_f32_16x16x32_bf16 v[62:65], v[172:175], v[156:159], v[62:65]
	v_mfma_f32_16x16x32_bf16 v[58:61], v[172:175], v[164:167], v[58:61]
	v_mfma_f32_16x16x32_bf16 v[54:57], v[180:183], v[156:159], v[54:57]
	v_mfma_f32_16x16x32_bf16 v[50:53], v[180:183], v[164:167], v[50:53]
	v_mfma_f32_16x16x32_bf16 v[46:49], v[188:191], v[156:159], v[46:49]
	v_mfma_f32_16x16x32_bf16 v[42:45], v[188:191], v[164:167], v[42:45]
	v_mfma_f32_16x16x32_bf16 v[38:41], v[196:199], v[156:159], v[38:41]
	v_mfma_f32_16x16x32_bf16 v[34:37], v[196:199], v[164:167], v[34:37]
	v_mfma_f32_16x16x32_bf16 v[62:65], v[176:179], v[160:163], v[62:65]
	v_mfma_f32_16x16x32_bf16 v[58:61], v[176:179], v[168:171], v[58:61]
	v_mfma_f32_16x16x32_bf16 v[54:57], v[184:187], v[160:163], v[54:57]
	v_mfma_f32_16x16x32_bf16 v[50:53], v[184:187], v[168:171], v[50:53]
	v_mfma_f32_16x16x32_bf16 v[46:49], v[192:195], v[160:163], v[46:49]
	v_mfma_f32_16x16x32_bf16 v[42:45], v[192:195], v[168:171], v[42:45]
	s_waitcnt lgkmcnt(0)
	v_mfma_f32_16x16x32_bf16 v[38:41], v[200:203], v[160:163], v[38:41]
	v_mfma_f32_16x16x32_bf16 v[34:37], v[200:203], v[168:171], v[34:37]
	s_barrier
	s_add_i32 m0, s100, 0x14000
	s_add_i32 s15, s3, 0xffffff80
	buffer_load_dwordx4 v137, s[4:7], s15 offen lds
	s_add_i32 m0, s100, 0x16000
	s_nop 0
	buffer_load_dwordx4 v136, s[4:7], s15 offen lds
	s_waitcnt vmcnt(6)
	s_barrier
; #define WAIT_V(n) asm volatile("s_waitcnt vmcnt(" #n ")" ::: "memory")
; #define WAIT_L(n) asm volatile("s_waitcnt lgkmcnt(" #n ")" ::: "memory")
; #define BAR __builtin_amdgcn_s_barrier()
; #define SCHED __builtin_amdgcn_sched_barrier(0)
; __device__ __forceinline__ void mainloop_8phase(const u16* __restrict__ A, const u16* __restrict__ Bt, int K,
;                                                 f32x4 (&acc)[2][2][4][2], int wid_s, int ld) {
;     ...
;     WAIT_V(6); BAR; MMA(1, 1, At, B1); BAR;
;     LDB(B0, 1, 0); SCHED; LDA(At, 1, 0); STAGE(SA(0, 1), A, brow + G_HALF, t + 2);
;     WAIT_L(8); BAR; WAIT_L(0); MMA(0, 0, At, B0); BAR; SCHED;
;     LDB(B1, 1, 1); STAGE(SB(1, 0), Bt, bcol, t + 3);
;     BAR; WAIT_L(0); MMA(0, 1, At, B1); BAR;
;     LDA(At, 1, 1); STAGE(SA(1, 0), A, brow, t + 3);
;     BAR; WAIT_L(0); MMA(1, 0, At, B0); BAR; SCHED;
	v_mfma_f32_16x16x32_bf16 v[30:33], v[172:175], v[204:207], v[30:33]
	v_mfma_f32_16x16x32_bf16 v[26:29], v[172:175], v[212:215], v[26:29]
	v_mfma_f32_16x16x32_bf16 v[22:25], v[180:183], v[204:207], v[22:25]
	v_mfma_f32_16x16x32_bf16 v[18:21], v[180:183], v[212:215], v[18:21]
	v_mfma_f32_16x16x32_bf16 v[14:17], v[188:191], v[204:207], v[14:17]
	v_mfma_f32_16x16x32_bf16 v[10:13], v[188:191], v[212:215], v[10:13]
	v_mfma_f32_16x16x32_bf16 v[6:9], v[196:199], v[204:207], v[6:9]
	v_mfma_f32_16x16x32_bf16 v[2:5], v[196:199], v[212:215], v[2:5]
	v_mfma_f32_16x16x32_bf16 v[30:33], v[176:179], v[208:211], v[30:33]
	v_mfma_f32_16x16x32_bf16 v[26:29], v[176:179], v[216:219], v[26:29]
	v_mfma_f32_16x16x32_bf16 v[22:25], v[184:187], v[208:211], v[22:25]
	v_mfma_f32_16x16x32_bf16 v[18:21], v[184:187], v[216:219], v[18:21]
	v_mfma_f32_16x16x32_bf16 v[14:17], v[192:195], v[208:211], v[14:17]
	v_mfma_f32_16x16x32_bf16 v[10:13], v[192:195], v[216:219], v[10:13]
	v_mfma_f32_16x16x32_bf16 v[6:9], v[200:203], v[208:211], v[6:9]
	v_mfma_f32_16x16x32_bf16 v[2:5], v[200:203], v[216:219], v[2:5]
	s_barrier
	ds_read_b128 v[156:159], v135
	ds_read_b128 v[160:163], v135 offset:1024
	ds_read_b128 v[164:167], v135 offset:2048
	ds_read_b128 v[168:171], v135 offset:3072
	s_add_i32 m0, s100, 0x4000
	ds_read_b128 v[172:175], v133 offset:32768
	ds_read_b128 v[176:179], v133 offset:33792
	ds_read_b128 v[180:183], v132 offset:32768
	ds_read_b128 v[184:187], v132 offset:33792
	ds_read_b128 v[188:191], v131 offset:32768
	ds_read_b128 v[192:195], v131 offset:33792
	ds_read_b128 v[196:199], v130 offset:32768
	buffer_load_dwordx4 v137, s[88:91], s15 offen lds
	s_add_i32 m0, s100, 0x6000
	ds_read_b128 v[200:203], v130 offset:33792
	buffer_load_dwordx4 v136, s[88:91], s15 offen lds
	s_waitcnt lgkmcnt(8)
	s_barrier
	s_waitcnt lgkmcnt(1)
	v_mfma_f32_16x16x32_bf16 v[126:129], v[172:175], v[156:159], v[126:129]
	v_mfma_f32_16x16x32_bf16 v[122:125], v[172:175], v[164:167], v[122:125]
	v_mfma_f32_16x16x32_bf16 v[118:121], v[180:183], v[156:159], v[118:121]
	v_mfma_f32_16x16x32_bf16 v[114:117], v[180:183], v[164:167], v[114:117]
	v_mfma_f32_16x16x32_bf16 v[110:113], v[188:191], v[156:159], v[110:113]
	v_mfma_f32_16x16x32_bf16 v[106:109], v[188:191], v[164:167], v[106:109]
	v_mfma_f32_16x16x32_bf16 v[102:105], v[196:199], v[156:159], v[102:105]
	v_mfma_f32_16x16x32_bf16 v[98:101], v[196:199], v[164:167], v[98:101]
	v_mfma_f32_16x16x32_bf16 v[126:129], v[176:179], v[160:163], v[126:129]
	v_mfma_f32_16x16x32_bf16 v[122:125], v[176:179], v[168:171], v[122:125]
	v_mfma_f32_16x16x32_bf16 v[118:121], v[184:187], v[160:163], v[118:121]
	v_mfma_f32_16x16x32_bf16 v[114:117], v[184:187], v[168:171], v[114:117]
	v_mfma_f32_16x16x32_bf16 v[110:113], v[192:195], v[160:163], v[110:113]
	v_mfma_f32_16x16x32_bf16 v[106:109], v[192:195], v[168:171], v[106:109]
	s_waitcnt lgkmcnt(0)
	v_mfma_f32_16x16x32_bf16 v[102:105], v[200:203], v[160:163], v[102:105]
	v_mfma_f32_16x16x32_bf16 v[98:101], v[200:203], v[168:171], v[98:101]
	s_barrier
	s_add_i32 s15, s3, 0xfff80000
	s_add_i32 m0, s100, 0x18000
	ds_read_b128 v[204:207], v134
	ds_read_b128 v[208:211], v134 offset:1024
	ds_read_b128 v[212:215], v134 offset:2048
	buffer_load_dwordx4 v137, s[4:7], s15 offen lds
	s_add_i32 m0, s100, 0x1a000
	ds_read_b128 v[216:219], v134 offset:3072
	buffer_load_dwordx4 v136, s[4:7], s15 offen lds
	s_barrier
	s_waitcnt lgkmcnt(1)
	v_mfma_f32_16x16x32_bf16 v[94:97], v[172:175], v[204:207], v[94:97]
	v_mfma_f32_16x16x32_bf16 v[90:93], v[172:175], v[212:215], v[90:93]
	v_mfma_f32_16x16x32_bf16 v[86:89], v[180:183], v[204:207], v[86:89]
	v_mfma_f32_16x16x32_bf16 v[82:85], v[180:183], v[212:215], v[82:85]
	v_mfma_f32_16x16x32_bf16 v[78:81], v[188:191], v[204:207], v[78:81]
	v_mfma_f32_16x16x32_bf16 v[74:77], v[188:191], v[212:215], v[74:77]
	v_mfma_f32_16x16x32_bf16 v[70:73], v[196:199], v[204:207], v[70:73]
	v_mfma_f32_16x16x32_bf16 v[66:69], v[196:199], v[212:215], v[66:69]
	v_mfma_f32_16x16x32_bf16 v[94:97], v[176:179], v[208:211], v[94:97]
	s_waitcnt lgkmcnt(0)
	v_mfma_f32_16x16x32_bf16 v[90:93], v[176:179], v[216:219], v[90:93]
	v_mfma_f32_16x16x32_bf16 v[86:89], v[184:187], v[208:211], v[86:89]
	v_mfma_f32_16x16x32_bf16 v[82:85], v[184:187], v[216:219], v[82:85]
	v_mfma_f32_16x16x32_bf16 v[78:81], v[192:195], v[208:211], v[78:81]
	v_mfma_f32_16x16x32_bf16 v[74:77], v[192:195], v[216:219], v[74:77]
	v_mfma_f32_16x16x32_bf16 v[70:73], v[200:203], v[208:211], v[70:73]
	v_mfma_f32_16x16x32_bf16 v[66:69], v[200:203], v[216:219], v[66:69]
	s_add_i32 m0, s100, 0x8000
	s_barrier
	ds_read_b128 v[172:175], v133 offset:49152
	ds_read_b128 v[176:179], v133 offset:50176
	ds_read_b128 v[180:183], v132 offset:49152
	ds_read_b128 v[184:187], v132 offset:50176
	ds_read_b128 v[188:191], v131 offset:49152
	ds_read_b128 v[192:195], v131 offset:50176
	ds_read_b128 v[196:199], v130 offset:49152
	buffer_load_dwordx4 v137, s[88:91], s15 offen lds
	s_add_i32 m0, s100, 0xa000
	ds_read_b128 v[200:203], v130 offset:50176
	buffer_load_dwordx4 v136, s[88:91], s15 offen lds
	s_barrier
	s_waitcnt lgkmcnt(1)
	v_mfma_f32_16x16x32_bf16 v[62:65], v[172:175], v[156:159], v[62:65]
	v_mfma_f32_16x16x32_bf16 v[58:61], v[172:175], v[164:167], v[58:61]
	v_mfma_f32_16x16x32_bf16 v[54:57], v[180:183], v[156:159], v[54:57]
	v_mfma_f32_16x16x32_bf16 v[50:53], v[180:183], v[164:167], v[50:53]
	v_mfma_f32_16x16x32_bf16 v[46:49], v[188:191], v[156:159], v[46:49]
	v_mfma_f32_16x16x32_bf16 v[42:45], v[188:191], v[164:167], v[42:45]
	v_mfma_f32_16x16x32_bf16 v[38:41], v[196:199], v[156:159], v[38:41]
	v_mfma_f32_16x16x32_bf16 v[34:37], v[196:199], v[164:167], v[34:37]
	v_mfma_f32_16x16x32_bf16 v[62:65], v[176:179], v[160:163], v[62:65]
	v_mfma_f32_16x16x32_bf16 v[58:61], v[176:179], v[168:171], v[58:61]
	v_mfma_f32_16x16x32_bf16 v[54:57], v[184:187], v[160:163], v[54:57]
	v_mfma_f32_16x16x32_bf16 v[50:53], v[184:187], v[168:171], v[50:53]
	v_mfma_f32_16x16x32_bf16 v[46:49], v[192:195], v[160:163], v[46:49]
	v_mfma_f32_16x16x32_bf16 v[42:45], v[192:195], v[168:171], v[42:45]
	s_waitcnt lgkmcnt(0)
	v_mfma_f32_16x16x32_bf16 v[38:41], v[200:203], v[160:163], v[38:41]
	v_mfma_f32_16x16x32_bf16 v[34:37], v[200:203], v[168:171], v[34:37]
	s_barrier
; #define WAIT_V(n) asm volatile("s_waitcnt vmcnt(" #n ")" ::: "memory")
; #define WAIT_L(n) asm volatile("s_waitcnt lgkmcnt(" #n ")" ::: "memory")
; #define BAR __builtin_amdgcn_s_barrier()
; __device__ __forceinline__ void mainloop_8phase(const u16* __restrict__ A, const u16* __restrict__ Bt, int K,
;                                                 f32x4 (&acc)[2][2][4][2], int wid_s, int ld) {
;     ...
;     STAGE(SB(1, 1), Bt, bcol + G_HALF, t + 3);
;     WAIT_V(6); BAR; MMA(1, 1, At, B1); BAR;
;   }
;   { LDB(B0, 0, 0); LDA(At, 0, 0); STAGE(SA(1, 1), A, brow + G_HALF, nt - 1);
;     BAR; WAIT_L(0); MMA(0, 0, At, B0); BAR;
;     LDB(B1, 0, 1); BAR; WAIT_L(0); MMA(0, 1, At, B1); BAR;
;     LDA(At, 0, 1); WAIT_V(4); BAR; WAIT_L(0); MMA(1, 0, At, B0); MMA(1, 1, At, B1); BAR; }
	s_add_i32 m0, s100, 0x1c000
	s_nop 0
	buffer_load_dwordx4 v137, s[4:7], s3 offen lds
	s_add_i32 m0, s100, 0x1e000
	s_nop 0
	buffer_load_dwordx4 v136, s[4:7], s3 offen lds
	s_waitcnt vmcnt(6)
	s_barrier
	v_mfma_f32_16x16x32_bf16 v[30:33], v[172:175], v[204:207], v[30:33]
	v_mfma_f32_16x16x32_bf16 v[26:29], v[172:175], v[212:215], v[26:29]
	v_mfma_f32_16x16x32_bf16 v[22:25], v[180:183], v[204:207], v[22:25]
	v_mfma_f32_16x16x32_bf16 v[18:21], v[180:183], v[212:215], v[18:21]
	v_mfma_f32_16x16x32_bf16 v[14:17], v[188:191], v[204:207], v[14:17]
	v_mfma_f32_16x16x32_bf16 v[10:13], v[188:191], v[212:215], v[10:13]
	v_mfma_f32_16x16x32_bf16 v[6:9], v[196:199], v[204:207], v[6:9]
	v_mfma_f32_16x16x32_bf16 v[2:5], v[196:199], v[212:215], v[2:5]
	v_mfma_f32_16x16x32_bf16 v[30:33], v[176:179], v[208:211], v[30:33]
	v_mfma_f32_16x16x32_bf16 v[26:29], v[176:179], v[216:219], v[26:29]
	v_mfma_f32_16x16x32_bf16 v[22:25], v[184:187], v[208:211], v[22:25]
	v_mfma_f32_16x16x32_bf16 v[18:21], v[184:187], v[216:219], v[18:21]
	v_mfma_f32_16x16x32_bf16 v[14:17], v[192:195], v[208:211], v[14:17]
	v_mfma_f32_16x16x32_bf16 v[10:13], v[192:195], v[216:219], v[10:13]
	v_mfma_f32_16x16x32_bf16 v[6:9], v[200:203], v[208:211], v[6:9]
	v_mfma_f32_16x16x32_bf16 v[2:5], v[200:203], v[216:219], v[2:5]
	s_add_i32 s2, s2, 2
	s_addk_i32 s3, 0x100
	s_cmp_lt_u32 s2, 28
	s_barrier
	s_cbranch_scc1 .LBB0_162
	v_readfirstlane_b32 s2, v150
	s_mov_b32 m0, s2
	s_mov_b32 s3, 0x80f80
	v_readfirstlane_b32 s2, v149
	ds_read_b128 v[138:141], v148
	ds_read_b128 v[152:155], v148 offset:1024
	ds_read_b128 v[156:159], v148 offset:2048
	ds_read_b128 v[160:163], v148 offset:3072
	ds_read_b128 v[164:167], v133
	ds_read_b128 v[168:171], v133 offset:1024
	ds_read_b128 v[172:175], v132
	ds_read_b128 v[176:179], v132 offset:1024
	ds_read_b128 v[180:183], v131
	ds_read_b128 v[184:187], v131 offset:1024
	ds_read_b128 v[188:191], v130
	ds_read_b128 v[192:195], v130 offset:1024
	buffer_load_dwordx4 v137, s[88:91], s3 offen lds
	s_mov_b32 m0, s2
	s_nop 0
	buffer_load_dwordx4 v136, s[88:91], s3 offen lds
	s_barrier
	s_waitcnt lgkmcnt(0)
	v_mfma_f32_16x16x32_bf16 v[126:129], v[164:167], v[138:141], v[126:129]
	v_mfma_f32_16x16x32_bf16 v[118:121], v[172:175], v[138:141], v[118:121]
	v_mfma_f32_16x16x32_bf16 v[110:113], v[180:183], v[138:141], v[110:113]
	v_mfma_f32_16x16x32_bf16 v[102:105], v[188:191], v[138:141], v[102:105]
	v_mfma_f32_16x16x32_bf16 v[126:129], v[168:171], v[152:155], v[126:129]
	v_mfma_f32_16x16x32_bf16 v[122:125], v[164:167], v[156:159], v[122:125]
	v_mfma_f32_16x16x32_bf16 v[118:121], v[176:179], v[152:155], v[118:121]
	v_mfma_f32_16x16x32_bf16 v[114:117], v[172:175], v[156:159], v[114:117]
	v_mfma_f32_16x16x32_bf16 v[110:113], v[184:187], v[152:155], v[110:113]
	v_mfma_f32_16x16x32_bf16 v[106:109], v[180:183], v[156:159], v[106:109]
	v_mfma_f32_16x16x32_bf16 v[102:105], v[192:195], v[152:155], v[102:105]
	v_mfma_f32_16x16x32_bf16 v[98:101], v[188:191], v[156:159], v[98:101]
	v_mfma_f32_16x16x32_bf16 v[146:149], v[168:171], v[160:163], v[122:125]
	v_mfma_f32_16x16x32_bf16 v[196:199], v[176:179], v[160:163], v[114:117]
	v_mfma_f32_16x16x32_bf16 v[200:203], v[184:187], v[160:163], v[106:109]
	v_mfma_f32_16x16x32_bf16 v[204:207], v[192:195], v[160:163], v[98:101]
	s_barrier
	s_nop 1
	ds_read_b128 v[98:101], v145
	ds_read_b128 v[106:109], v145 offset:1024
	ds_read_b128 v[114:117], v145 offset:2048
	ds_read_b128 v[122:125], v145 offset:3072
	s_barrier
	s_waitcnt lgkmcnt(0)
	v_mfma_f32_16x16x32_bf16 v[94:97], v[164:167], v[98:101], v[94:97]
	v_mfma_f32_16x16x32_bf16 v[90:93], v[164:167], v[114:117], v[90:93]
	v_mfma_f32_16x16x32_bf16 v[86:89], v[172:175], v[98:101], v[86:89]
	v_mfma_f32_16x16x32_bf16 v[82:85], v[172:175], v[114:117], v[82:85]
	v_mfma_f32_16x16x32_bf16 v[78:81], v[180:183], v[98:101], v[78:81]
	v_mfma_f32_16x16x32_bf16 v[74:77], v[180:183], v[114:117], v[74:77]
	v_mfma_f32_16x16x32_bf16 v[70:73], v[188:191], v[98:101], v[70:73]
	v_mfma_f32_16x16x32_bf16 v[66:69], v[188:191], v[114:117], v[66:69]
	v_mfma_f32_16x16x32_bf16 v[94:97], v[168:171], v[106:109], v[94:97]
	v_mfma_f32_16x16x32_bf16 v[90:93], v[168:171], v[122:125], v[90:93]
	v_mfma_f32_16x16x32_bf16 v[86:89], v[176:179], v[106:109], v[86:89]
	v_mfma_f32_16x16x32_bf16 v[82:85], v[176:179], v[122:125], v[82:85]
	v_mfma_f32_16x16x32_bf16 v[78:81], v[184:187], v[106:109], v[78:81]
	v_mfma_f32_16x16x32_bf16 v[74:77], v[184:187], v[122:125], v[74:77]
	v_mfma_f32_16x16x32_bf16 v[70:73], v[192:195], v[106:109], v[70:73]
	v_mfma_f32_16x16x32_bf16 v[66:69], v[192:195], v[122:125], v[66:69]
	s_barrier
	ds_read_b128 v[142:145], v133 offset:16384
	ds_read_b128 v[164:167], v133 offset:17408
	ds_read_b128 v[168:171], v132 offset:16384
	ds_read_b128 v[172:175], v132 offset:17408
	ds_read_b128 v[176:179], v131 offset:16384
	ds_read_b128 v[180:183], v131 offset:17408
	ds_read_b128 v[184:187], v130 offset:16384
	ds_read_b128 v[188:191], v130 offset:17408
	s_waitcnt vmcnt(4)
	s_barrier
; #define WAIT_V(n) asm volatile("s_waitcnt vmcnt(" #n ")" ::: "memory")
; #define WAIT_L(n) asm volatile("s_waitcnt lgkmcnt(" #n ")" ::: "memory")
; #define BAR __builtin_amdgcn_s_barrier()
; __device__ __forceinline__ void mainloop_8phase(const u16* __restrict__ A, const u16* __restrict__ Bt, int K,
;                                                 f32x4 (&acc)[2][2][4][2], int wid_s, int ld) {
;     ...
;     LDA(At, 0, 1); WAIT_V(4); BAR; WAIT_L(0); MMA(1, 0, At, B0); MMA(1, 1, At, B1); BAR; }
;   { LDB(B0, 1, 0); LDA(At, 1, 0); WAIT_V(2); BAR; WAIT_L(0); MMA(0, 0, At, B0); BAR;
	s_waitcnt lgkmcnt(0)
	v_mfma_f32_16x16x32_bf16 v[62:65], v[142:145], v[138:141], v[62:65]
	v_mfma_f32_16x16x32_bf16 v[58:61], v[142:145], v[156:159], v[58:61]
	v_mfma_f32_16x16x32_bf16 v[54:57], v[168:171], v[138:141], v[54:57]
	v_mfma_f32_16x16x32_bf16 v[50:53], v[168:171], v[156:159], v[50:53]
	v_mfma_f32_16x16x32_bf16 v[46:49], v[176:179], v[138:141], v[46:49]
	v_mfma_f32_16x16x32_bf16 v[42:45], v[176:179], v[156:159], v[42:45]
	v_mfma_f32_16x16x32_bf16 v[38:41], v[184:187], v[138:141], v[38:41]
	v_mfma_f32_16x16x32_bf16 v[34:37], v[184:187], v[156:159], v[34:37]
	v_mfma_f32_16x16x32_bf16 v[192:195], v[164:167], v[152:155], v[62:65]
	v_mfma_f32_16x16x32_bf16 v[208:211], v[164:167], v[160:163], v[58:61]
	v_mfma_f32_16x16x32_bf16 v[212:215], v[172:175], v[152:155], v[54:57]
	v_mfma_f32_16x16x32_bf16 v[216:219], v[172:175], v[160:163], v[50:53]
	v_mfma_f32_16x16x32_bf16 v[220:223], v[180:183], v[152:155], v[46:49]
	v_mfma_f32_16x16x32_bf16 v[224:227], v[180:183], v[160:163], v[42:45]
	v_mfma_f32_16x16x32_bf16 v[136:139], v[188:191], v[152:155], v[38:41]
	v_mfma_f32_16x16x32_bf16 v[150:153], v[188:191], v[160:163], v[34:37]
	v_mfma_f32_16x16x32_bf16 v[30:33], v[142:145], v[98:101], v[30:33]
	v_mfma_f32_16x16x32_bf16 v[22:25], v[168:171], v[98:101], v[22:25]
	v_mfma_f32_16x16x32_bf16 v[14:17], v[176:179], v[98:101], v[14:17]
	v_mfma_f32_16x16x32_bf16 v[6:9], v[184:187], v[98:101], v[6:9]
	v_mfma_f32_16x16x32_bf16 v[30:33], v[164:167], v[106:109], v[30:33]
	v_mfma_f32_16x16x32_bf16 v[26:29], v[142:145], v[114:117], v[26:29]
	v_mfma_f32_16x16x32_bf16 v[22:25], v[172:175], v[106:109], v[22:25]
	v_mfma_f32_16x16x32_bf16 v[18:21], v[168:171], v[114:117], v[18:21]
	v_mfma_f32_16x16x32_bf16 v[14:17], v[180:183], v[106:109], v[14:17]
	v_mfma_f32_16x16x32_bf16 v[10:13], v[176:179], v[114:117], v[10:13]
	v_mfma_f32_16x16x32_bf16 v[6:9], v[188:191], v[106:109], v[6:9]
	v_mfma_f32_16x16x32_bf16 v[2:5], v[184:187], v[114:117], v[2:5]
	v_mfma_f32_16x16x32_bf16 v[140:143], v[164:167], v[122:125], v[26:29]
	v_mfma_f32_16x16x32_bf16 v[154:157], v[172:175], v[122:125], v[18:21]
	v_mfma_f32_16x16x32_bf16 v[158:161], v[180:183], v[122:125], v[10:13]
	v_mfma_f32_16x16x32_bf16 v[162:165], v[188:191], v[122:125], v[2:5]
	s_barrier
	s_nop 1
	ds_read_b128 v[2:5], v135
	ds_read_b128 v[166:169], v135 offset:1024
	ds_read_b128 v[170:173], v135 offset:2048
	ds_read_b128 v[174:177], v135 offset:3072
	ds_read_b128 v[10:13], v133 offset:32768
	ds_read_b128 v[18:21], v133 offset:33792
	ds_read_b128 v[26:29], v132 offset:32768
	ds_read_b128 v[38:41], v132 offset:33792
	ds_read_b128 v[46:49], v131 offset:32768
	ds_read_b128 v[178:181], v131 offset:33792
	ds_read_b128 v[182:185], v130 offset:32768
	ds_read_b128 v[186:189], v130 offset:33792
	s_waitcnt vmcnt(2)
	s_barrier
	s_waitcnt lgkmcnt(0)
	v_mfma_f32_16x16x32_bf16 v[34:37], v[10:13], v[2:5], v[126:129]
	v_mfma_f32_16x16x32_bf16 v[122:125], v[18:21], v[166:169], v[34:37]
	v_mfma_f32_16x16x32_bf16 v[34:37], v[10:13], v[170:173], v[146:149]
	v_mfma_f32_16x16x32_bf16 v[58:61], v[18:21], v[174:177], v[34:37]
	v_mfma_f32_16x16x32_bf16 v[34:37], v[26:29], v[2:5], v[118:121]
	v_mfma_f32_16x16x32_bf16 v[114:117], v[38:41], v[166:169], v[34:37]
	v_mfma_f32_16x16x32_bf16 v[34:37], v[26:29], v[170:173], v[196:199]
	v_mfma_f32_16x16x32_bf16 v[50:53], v[38:41], v[174:177], v[34:37]
	v_mfma_f32_16x16x32_bf16 v[34:37], v[46:49], v[2:5], v[110:113]
	v_mfma_f32_16x16x32_bf16 v[106:109], v[178:181], v[166:169], v[34:37]
	v_mfma_f32_16x16x32_bf16 v[34:37], v[46:49], v[170:173], v[200:203]
	v_mfma_f32_16x16x32_bf16 v[42:45], v[178:181], v[174:177], v[34:37]
	v_mfma_f32_16x16x32_bf16 v[34:37], v[182:185], v[2:5], v[102:105]
	v_mfma_f32_16x16x32_bf16 v[98:101], v[186:189], v[166:169], v[34:37]
	v_mfma_f32_16x16x32_bf16 v[34:37], v[182:185], v[170:173], v[204:207]
	v_mfma_f32_16x16x32_bf16 v[34:37], v[186:189], v[174:177], v[34:37]
	s_barrier
; #define WAIT_V(n) asm volatile("s_waitcnt vmcnt(" #n ")" ::: "memory")
; #define WAIT_L(n) asm volatile("s_waitcnt lgkmcnt(" #n ")" ::: "memory")
; #define BAR __builtin_amdgcn_s_barrier()
; __device__ __forceinline__ void mainloop_8phase(const u16* __restrict__ A, const u16* __restrict__ Bt, int K,
;                                                 f32x4 (&acc)[2][2][4][2], int wid_s, int ld) {
;     ...
;     LDB(B1, 1, 1); WAIT_V(0); BAR; WAIT_L(0); MMA(0, 1, At, B1); BAR;
;     LDA(At, 1, 1); BAR; WAIT_L(0); MMA(1, 0, At, B0); MMA(1, 1, At, B1); BAR; }
;   if (wr == 0) BAR;
	ds_read_b128 v[144:147], v134
	ds_read_b128 v[196:199], v134 offset:1024
	ds_read_b128 v[200:203], v134 offset:2048
	ds_read_b128 v[204:207], v134 offset:3072
	s_waitcnt vmcnt(0)
	s_barrier
	s_waitcnt lgkmcnt(0)
	v_mfma_f32_16x16x32_bf16 v[54:57], v[10:13], v[144:147], v[94:97]
	v_mfma_f32_16x16x32_bf16 v[10:13], v[10:13], v[200:203], v[90:93]
	v_mfma_f32_16x16x32_bf16 v[62:65], v[18:21], v[204:207], v[10:13]
	v_mfma_f32_16x16x32_bf16 v[10:13], v[26:29], v[144:147], v[86:89]
	v_mfma_f32_16x16x32_bf16 v[118:121], v[38:41], v[196:199], v[10:13]
	v_mfma_f32_16x16x32_bf16 v[10:13], v[26:29], v[200:203], v[82:85]
	v_mfma_f32_16x16x32_bf16 v[126:129], v[18:21], v[196:199], v[54:57]
	v_mfma_f32_16x16x32_bf16 v[54:57], v[38:41], v[204:207], v[10:13]
	v_mfma_f32_16x16x32_bf16 v[10:13], v[46:49], v[144:147], v[78:81]
	v_mfma_f32_16x16x32_bf16 v[110:113], v[178:181], v[196:199], v[10:13]
	v_mfma_f32_16x16x32_bf16 v[10:13], v[46:49], v[200:203], v[74:77]
	v_mfma_f32_16x16x32_bf16 v[46:49], v[178:181], v[204:207], v[10:13]
	v_mfma_f32_16x16x32_bf16 v[10:13], v[182:185], v[144:147], v[70:73]
	v_mfma_f32_16x16x32_bf16 v[102:105], v[186:189], v[196:199], v[10:13]
	v_mfma_f32_16x16x32_bf16 v[10:13], v[182:185], v[200:203], v[66:69]
	v_mfma_f32_16x16x32_bf16 v[38:41], v[186:189], v[204:207], v[10:13]
	s_barrier
	ds_read_b128 v[70:73], v133 offset:49152
	ds_read_b128 v[78:81], v133 offset:50176
	ds_read_b128 v[178:181], v132 offset:49152
	ds_read_b128 v[132:135], v132 offset:50176
	ds_read_b128 v[182:185], v131 offset:49152
	ds_read_b128 v[186:189], v131 offset:50176
	ds_read_b128 v[228:231], v130 offset:49152
	ds_read_b128 v[232:235], v130 offset:50176
	s_barrier
	s_waitcnt lgkmcnt(0)
	v_mfma_f32_16x16x32_bf16 v[10:13], v[70:73], v[2:5], v[192:195]
	v_mfma_f32_16x16x32_bf16 v[90:93], v[78:81], v[166:169], v[10:13]
	v_mfma_f32_16x16x32_bf16 v[10:13], v[70:73], v[170:173], v[208:211]
	v_mfma_f32_16x16x32_bf16 v[26:29], v[78:81], v[174:177], v[10:13]
	v_mfma_f32_16x16x32_bf16 v[10:13], v[178:181], v[2:5], v[212:215]
	v_mfma_f32_16x16x32_bf16 v[82:85], v[132:135], v[166:169], v[10:13]
	v_mfma_f32_16x16x32_bf16 v[10:13], v[178:181], v[170:173], v[216:219]
	v_mfma_f32_16x16x32_bf16 v[18:21], v[132:135], v[174:177], v[10:13]
	v_mfma_f32_16x16x32_bf16 v[10:13], v[182:185], v[2:5], v[220:223]
	v_mfma_f32_16x16x32_bf16 v[2:5], v[228:231], v[2:5], v[136:139]
	v_mfma_f32_16x16x32_bf16 v[74:77], v[186:189], v[166:169], v[10:13]
	v_mfma_f32_16x16x32_bf16 v[10:13], v[182:185], v[170:173], v[224:227]
	v_mfma_f32_16x16x32_bf16 v[66:69], v[232:235], v[166:169], v[2:5]
	v_mfma_f32_16x16x32_bf16 v[2:5], v[228:231], v[170:173], v[150:153]
	v_mfma_f32_16x16x32_bf16 v[10:13], v[186:189], v[174:177], v[10:13]
	v_mfma_f32_16x16x32_bf16 v[2:5], v[232:235], v[174:177], v[2:5]
	v_mfma_f32_16x16x32_bf16 v[30:33], v[70:73], v[144:147], v[30:33]
	v_mfma_f32_16x16x32_bf16 v[94:97], v[78:81], v[196:199], v[30:33]
	v_mfma_f32_16x16x32_bf16 v[30:33], v[70:73], v[200:203], v[140:143]
	v_mfma_f32_16x16x32_bf16 v[22:25], v[178:181], v[144:147], v[22:25]
	v_mfma_f32_16x16x32_bf16 v[14:17], v[182:185], v[144:147], v[14:17]
	v_mfma_f32_16x16x32_bf16 v[6:9], v[228:231], v[144:147], v[6:9]
	v_mfma_f32_16x16x32_bf16 v[30:33], v[78:81], v[204:207], v[30:33]
	v_mfma_f32_16x16x32_bf16 v[86:89], v[132:135], v[196:199], v[22:25]
	v_mfma_f32_16x16x32_bf16 v[22:25], v[178:181], v[200:203], v[154:157]
	v_mfma_f32_16x16x32_bf16 v[78:81], v[186:189], v[196:199], v[14:17]
	v_mfma_f32_16x16x32_bf16 v[14:17], v[182:185], v[200:203], v[158:161]
	v_mfma_f32_16x16x32_bf16 v[70:73], v[232:235], v[196:199], v[6:9]
	v_mfma_f32_16x16x32_bf16 v[6:9], v[228:231], v[200:203], v[162:165]
	v_mfma_f32_16x16x32_bf16 v[22:25], v[132:135], v[204:207], v[22:25]
	v_mfma_f32_16x16x32_bf16 v[14:17], v[186:189], v[204:207], v[14:17]
	v_mfma_f32_16x16x32_bf16 v[6:9], v[232:235], v[204:207], v[6:9]
	s_movk_i32 s2, 0x100
	v_cmp_gt_u32_e32 vcc, s2, v0
	s_barrier
	s_and_saveexec_b64 s[2:3], vcc
	s_cbranch_execz .LBB0_165
	s_barrier

; #define WAIT_V(n) asm volatile("s_waitcnt vmcnt(" #n ")" ::: "memory")
; #define WAIT_L(n) asm volatile("s_waitcnt lgkmcnt(" #n ")" ::: "memory")
; #define BAR __builtin_amdgcn_s_barrier()
; #define SCHED __builtin_amdgcn_sched_barrier(0)
; __device__ __forceinline__ void mainloop_8phase(const u16* __restrict__ A, const u16* __restrict__ Bt, int K,
;                                                 f32x4 (&acc)[2][2][4][2], int wid_s, int ld) {
;     ...
;     LDB(B0, 0, 0); SCHED; LDA(At, 0, 0); STAGE(SA(1, 1), A, brow + G_HALF, t + 1);
;     WAIT_L(8); BAR; WAIT_L(0); MMA(0, 0, At, B0); BAR; SCHED;
;     LDB(B1, 0, 1); STAGE(SB(0, 0), Bt, bcol, t + 2);
;     BAR; WAIT_L(0); MMA(0, 1, At, B1); BAR;
;     LDA(At, 0, 1); STAGE(SA(0, 0), A, brow, t + 2);
;     BAR; WAIT_L(0); MMA(1, 0, At, B0); BAR; SCHED;
;     STAGE(SB(0, 1), Bt, bcol + G_HALF, t + 2);
;     WAIT_V(6); BAR; MMA(1, 1, At, B1); BAR;
.LBB0_247:
	ds_read_b128 v[156:159], v155
	ds_read_b128 v[160:163], v155 offset:1024
	ds_read_b128 v[164:167], v155 offset:2048
	ds_read_b128 v[168:171], v155 offset:3072
	s_add_i32 s3, s1, 0xffffff00
	s_add_i32 m0, s100, 0xc000
	ds_read_b128 v[172:175], v133
	ds_read_b128 v[176:179], v133 offset:1024
	ds_read_b128 v[180:183], v132
	ds_read_b128 v[184:187], v132 offset:1024
	ds_read_b128 v[188:191], v131
	ds_read_b128 v[192:195], v131 offset:1024
	ds_read_b128 v[196:199], v130
	buffer_load_dwordx4 v137, s[88:91], s3 offen lds
	s_add_i32 m0, s100, 0xe000
	ds_read_b128 v[200:203], v130 offset:1024
	buffer_load_dwordx4 v136, s[88:91], s3 offen lds
	s_waitcnt lgkmcnt(8)
	s_barrier
	s_waitcnt lgkmcnt(1)
	v_mfma_f32_16x16x32_bf16 v[126:129], v[172:175], v[156:159], v[126:129]
	v_mfma_f32_16x16x32_bf16 v[122:125], v[172:175], v[164:167], v[122:125]
	v_mfma_f32_16x16x32_bf16 v[118:121], v[180:183], v[156:159], v[118:121]
	v_mfma_f32_16x16x32_bf16 v[114:117], v[180:183], v[164:167], v[114:117]
	v_mfma_f32_16x16x32_bf16 v[110:113], v[188:191], v[156:159], v[110:113]
	v_mfma_f32_16x16x32_bf16 v[106:109], v[188:191], v[164:167], v[106:109]
	v_mfma_f32_16x16x32_bf16 v[102:105], v[196:199], v[156:159], v[102:105]
	v_mfma_f32_16x16x32_bf16 v[98:101], v[196:199], v[164:167], v[98:101]
	v_mfma_f32_16x16x32_bf16 v[126:129], v[176:179], v[160:163], v[126:129]
	v_mfma_f32_16x16x32_bf16 v[122:125], v[176:179], v[168:171], v[122:125]
	v_mfma_f32_16x16x32_bf16 v[118:121], v[184:187], v[160:163], v[118:121]
	v_mfma_f32_16x16x32_bf16 v[114:117], v[184:187], v[168:171], v[114:117]
	v_mfma_f32_16x16x32_bf16 v[110:113], v[192:195], v[160:163], v[110:113]
	v_mfma_f32_16x16x32_bf16 v[106:109], v[192:195], v[168:171], v[106:109]
	s_waitcnt lgkmcnt(0)
	v_mfma_f32_16x16x32_bf16 v[102:105], v[200:203], v[160:163], v[102:105]
	v_mfma_f32_16x16x32_bf16 v[98:101], v[200:203], v[168:171], v[98:101]
	s_barrier
	s_add_i32 s3, s1, 0xfff7ff80
	s_add_i32 m0, s100, 0x10000
	ds_read_b128 v[204:207], v147
	ds_read_b128 v[208:211], v147 offset:1024
	ds_read_b128 v[212:215], v147 offset:2048
	buffer_load_dwordx4 v137, s[4:7], s3 offen lds
	s_add_i32 m0, s100, 0x12000
	ds_read_b128 v[216:219], v147 offset:3072
	buffer_load_dwordx4 v136, s[4:7], s3 offen lds
	s_barrier
	s_waitcnt lgkmcnt(1)
	v_mfma_f32_16x16x32_bf16 v[94:97], v[172:175], v[204:207], v[94:97]
	v_mfma_f32_16x16x32_bf16 v[90:93], v[172:175], v[212:215], v[90:93]
	v_mfma_f32_16x16x32_bf16 v[86:89], v[180:183], v[204:207], v[86:89]
	v_mfma_f32_16x16x32_bf16 v[82:85], v[180:183], v[212:215], v[82:85]
	v_mfma_f32_16x16x32_bf16 v[78:81], v[188:191], v[204:207], v[78:81]
	v_mfma_f32_16x16x32_bf16 v[74:77], v[188:191], v[212:215], v[74:77]
	v_mfma_f32_16x16x32_bf16 v[70:73], v[196:199], v[204:207], v[70:73]
	v_mfma_f32_16x16x32_bf16 v[66:69], v[196:199], v[212:215], v[66:69]
	v_mfma_f32_16x16x32_bf16 v[94:97], v[176:179], v[208:211], v[94:97]
	s_waitcnt lgkmcnt(0)
	v_mfma_f32_16x16x32_bf16 v[90:93], v[176:179], v[216:219], v[90:93]
	v_mfma_f32_16x16x32_bf16 v[86:89], v[184:187], v[208:211], v[86:89]
	v_mfma_f32_16x16x32_bf16 v[82:85], v[184:187], v[216:219], v[82:85]
	v_mfma_f32_16x16x32_bf16 v[78:81], v[192:195], v[208:211], v[78:81]
	v_mfma_f32_16x16x32_bf16 v[74:77], v[192:195], v[216:219], v[74:77]
	v_mfma_f32_16x16x32_bf16 v[70:73], v[200:203], v[208:211], v[70:73]
	v_mfma_f32_16x16x32_bf16 v[66:69], v[200:203], v[216:219], v[66:69]
	s_mov_b32 m0, s100
	s_barrier
	ds_read_b128 v[172:175], v133 offset:16384
	ds_read_b128 v[176:179], v133 offset:17408
	ds_read_b128 v[180:183], v132 offset:16384
	ds_read_b128 v[184:187], v132 offset:17408
	ds_read_b128 v[188:191], v131 offset:16384
	ds_read_b128 v[192:195], v131 offset:17408
	ds_read_b128 v[196:199], v130 offset:16384
	buffer_load_dwordx4 v137, s[88:91], s3 offen lds
	s_add_i32 m0, s100, 0x2000
	ds_read_b128 v[200:203], v130 offset:17408
	buffer_load_dwordx4 v136, s[88:91], s3 offen lds
	s_barrier
	s_waitcnt lgkmcnt(1)
	v_mfma_f32_16x16x32_bf16 v[62:65], v[172:175], v[156:159], v[62:65]
	v_mfma_f32_16x16x32_bf16 v[58:61], v[172:175], v[164:167], v[58:61]
	v_mfma_f32_16x16x32_bf16 v[54:57], v[180:183], v[156:159], v[54:57]
	v_mfma_f32_16x16x32_bf16 v[50:53], v[180:183], v[164:167], v[50:53]
	v_mfma_f32_16x16x32_bf16 v[46:49], v[188:191], v[156:159], v[46:49]
	v_mfma_f32_16x16x32_bf16 v[42:45], v[188:191], v[164:167], v[42:45]
	v_mfma_f32_16x16x32_bf16 v[38:41], v[196:199], v[156:159], v[38:41]
	v_mfma_f32_16x16x32_bf16 v[34:37], v[196:199], v[164:167], v[34:37]
	v_mfma_f32_16x16x32_bf16 v[62:65], v[176:179], v[160:163], v[62:65]
	v_mfma_f32_16x16x32_bf16 v[58:61], v[176:179], v[168:171], v[58:61]
	v_mfma_f32_16x16x32_bf16 v[54:57], v[184:187], v[160:163], v[54:57]
	v_mfma_f32_16x16x32_bf16 v[50:53], v[184:187], v[168:171], v[50:53]
	v_mfma_f32_16x16x32_bf16 v[46:49], v[192:195], v[160:163], v[46:49]
	v_mfma_f32_16x16x32_bf16 v[42:45], v[192:195], v[168:171], v[42:45]
	s_waitcnt lgkmcnt(0)
	v_mfma_f32_16x16x32_bf16 v[38:41], v[200:203], v[160:163], v[38:41]
	v_mfma_f32_16x16x32_bf16 v[34:37], v[200:203], v[168:171], v[34:37]
	s_barrier
	s_add_i32 m0, s100, 0x14000
	s_add_i32 s3, s1, 0xffffff80
	buffer_load_dwordx4 v137, s[4:7], s3 offen lds
	s_add_i32 m0, s100, 0x16000
	s_nop 0
	buffer_load_dwordx4 v136, s[4:7], s3 offen lds
	s_waitcnt vmcnt(6)
	s_barrier
; #define WAIT_V(n) asm volatile("s_waitcnt vmcnt(" #n ")" ::: "memory")
; #define WAIT_L(n) asm volatile("s_waitcnt lgkmcnt(" #n ")" ::: "memory")
; #define BAR __builtin_amdgcn_s_barrier()
; #define SCHED __builtin_amdgcn_sched_barrier(0)
; __device__ __forceinline__ void mainloop_8phase(const u16* __restrict__ A, const u16* __restrict__ Bt, int K,
;                                                 f32x4 (&acc)[2][2][4][2], int wid_s, int ld) {
;     ...
;     WAIT_V(6); BAR; MMA(1, 1, At, B1); BAR;
;     LDB(B0, 1, 0); SCHED; LDA(At, 1, 0); STAGE(SA(0, 1), A, brow + G_HALF, t + 2);
;     WAIT_L(8); BAR; WAIT_L(0); MMA(0, 0, At, B0); BAR; SCHED;
;     LDB(B1, 1, 1); STAGE(SB(1, 0), Bt, bcol, t + 3);
;     BAR; WAIT_L(0); MMA(0, 1, At, B1); BAR;
;     LDA(At, 1, 1); STAGE(SA(1, 0), A, brow, t + 3);
;     BAR; WAIT_L(0); MMA(1, 0, At, B0); BAR; SCHED;
	v_mfma_f32_16x16x32_bf16 v[30:33], v[172:175], v[204:207], v[30:33]
	v_mfma_f32_16x16x32_bf16 v[26:29], v[172:175], v[212:215], v[26:29]
	v_mfma_f32_16x16x32_bf16 v[22:25], v[180:183], v[204:207], v[22:25]
	v_mfma_f32_16x16x32_bf16 v[18:21], v[180:183], v[212:215], v[18:21]
	v_mfma_f32_16x16x32_bf16 v[14:17], v[188:191], v[204:207], v[14:17]
	v_mfma_f32_16x16x32_bf16 v[10:13], v[188:191], v[212:215], v[10:13]
	v_mfma_f32_16x16x32_bf16 v[6:9], v[196:199], v[204:207], v[6:9]
	v_mfma_f32_16x16x32_bf16 v[2:5], v[196:199], v[212:215], v[2:5]
	v_mfma_f32_16x16x32_bf16 v[30:33], v[176:179], v[208:211], v[30:33]
	v_mfma_f32_16x16x32_bf16 v[26:29], v[176:179], v[216:219], v[26:29]
	v_mfma_f32_16x16x32_bf16 v[22:25], v[184:187], v[208:211], v[22:25]
	v_mfma_f32_16x16x32_bf16 v[18:21], v[184:187], v[216:219], v[18:21]
	v_mfma_f32_16x16x32_bf16 v[14:17], v[192:195], v[208:211], v[14:17]
	v_mfma_f32_16x16x32_bf16 v[10:13], v[192:195], v[216:219], v[10:13]
	v_mfma_f32_16x16x32_bf16 v[6:9], v[200:203], v[208:211], v[6:9]
	v_mfma_f32_16x16x32_bf16 v[2:5], v[200:203], v[216:219], v[2:5]
	s_barrier
	ds_read_b128 v[156:159], v135
	ds_read_b128 v[160:163], v135 offset:1024
	ds_read_b128 v[164:167], v135 offset:2048
	ds_read_b128 v[168:171], v135 offset:3072
	s_add_i32 m0, s100, 0x4000
	ds_read_b128 v[172:175], v133 offset:32768
	ds_read_b128 v[176:179], v133 offset:33792
	ds_read_b128 v[180:183], v132 offset:32768
	ds_read_b128 v[184:187], v132 offset:33792
	ds_read_b128 v[188:191], v131 offset:32768
	ds_read_b128 v[192:195], v131 offset:33792
	ds_read_b128 v[196:199], v130 offset:32768
	buffer_load_dwordx4 v137, s[88:91], s3 offen lds
	s_add_i32 m0, s100, 0x6000
	ds_read_b128 v[200:203], v130 offset:33792
	buffer_load_dwordx4 v136, s[88:91], s3 offen lds
	s_waitcnt lgkmcnt(8)
	s_barrier
	s_waitcnt lgkmcnt(1)
	v_mfma_f32_16x16x32_bf16 v[126:129], v[172:175], v[156:159], v[126:129]
	v_mfma_f32_16x16x32_bf16 v[122:125], v[172:175], v[164:167], v[122:125]
	v_mfma_f32_16x16x32_bf16 v[118:121], v[180:183], v[156:159], v[118:121]
	v_mfma_f32_16x16x32_bf16 v[114:117], v[180:183], v[164:167], v[114:117]
	v_mfma_f32_16x16x32_bf16 v[110:113], v[188:191], v[156:159], v[110:113]
	v_mfma_f32_16x16x32_bf16 v[106:109], v[188:191], v[164:167], v[106:109]
	v_mfma_f32_16x16x32_bf16 v[102:105], v[196:199], v[156:159], v[102:105]
	v_mfma_f32_16x16x32_bf16 v[98:101], v[196:199], v[164:167], v[98:101]
	v_mfma_f32_16x16x32_bf16 v[126:129], v[176:179], v[160:163], v[126:129]
	v_mfma_f32_16x16x32_bf16 v[122:125], v[176:179], v[168:171], v[122:125]
	v_mfma_f32_16x16x32_bf16 v[118:121], v[184:187], v[160:163], v[118:121]
	v_mfma_f32_16x16x32_bf16 v[114:117], v[184:187], v[168:171], v[114:117]
	v_mfma_f32_16x16x32_bf16 v[110:113], v[192:195], v[160:163], v[110:113]
	v_mfma_f32_16x16x32_bf16 v[106:109], v[192:195], v[168:171], v[106:109]
	s_waitcnt lgkmcnt(0)
	v_mfma_f32_16x16x32_bf16 v[102:105], v[200:203], v[160:163], v[102:105]
	v_mfma_f32_16x16x32_bf16 v[98:101], v[200:203], v[168:171], v[98:101]
	s_barrier
	s_add_i32 s3, s1, 0xfff80000
	s_add_i32 m0, s100, 0x18000
	ds_read_b128 v[204:207], v134
	ds_read_b128 v[208:211], v134 offset:1024
	ds_read_b128 v[212:215], v134 offset:2048
	buffer_load_dwordx4 v137, s[4:7], s3 offen lds
	s_add_i32 m0, s100, 0x1a000
	ds_read_b128 v[216:219], v134 offset:3072
	buffer_load_dwordx4 v136, s[4:7], s3 offen lds
	s_barrier
	s_waitcnt lgkmcnt(1)
	v_mfma_f32_16x16x32_bf16 v[94:97], v[172:175], v[204:207], v[94:97]
	v_mfma_f32_16x16x32_bf16 v[90:93], v[172:175], v[212:215], v[90:93]
	v_mfma_f32_16x16x32_bf16 v[86:89], v[180:183], v[204:207], v[86:89]
	v_mfma_f32_16x16x32_bf16 v[82:85], v[180:183], v[212:215], v[82:85]
	v_mfma_f32_16x16x32_bf16 v[78:81], v[188:191], v[204:207], v[78:81]
	v_mfma_f32_16x16x32_bf16 v[74:77], v[188:191], v[212:215], v[74:77]
	v_mfma_f32_16x16x32_bf16 v[70:73], v[196:199], v[204:207], v[70:73]
	v_mfma_f32_16x16x32_bf16 v[66:69], v[196:199], v[212:215], v[66:69]
	v_mfma_f32_16x16x32_bf16 v[94:97], v[176:179], v[208:211], v[94:97]
	s_waitcnt lgkmcnt(0)
	v_mfma_f32_16x16x32_bf16 v[90:93], v[176:179], v[216:219], v[90:93]
	v_mfma_f32_16x16x32_bf16 v[86:89], v[184:187], v[208:211], v[86:89]
	v_mfma_f32_16x16x32_bf16 v[82:85], v[184:187], v[216:219], v[82:85]
	v_mfma_f32_16x16x32_bf16 v[78:81], v[192:195], v[208:211], v[78:81]
	v_mfma_f32_16x16x32_bf16 v[74:77], v[192:195], v[216:219], v[74:77]
	v_mfma_f32_16x16x32_bf16 v[70:73], v[200:203], v[208:211], v[70:73]
	v_mfma_f32_16x16x32_bf16 v[66:69], v[200:203], v[216:219], v[66:69]
	s_add_i32 m0, s100, 0x8000
	s_barrier
	ds_read_b128 v[172:175], v133 offset:49152
	ds_read_b128 v[176:179], v133 offset:50176
	ds_read_b128 v[180:183], v132 offset:49152
	ds_read_b128 v[184:187], v132 offset:50176
	ds_read_b128 v[188:191], v131 offset:49152
	ds_read_b128 v[192:195], v131 offset:50176
	ds_read_b128 v[196:199], v130 offset:49152
	buffer_load_dwordx4 v137, s[88:91], s3 offen lds
	s_add_i32 m0, s100, 0xa000
	ds_read_b128 v[200:203], v130 offset:50176
	buffer_load_dwordx4 v136, s[88:91], s3 offen lds
	s_barrier
	s_waitcnt lgkmcnt(1)
	v_mfma_f32_16x16x32_bf16 v[62:65], v[172:175], v[156:159], v[62:65]
	v_mfma_f32_16x16x32_bf16 v[58:61], v[172:175], v[164:167], v[58:61]
	v_mfma_f32_16x16x32_bf16 v[54:57], v[180:183], v[156:159], v[54:57]
	v_mfma_f32_16x16x32_bf16 v[50:53], v[180:183], v[164:167], v[50:53]
	v_mfma_f32_16x16x32_bf16 v[46:49], v[188:191], v[156:159], v[46:49]
	v_mfma_f32_16x16x32_bf16 v[42:45], v[188:191], v[164:167], v[42:45]
	v_mfma_f32_16x16x32_bf16 v[38:41], v[196:199], v[156:159], v[38:41]
	v_mfma_f32_16x16x32_bf16 v[34:37], v[196:199], v[164:167], v[34:37]
	v_mfma_f32_16x16x32_bf16 v[62:65], v[176:179], v[160:163], v[62:65]
	v_mfma_f32_16x16x32_bf16 v[58:61], v[176:179], v[168:171], v[58:61]
	v_mfma_f32_16x16x32_bf16 v[54:57], v[184:187], v[160:163], v[54:57]
	v_mfma_f32_16x16x32_bf16 v[50:53], v[184:187], v[168:171], v[50:53]
	v_mfma_f32_16x16x32_bf16 v[46:49], v[192:195], v[160:163], v[46:49]
	v_mfma_f32_16x16x32_bf16 v[42:45], v[192:195], v[168:171], v[42:45]
	s_waitcnt lgkmcnt(0)
	v_mfma_f32_16x16x32_bf16 v[38:41], v[200:203], v[160:163], v[38:41]
	v_mfma_f32_16x16x32_bf16 v[34:37], v[200:203], v[168:171], v[34:37]
	s_barrier
; #define WAIT_V(n) asm volatile("s_waitcnt vmcnt(" #n ")" ::: "memory")
; #define WAIT_L(n) asm volatile("s_waitcnt lgkmcnt(" #n ")" ::: "memory")
; #define BAR __builtin_amdgcn_s_barrier()
; __device__ __forceinline__ void mainloop_8phase(const u16* __restrict__ A, const u16* __restrict__ Bt, int K,
;                                                 f32x4 (&acc)[2][2][4][2], int wid_s, int ld) {
;     ...
;     STAGE(SB(1, 1), Bt, bcol + G_HALF, t + 3);
;     WAIT_V(6); BAR; MMA(1, 1, At, B1); BAR;
;   }
;   { LDB(B0, 0, 0); LDA(At, 0, 0); STAGE(SA(1, 1), A, brow + G_HALF, nt - 1);
;     BAR; WAIT_L(0); MMA(0, 0, At, B0); BAR;
;     LDB(B1, 0, 1); BAR; WAIT_L(0); MMA(0, 1, At, B1); BAR;
	s_add_i32 m0, s100, 0x1c000
	s_nop 0
	buffer_load_dwordx4 v137, s[4:7], s1 offen lds
	s_add_i32 m0, s100, 0x1e000
	s_nop 0
	buffer_load_dwordx4 v136, s[4:7], s1 offen lds
	s_waitcnt vmcnt(6)
	s_barrier
	v_mfma_f32_16x16x32_bf16 v[30:33], v[172:175], v[204:207], v[30:33]
	v_mfma_f32_16x16x32_bf16 v[26:29], v[172:175], v[212:215], v[26:29]
	v_mfma_f32_16x16x32_bf16 v[22:25], v[180:183], v[204:207], v[22:25]
	v_mfma_f32_16x16x32_bf16 v[18:21], v[180:183], v[212:215], v[18:21]
	v_mfma_f32_16x16x32_bf16 v[14:17], v[188:191], v[204:207], v[14:17]
	v_mfma_f32_16x16x32_bf16 v[10:13], v[188:191], v[212:215], v[10:13]
	v_mfma_f32_16x16x32_bf16 v[6:9], v[196:199], v[204:207], v[6:9]
	v_mfma_f32_16x16x32_bf16 v[2:5], v[196:199], v[212:215], v[2:5]
	v_mfma_f32_16x16x32_bf16 v[30:33], v[176:179], v[208:211], v[30:33]
	v_mfma_f32_16x16x32_bf16 v[26:29], v[176:179], v[216:219], v[26:29]
	v_mfma_f32_16x16x32_bf16 v[22:25], v[184:187], v[208:211], v[22:25]
	v_mfma_f32_16x16x32_bf16 v[18:21], v[184:187], v[216:219], v[18:21]
	v_mfma_f32_16x16x32_bf16 v[14:17], v[192:195], v[208:211], v[14:17]
	v_mfma_f32_16x16x32_bf16 v[10:13], v[192:195], v[216:219], v[10:13]
	v_mfma_f32_16x16x32_bf16 v[6:9], v[200:203], v[208:211], v[6:9]
	v_mfma_f32_16x16x32_bf16 v[2:5], v[200:203], v[216:219], v[2:5]
	s_add_i32 s0, s0, 2
	s_addk_i32 s1, 0x100
	s_cmp_lt_u32 s0, 28
	s_barrier
	s_cbranch_scc1 .LBB0_247
	v_readfirstlane_b32 s0, v145
	s_mov_b32 m0, s0
	s_mov_b32 s1, 0x80f80
	v_readfirstlane_b32 s0, v144
	ds_read_b128 v[138:141], v155
	ds_read_b128 v[148:151], v155 offset:1024
	ds_read_b128 v[156:159], v155 offset:2048
	ds_read_b128 v[152:155], v155 offset:3072
	ds_read_b128 v[160:163], v133
	ds_read_b128 v[164:167], v133 offset:1024
	ds_read_b128 v[168:171], v132
	ds_read_b128 v[172:175], v132 offset:1024
	ds_read_b128 v[176:179], v131
	ds_read_b128 v[180:183], v131 offset:1024
	ds_read_b128 v[184:187], v130
	ds_read_b128 v[188:191], v130 offset:1024
	buffer_load_dwordx4 v137, s[88:91], s1 offen lds
	s_mov_b32 m0, s0
	s_nop 0
	buffer_load_dwordx4 v136, s[88:91], s1 offen lds
	s_barrier
	s_waitcnt lgkmcnt(0)
	v_mfma_f32_16x16x32_bf16 v[126:129], v[160:163], v[138:141], v[126:129]
	v_mfma_f32_16x16x32_bf16 v[118:121], v[168:171], v[138:141], v[118:121]
	v_mfma_f32_16x16x32_bf16 v[110:113], v[176:179], v[138:141], v[110:113]
	v_mfma_f32_16x16x32_bf16 v[102:105], v[184:187], v[138:141], v[102:105]
	v_mfma_f32_16x16x32_bf16 v[126:129], v[164:167], v[148:151], v[126:129]
	v_mfma_f32_16x16x32_bf16 v[122:125], v[160:163], v[156:159], v[122:125]
	v_mfma_f32_16x16x32_bf16 v[118:121], v[172:175], v[148:151], v[118:121]
	v_mfma_f32_16x16x32_bf16 v[114:117], v[168:171], v[156:159], v[114:117]
	v_mfma_f32_16x16x32_bf16 v[110:113], v[180:183], v[148:151], v[110:113]
	v_mfma_f32_16x16x32_bf16 v[106:109], v[176:179], v[156:159], v[106:109]
	v_mfma_f32_16x16x32_bf16 v[102:105], v[188:191], v[148:151], v[102:105]
	v_mfma_f32_16x16x32_bf16 v[98:101], v[184:187], v[156:159], v[98:101]
	v_mfma_f32_16x16x32_bf16 v[142:145], v[164:167], v[152:155], v[122:125]
	v_mfma_f32_16x16x32_bf16 v[192:195], v[172:175], v[152:155], v[114:117]
	v_mfma_f32_16x16x32_bf16 v[196:199], v[180:183], v[152:155], v[106:109]
	v_mfma_f32_16x16x32_bf16 v[200:203], v[188:191], v[152:155], v[98:101]
	s_barrier
	s_nop 1
	ds_read_b128 v[98:101], v147
	ds_read_b128 v[106:109], v147 offset:1024
	ds_read_b128 v[114:117], v147 offset:2048
	ds_read_b128 v[122:125], v147 offset:3072
	s_barrier
	s_waitcnt lgkmcnt(0)
	v_mfma_f32_16x16x32_bf16 v[94:97], v[160:163], v[98:101], v[94:97]
	v_mfma_f32_16x16x32_bf16 v[90:93], v[160:163], v[114:117], v[90:93]
	v_mfma_f32_16x16x32_bf16 v[86:89], v[168:171], v[98:101], v[86:89]
	v_mfma_f32_16x16x32_bf16 v[82:85], v[168:171], v[114:117], v[82:85]
	v_mfma_f32_16x16x32_bf16 v[78:81], v[176:179], v[98:101], v[78:81]
	v_mfma_f32_16x16x32_bf16 v[74:77], v[176:179], v[114:117], v[74:77]
	v_mfma_f32_16x16x32_bf16 v[70:73], v[184:187], v[98:101], v[70:73]
	v_mfma_f32_16x16x32_bf16 v[66:69], v[184:187], v[114:117], v[66:69]
	v_mfma_f32_16x16x32_bf16 v[94:97], v[164:167], v[106:109], v[94:97]
	v_mfma_f32_16x16x32_bf16 v[90:93], v[164:167], v[122:125], v[90:93]
	v_mfma_f32_16x16x32_bf16 v[86:89], v[172:175], v[106:109], v[86:89]
	v_mfma_f32_16x16x32_bf16 v[82:85], v[172:175], v[122:125], v[82:85]
	v_mfma_f32_16x16x32_bf16 v[78:81], v[180:183], v[106:109], v[78:81]
	v_mfma_f32_16x16x32_bf16 v[74:77], v[180:183], v[122:125], v[74:77]
	v_mfma_f32_16x16x32_bf16 v[70:73], v[188:191], v[106:109], v[70:73]
	v_mfma_f32_16x16x32_bf16 v[66:69], v[188:191], v[122:125], v[66:69]
	s_barrier
	ds_read_b128 v[160:163], v133 offset:16384
	ds_read_b128 v[164:167], v133 offset:17408
	ds_read_b128 v[168:171], v132 offset:16384
	ds_read_b128 v[172:175], v132 offset:17408
	ds_read_b128 v[176:179], v131 offset:16384
	ds_read_b128 v[180:183], v131 offset:17408
	ds_read_b128 v[184:187], v130 offset:16384
	ds_read_b128 v[188:191], v130 offset:17408
	s_waitcnt vmcnt(4)
	s_barrier
; #define WAIT_V(n) asm volatile("s_waitcnt vmcnt(" #n ")" ::: "memory")
; #define WAIT_L(n) asm volatile("s_waitcnt lgkmcnt(" #n ")" ::: "memory")
; #define BAR __builtin_amdgcn_s_barrier()
; __device__ __forceinline__ void mainloop_8phase(const u16* __restrict__ A, const u16* __restrict__ Bt, int K,
;                                                 f32x4 (&acc)[2][2][4][2], int wid_s, int ld) {
;     ...
;     LDA(At, 0, 1); WAIT_V(4); BAR; WAIT_L(0); MMA(1, 0, At, B0); MMA(1, 1, At, B1); BAR; }
;   { LDB(B0, 1, 0); LDA(At, 1, 0); WAIT_V(2); BAR; WAIT_L(0); MMA(0, 0, At, B0); BAR;
	s_waitcnt lgkmcnt(0)
	v_mfma_f32_16x16x32_bf16 v[62:65], v[160:163], v[138:141], v[62:65]
	v_mfma_f32_16x16x32_bf16 v[58:61], v[160:163], v[156:159], v[58:61]
	v_mfma_f32_16x16x32_bf16 v[54:57], v[168:171], v[138:141], v[54:57]
	v_mfma_f32_16x16x32_bf16 v[50:53], v[168:171], v[156:159], v[50:53]
	v_mfma_f32_16x16x32_bf16 v[46:49], v[176:179], v[138:141], v[46:49]
	v_mfma_f32_16x16x32_bf16 v[42:45], v[176:179], v[156:159], v[42:45]
	v_mfma_f32_16x16x32_bf16 v[38:41], v[184:187], v[138:141], v[38:41]
	v_mfma_f32_16x16x32_bf16 v[34:37], v[184:187], v[156:159], v[34:37]
	v_mfma_f32_16x16x32_bf16 v[204:207], v[164:167], v[148:151], v[62:65]
	v_mfma_f32_16x16x32_bf16 v[208:211], v[164:167], v[152:155], v[58:61]
	v_mfma_f32_16x16x32_bf16 v[212:215], v[172:175], v[148:151], v[54:57]
	v_mfma_f32_16x16x32_bf16 v[216:219], v[172:175], v[152:155], v[50:53]
	v_mfma_f32_16x16x32_bf16 v[220:223], v[180:183], v[148:151], v[46:49]
	v_mfma_f32_16x16x32_bf16 v[224:227], v[180:183], v[152:155], v[42:45]
	v_mfma_f32_16x16x32_bf16 v[136:139], v[188:191], v[148:151], v[38:41]
	v_mfma_f32_16x16x32_bf16 v[146:149], v[188:191], v[152:155], v[34:37]
	v_mfma_f32_16x16x32_bf16 v[30:33], v[160:163], v[98:101], v[30:33]
	v_mfma_f32_16x16x32_bf16 v[22:25], v[168:171], v[98:101], v[22:25]
	v_mfma_f32_16x16x32_bf16 v[14:17], v[176:179], v[98:101], v[14:17]
	v_mfma_f32_16x16x32_bf16 v[6:9], v[184:187], v[98:101], v[6:9]
	v_mfma_f32_16x16x32_bf16 v[30:33], v[164:167], v[106:109], v[30:33]
	v_mfma_f32_16x16x32_bf16 v[26:29], v[160:163], v[114:117], v[26:29]
	v_mfma_f32_16x16x32_bf16 v[22:25], v[172:175], v[106:109], v[22:25]
	v_mfma_f32_16x16x32_bf16 v[18:21], v[168:171], v[114:117], v[18:21]
	v_mfma_f32_16x16x32_bf16 v[14:17], v[180:183], v[106:109], v[14:17]
	v_mfma_f32_16x16x32_bf16 v[10:13], v[176:179], v[114:117], v[10:13]
	v_mfma_f32_16x16x32_bf16 v[6:9], v[188:191], v[106:109], v[6:9]
	v_mfma_f32_16x16x32_bf16 v[2:5], v[184:187], v[114:117], v[2:5]
	v_mfma_f32_16x16x32_bf16 v[150:153], v[164:167], v[122:125], v[26:29]
	v_mfma_f32_16x16x32_bf16 v[154:157], v[172:175], v[122:125], v[18:21]
	v_mfma_f32_16x16x32_bf16 v[158:161], v[180:183], v[122:125], v[10:13]
	v_mfma_f32_16x16x32_bf16 v[162:165], v[188:191], v[122:125], v[2:5]
	s_barrier
	s_nop 1
	ds_read_b128 v[2:5], v135
	ds_read_b128 v[10:13], v135 offset:1024
	ds_read_b128 v[18:21], v135 offset:2048
	ds_read_b128 v[26:29], v135 offset:3072
	ds_read_b128 v[34:37], v133 offset:32768
	ds_read_b128 v[38:41], v133 offset:33792
	ds_read_b128 v[42:45], v132 offset:32768
	ds_read_b128 v[46:49], v132 offset:33792
	ds_read_b128 v[166:169], v131 offset:32768
	ds_read_b128 v[170:173], v131 offset:33792
	ds_read_b128 v[174:177], v130 offset:32768
	ds_read_b128 v[178:181], v130 offset:33792
	s_waitcnt vmcnt(2)
	s_barrier
	s_waitcnt lgkmcnt(0)
	v_mfma_f32_16x16x32_bf16 v[50:53], v[34:37], v[2:5], v[126:129]
	v_mfma_f32_16x16x32_bf16 v[122:125], v[38:41], v[10:13], v[50:53]
	v_mfma_f32_16x16x32_bf16 v[50:53], v[34:37], v[18:21], v[142:145]
	v_mfma_f32_16x16x32_bf16 v[126:129], v[38:41], v[26:29], v[50:53]
	v_mfma_f32_16x16x32_bf16 v[50:53], v[42:45], v[2:5], v[118:121]
	v_mfma_f32_16x16x32_bf16 v[114:117], v[46:49], v[10:13], v[50:53]
	v_mfma_f32_16x16x32_bf16 v[50:53], v[42:45], v[18:21], v[192:195]
	v_mfma_f32_16x16x32_bf16 v[118:121], v[46:49], v[26:29], v[50:53]
	v_mfma_f32_16x16x32_bf16 v[50:53], v[166:169], v[2:5], v[110:113]
	v_mfma_f32_16x16x32_bf16 v[106:109], v[170:173], v[10:13], v[50:53]
	v_mfma_f32_16x16x32_bf16 v[50:53], v[166:169], v[18:21], v[196:199]
	v_mfma_f32_16x16x32_bf16 v[110:113], v[170:173], v[26:29], v[50:53]
	v_mfma_f32_16x16x32_bf16 v[50:53], v[174:177], v[2:5], v[102:105]
	v_mfma_f32_16x16x32_bf16 v[98:101], v[178:181], v[10:13], v[50:53]
	v_mfma_f32_16x16x32_bf16 v[50:53], v[174:177], v[18:21], v[200:203]
	v_mfma_f32_16x16x32_bf16 v[102:105], v[178:181], v[26:29], v[50:53]
	s_barrier
; #define WAIT_V(n) asm volatile("s_waitcnt vmcnt(" #n ")" ::: "memory")
; #define WAIT_L(n) asm volatile("s_waitcnt lgkmcnt(" #n ")" ::: "memory")
; #define BAR __builtin_amdgcn_s_barrier()
; __device__ __forceinline__ void mainloop_8phase(const u16* __restrict__ A, const u16* __restrict__ Bt, int K,
;                                                 f32x4 (&acc)[2][2][4][2], int wid_s, int ld) {
;     ...
;     LDB(B1, 1, 1); WAIT_V(0); BAR; WAIT_L(0); MMA(0, 1, At, B1); BAR;
;     LDA(At, 1, 1); BAR; WAIT_L(0); MMA(1, 0, At, B0); MMA(1, 1, At, B1); BAR; }
;   if (wr == 0) BAR;
	ds_read_b128 v[140:143], v134
	ds_read_b128 v[182:185], v134 offset:1024
	ds_read_b128 v[186:189], v134 offset:2048
	ds_read_b128 v[190:193], v134 offset:3072
	s_waitcnt vmcnt(0)
	s_barrier
	s_waitcnt lgkmcnt(0)
	v_mfma_f32_16x16x32_bf16 v[50:53], v[34:37], v[140:143], v[94:97]
	v_mfma_f32_16x16x32_bf16 v[34:37], v[34:37], v[186:189], v[90:93]
	v_mfma_f32_16x16x32_bf16 v[62:65], v[38:41], v[190:193], v[34:37]
	v_mfma_f32_16x16x32_bf16 v[34:37], v[42:45], v[140:143], v[86:89]
	v_mfma_f32_16x16x32_bf16 v[58:61], v[38:41], v[182:185], v[50:53]
	v_mfma_f32_16x16x32_bf16 v[50:53], v[46:49], v[182:185], v[34:37]
	v_mfma_f32_16x16x32_bf16 v[34:37], v[42:45], v[186:189], v[82:85]
	v_mfma_f32_16x16x32_bf16 v[54:57], v[46:49], v[190:193], v[34:37]
	v_mfma_f32_16x16x32_bf16 v[34:37], v[166:169], v[140:143], v[78:81]
	v_mfma_f32_16x16x32_bf16 v[42:45], v[170:173], v[182:185], v[34:37]
	v_mfma_f32_16x16x32_bf16 v[34:37], v[166:169], v[186:189], v[74:77]
	v_mfma_f32_16x16x32_bf16 v[46:49], v[170:173], v[190:193], v[34:37]
	v_mfma_f32_16x16x32_bf16 v[34:37], v[174:177], v[140:143], v[70:73]
	v_mfma_f32_16x16x32_bf16 v[38:41], v[174:177], v[186:189], v[66:69]
	v_mfma_f32_16x16x32_bf16 v[34:37], v[178:181], v[182:185], v[34:37]
	v_mfma_f32_16x16x32_bf16 v[38:41], v[178:181], v[190:193], v[38:41]
	s_barrier
	ds_read_b128 v[166:169], v133 offset:49152
	ds_read_b128 v[170:173], v133 offset:50176
	ds_read_b128 v[174:177], v132 offset:49152
	ds_read_b128 v[132:135], v132 offset:50176
	ds_read_b128 v[178:181], v131 offset:49152
	ds_read_b128 v[194:197], v131 offset:50176
	ds_read_b128 v[198:201], v130 offset:49152
	ds_read_b128 v[228:231], v130 offset:50176
	s_barrier
	s_waitcnt lgkmcnt(0)
	v_mfma_f32_16x16x32_bf16 v[66:69], v[166:169], v[2:5], v[204:207]
	v_mfma_f32_16x16x32_bf16 v[90:93], v[170:173], v[10:13], v[66:69]
	v_mfma_f32_16x16x32_bf16 v[66:69], v[166:169], v[18:21], v[208:211]
	v_mfma_f32_16x16x32_bf16 v[94:97], v[170:173], v[26:29], v[66:69]
	v_mfma_f32_16x16x32_bf16 v[66:69], v[174:177], v[2:5], v[212:215]
	v_mfma_f32_16x16x32_bf16 v[82:85], v[132:135], v[10:13], v[66:69]
	v_mfma_f32_16x16x32_bf16 v[66:69], v[174:177], v[18:21], v[216:219]
	v_mfma_f32_16x16x32_bf16 v[86:89], v[132:135], v[26:29], v[66:69]
	v_mfma_f32_16x16x32_bf16 v[66:69], v[178:181], v[2:5], v[220:223]
	v_mfma_f32_16x16x32_bf16 v[74:77], v[194:197], v[10:13], v[66:69]
	v_mfma_f32_16x16x32_bf16 v[66:69], v[178:181], v[18:21], v[224:227]
	v_mfma_f32_16x16x32_bf16 v[2:5], v[198:201], v[2:5], v[136:139]
	v_mfma_f32_16x16x32_bf16 v[78:81], v[194:197], v[26:29], v[66:69]
	v_mfma_f32_16x16x32_bf16 v[66:69], v[228:231], v[10:13], v[2:5]
	v_mfma_f32_16x16x32_bf16 v[2:5], v[198:201], v[18:21], v[146:149]
	v_mfma_f32_16x16x32_bf16 v[70:73], v[228:231], v[26:29], v[2:5]
	v_mfma_f32_16x16x32_bf16 v[2:5], v[166:169], v[140:143], v[30:33]
	v_mfma_f32_16x16x32_bf16 v[26:29], v[170:173], v[182:185], v[2:5]
	v_mfma_f32_16x16x32_bf16 v[2:5], v[166:169], v[186:189], v[150:153]
	v_mfma_f32_16x16x32_bf16 v[30:33], v[170:173], v[190:193], v[2:5]
	v_mfma_f32_16x16x32_bf16 v[2:5], v[174:177], v[140:143], v[22:25]
	v_mfma_f32_16x16x32_bf16 v[18:21], v[132:135], v[182:185], v[2:5]
	v_mfma_f32_16x16x32_bf16 v[2:5], v[174:177], v[186:189], v[154:157]
	v_mfma_f32_16x16x32_bf16 v[22:25], v[132:135], v[190:193], v[2:5]
	v_mfma_f32_16x16x32_bf16 v[2:5], v[178:181], v[140:143], v[14:17]
	v_mfma_f32_16x16x32_bf16 v[10:13], v[194:197], v[182:185], v[2:5]
	v_mfma_f32_16x16x32_bf16 v[2:5], v[178:181], v[186:189], v[158:161]
	v_mfma_f32_16x16x32_bf16 v[14:17], v[194:197], v[190:193], v[2:5]
	v_mfma_f32_16x16x32_bf16 v[2:5], v[198:201], v[140:143], v[6:9]
	v_mfma_f32_16x16x32_bf16 v[6:9], v[198:201], v[186:189], v[162:165]
	v_mfma_f32_16x16x32_bf16 v[2:5], v[228:231], v[182:185], v[2:5]
	v_mfma_f32_16x16x32_bf16 v[6:9], v[228:231], v[190:193], v[6:9]
	s_movk_i32 s0, 0x100
	v_cmp_gt_u32_e32 vcc, s0, v0
	s_barrier
	s_and_saveexec_b64 s[0:1], vcc
	s_cbranch_execz .LBB0_250
	s_barrier

; #define WAIT_V(n) asm volatile("s_waitcnt vmcnt(" #n ")" ::: "memory")
; #define WAIT_L(n) asm volatile("s_waitcnt lgkmcnt(" #n ")" ::: "memory")
; #define BAR __builtin_amdgcn_s_barrier()
; #define SCHED __builtin_amdgcn_sched_barrier(0)
; __device__ __forceinline__ void mainloop_8phase(const u16* __restrict__ A, const u16* __restrict__ Bt, int K,
;                                                 f32x4 (&acc)[2][2][4][2], int wid_s, int ld) {
;     ...
;     LDB(B0, 0, 0); SCHED; LDA(At, 0, 0); STAGE(SA(1, 1), A, brow + G_HALF, t + 1);
;     WAIT_L(8); BAR; WAIT_L(0); MMA(0, 0, At, B0); BAR; SCHED;
;     LDB(B1, 0, 1); STAGE(SB(0, 0), Bt, bcol, t + 2);
;     BAR; WAIT_L(0); MMA(0, 1, At, B1); BAR;
;     LDA(At, 0, 1); STAGE(SA(0, 0), A, brow, t + 2);
;     BAR; WAIT_L(0); MMA(1, 0, At, B0); BAR; SCHED;
;     STAGE(SB(0, 1), Bt, bcol + G_HALF, t + 2);
;     WAIT_V(6); BAR; MMA(1, 1, At, B1); BAR;
.LBB0_342:
	ds_read_b128 v[156:159], v155
	ds_read_b128 v[160:163], v155 offset:1024
	ds_read_b128 v[164:167], v155 offset:2048
	ds_read_b128 v[168:171], v155 offset:3072
	s_add_i32 s3, s2, 0xffffff00
	s_add_i32 m0, s100, 0xc000
	ds_read_b128 v[172:175], v133
	ds_read_b128 v[176:179], v133 offset:1024
	ds_read_b128 v[180:183], v132
	ds_read_b128 v[184:187], v132 offset:1024
	ds_read_b128 v[188:191], v131
	ds_read_b128 v[192:195], v131 offset:1024
	ds_read_b128 v[196:199], v130
	buffer_load_dwordx4 v136, s[88:91], s3 offen lds
	s_add_i32 m0, s100, 0xe000
	ds_read_b128 v[200:203], v130 offset:1024
	buffer_load_dwordx4 v135, s[88:91], s3 offen lds
	s_waitcnt lgkmcnt(8)
	s_barrier
	s_waitcnt lgkmcnt(1)
	v_mfma_f32_16x16x32_bf16 v[126:129], v[172:175], v[156:159], v[126:129]
	v_mfma_f32_16x16x32_bf16 v[122:125], v[172:175], v[164:167], v[122:125]
	v_mfma_f32_16x16x32_bf16 v[118:121], v[180:183], v[156:159], v[118:121]
	v_mfma_f32_16x16x32_bf16 v[114:117], v[180:183], v[164:167], v[114:117]
	v_mfma_f32_16x16x32_bf16 v[110:113], v[188:191], v[156:159], v[110:113]
	v_mfma_f32_16x16x32_bf16 v[106:109], v[188:191], v[164:167], v[106:109]
	v_mfma_f32_16x16x32_bf16 v[102:105], v[196:199], v[156:159], v[102:105]
	v_mfma_f32_16x16x32_bf16 v[98:101], v[196:199], v[164:167], v[98:101]
	v_mfma_f32_16x16x32_bf16 v[126:129], v[176:179], v[160:163], v[126:129]
	v_mfma_f32_16x16x32_bf16 v[122:125], v[176:179], v[168:171], v[122:125]
	v_mfma_f32_16x16x32_bf16 v[118:121], v[184:187], v[160:163], v[118:121]
	v_mfma_f32_16x16x32_bf16 v[114:117], v[184:187], v[168:171], v[114:117]
	v_mfma_f32_16x16x32_bf16 v[110:113], v[192:195], v[160:163], v[110:113]
	v_mfma_f32_16x16x32_bf16 v[106:109], v[192:195], v[168:171], v[106:109]
	s_waitcnt lgkmcnt(0)
	v_mfma_f32_16x16x32_bf16 v[102:105], v[200:203], v[160:163], v[102:105]
	v_mfma_f32_16x16x32_bf16 v[98:101], v[200:203], v[168:171], v[98:101]
	s_barrier
	s_add_i32 s3, s2, 0xfff7ff80
	s_add_i32 m0, s100, 0x10000
	ds_read_b128 v[204:207], v147
	ds_read_b128 v[208:211], v147 offset:1024
	ds_read_b128 v[212:215], v147 offset:2048
	buffer_load_dwordx4 v136, s[4:7], s3 offen lds
	s_add_i32 m0, s100, 0x12000
	ds_read_b128 v[216:219], v147 offset:3072
	buffer_load_dwordx4 v135, s[4:7], s3 offen lds
	s_barrier
	s_waitcnt lgkmcnt(1)
	v_mfma_f32_16x16x32_bf16 v[94:97], v[172:175], v[204:207], v[94:97]
	v_mfma_f32_16x16x32_bf16 v[90:93], v[172:175], v[212:215], v[90:93]
	v_mfma_f32_16x16x32_bf16 v[86:89], v[180:183], v[204:207], v[86:89]
	v_mfma_f32_16x16x32_bf16 v[82:85], v[180:183], v[212:215], v[82:85]
	v_mfma_f32_16x16x32_bf16 v[78:81], v[188:191], v[204:207], v[78:81]
	v_mfma_f32_16x16x32_bf16 v[74:77], v[188:191], v[212:215], v[74:77]
	v_mfma_f32_16x16x32_bf16 v[70:73], v[196:199], v[204:207], v[70:73]
	v_mfma_f32_16x16x32_bf16 v[66:69], v[196:199], v[212:215], v[66:69]
	v_mfma_f32_16x16x32_bf16 v[94:97], v[176:179], v[208:211], v[94:97]
	s_waitcnt lgkmcnt(0)
	v_mfma_f32_16x16x32_bf16 v[90:93], v[176:179], v[216:219], v[90:93]
	v_mfma_f32_16x16x32_bf16 v[86:89], v[184:187], v[208:211], v[86:89]
	v_mfma_f32_16x16x32_bf16 v[82:85], v[184:187], v[216:219], v[82:85]
	v_mfma_f32_16x16x32_bf16 v[78:81], v[192:195], v[208:211], v[78:81]
	v_mfma_f32_16x16x32_bf16 v[74:77], v[192:195], v[216:219], v[74:77]
	v_mfma_f32_16x16x32_bf16 v[70:73], v[200:203], v[208:211], v[70:73]
	v_mfma_f32_16x16x32_bf16 v[66:69], v[200:203], v[216:219], v[66:69]
	s_mov_b32 m0, s100
	s_barrier
	ds_read_b128 v[172:175], v133 offset:16384
	ds_read_b128 v[176:179], v133 offset:17408
	ds_read_b128 v[180:183], v132 offset:16384
	ds_read_b128 v[184:187], v132 offset:17408
	ds_read_b128 v[188:191], v131 offset:16384
	ds_read_b128 v[192:195], v131 offset:17408
	ds_read_b128 v[196:199], v130 offset:16384
	buffer_load_dwordx4 v136, s[88:91], s3 offen lds
	s_add_i32 m0, s100, 0x2000
	ds_read_b128 v[200:203], v130 offset:17408
	buffer_load_dwordx4 v135, s[88:91], s3 offen lds
	s_barrier
	s_waitcnt lgkmcnt(1)
	v_mfma_f32_16x16x32_bf16 v[62:65], v[172:175], v[156:159], v[62:65]
	v_mfma_f32_16x16x32_bf16 v[58:61], v[172:175], v[164:167], v[58:61]
	v_mfma_f32_16x16x32_bf16 v[54:57], v[180:183], v[156:159], v[54:57]
	v_mfma_f32_16x16x32_bf16 v[50:53], v[180:183], v[164:167], v[50:53]
	v_mfma_f32_16x16x32_bf16 v[46:49], v[188:191], v[156:159], v[46:49]
	v_mfma_f32_16x16x32_bf16 v[42:45], v[188:191], v[164:167], v[42:45]
	v_mfma_f32_16x16x32_bf16 v[38:41], v[196:199], v[156:159], v[38:41]
	v_mfma_f32_16x16x32_bf16 v[34:37], v[196:199], v[164:167], v[34:37]
	v_mfma_f32_16x16x32_bf16 v[62:65], v[176:179], v[160:163], v[62:65]
	v_mfma_f32_16x16x32_bf16 v[58:61], v[176:179], v[168:171], v[58:61]
	v_mfma_f32_16x16x32_bf16 v[54:57], v[184:187], v[160:163], v[54:57]
	v_mfma_f32_16x16x32_bf16 v[50:53], v[184:187], v[168:171], v[50:53]
	v_mfma_f32_16x16x32_bf16 v[46:49], v[192:195], v[160:163], v[46:49]
	v_mfma_f32_16x16x32_bf16 v[42:45], v[192:195], v[168:171], v[42:45]
	s_waitcnt lgkmcnt(0)
	v_mfma_f32_16x16x32_bf16 v[38:41], v[200:203], v[160:163], v[38:41]
	v_mfma_f32_16x16x32_bf16 v[34:37], v[200:203], v[168:171], v[34:37]
	s_barrier
	s_add_i32 m0, s100, 0x14000
	s_add_i32 s3, s2, 0xffffff80
	buffer_load_dwordx4 v136, s[4:7], s3 offen lds
	s_add_i32 m0, s100, 0x16000
	s_nop 0
	buffer_load_dwordx4 v135, s[4:7], s3 offen lds
	s_waitcnt vmcnt(6)
	s_barrier
; #define WAIT_V(n) asm volatile("s_waitcnt vmcnt(" #n ")" ::: "memory")
; #define WAIT_L(n) asm volatile("s_waitcnt lgkmcnt(" #n ")" ::: "memory")
; #define BAR __builtin_amdgcn_s_barrier()
; #define SCHED __builtin_amdgcn_sched_barrier(0)
; __device__ __forceinline__ void mainloop_8phase(const u16* __restrict__ A, const u16* __restrict__ Bt, int K,
;                                                 f32x4 (&acc)[2][2][4][2], int wid_s, int ld) {
;     ...
;     WAIT_V(6); BAR; MMA(1, 1, At, B1); BAR;
;     LDB(B0, 1, 0); SCHED; LDA(At, 1, 0); STAGE(SA(0, 1), A, brow + G_HALF, t + 2);
;     WAIT_L(8); BAR; WAIT_L(0); MMA(0, 0, At, B0); BAR; SCHED;
;     LDB(B1, 1, 1); STAGE(SB(1, 0), Bt, bcol, t + 3);
;     BAR; WAIT_L(0); MMA(0, 1, At, B1); BAR;
;     LDA(At, 1, 1); STAGE(SA(1, 0), A, brow, t + 3);
;     BAR; WAIT_L(0); MMA(1, 0, At, B0); BAR; SCHED;
	v_mfma_f32_16x16x32_bf16 v[30:33], v[172:175], v[204:207], v[30:33]
	v_mfma_f32_16x16x32_bf16 v[26:29], v[172:175], v[212:215], v[26:29]
	v_mfma_f32_16x16x32_bf16 v[22:25], v[180:183], v[204:207], v[22:25]
	v_mfma_f32_16x16x32_bf16 v[18:21], v[180:183], v[212:215], v[18:21]
	v_mfma_f32_16x16x32_bf16 v[14:17], v[188:191], v[204:207], v[14:17]
	v_mfma_f32_16x16x32_bf16 v[10:13], v[188:191], v[212:215], v[10:13]
	v_mfma_f32_16x16x32_bf16 v[6:9], v[196:199], v[204:207], v[6:9]
	v_mfma_f32_16x16x32_bf16 v[2:5], v[196:199], v[212:215], v[2:5]
	v_mfma_f32_16x16x32_bf16 v[30:33], v[176:179], v[208:211], v[30:33]
	v_mfma_f32_16x16x32_bf16 v[26:29], v[176:179], v[216:219], v[26:29]
	v_mfma_f32_16x16x32_bf16 v[22:25], v[184:187], v[208:211], v[22:25]
	v_mfma_f32_16x16x32_bf16 v[18:21], v[184:187], v[216:219], v[18:21]
	v_mfma_f32_16x16x32_bf16 v[14:17], v[192:195], v[208:211], v[14:17]
	v_mfma_f32_16x16x32_bf16 v[10:13], v[192:195], v[216:219], v[10:13]
	v_mfma_f32_16x16x32_bf16 v[6:9], v[200:203], v[208:211], v[6:9]
	v_mfma_f32_16x16x32_bf16 v[2:5], v[200:203], v[216:219], v[2:5]
	s_barrier
	ds_read_b128 v[156:159], v137
	ds_read_b128 v[160:163], v137 offset:1024
	ds_read_b128 v[164:167], v137 offset:2048
	ds_read_b128 v[168:171], v137 offset:3072
	s_add_i32 m0, s100, 0x4000
	ds_read_b128 v[172:175], v133 offset:32768
	ds_read_b128 v[176:179], v133 offset:33792
	ds_read_b128 v[180:183], v132 offset:32768
	ds_read_b128 v[184:187], v132 offset:33792
	ds_read_b128 v[188:191], v131 offset:32768
	ds_read_b128 v[192:195], v131 offset:33792
	ds_read_b128 v[196:199], v130 offset:32768
	buffer_load_dwordx4 v136, s[88:91], s3 offen lds
	s_add_i32 m0, s100, 0x6000
	ds_read_b128 v[200:203], v130 offset:33792
	buffer_load_dwordx4 v135, s[88:91], s3 offen lds
	s_waitcnt lgkmcnt(8)
	s_barrier
	s_waitcnt lgkmcnt(1)
	v_mfma_f32_16x16x32_bf16 v[126:129], v[172:175], v[156:159], v[126:129]
	v_mfma_f32_16x16x32_bf16 v[122:125], v[172:175], v[164:167], v[122:125]
	v_mfma_f32_16x16x32_bf16 v[118:121], v[180:183], v[156:159], v[118:121]
	v_mfma_f32_16x16x32_bf16 v[114:117], v[180:183], v[164:167], v[114:117]
	v_mfma_f32_16x16x32_bf16 v[110:113], v[188:191], v[156:159], v[110:113]
	v_mfma_f32_16x16x32_bf16 v[106:109], v[188:191], v[164:167], v[106:109]
	v_mfma_f32_16x16x32_bf16 v[102:105], v[196:199], v[156:159], v[102:105]
	v_mfma_f32_16x16x32_bf16 v[98:101], v[196:199], v[164:167], v[98:101]
	v_mfma_f32_16x16x32_bf16 v[126:129], v[176:179], v[160:163], v[126:129]
	v_mfma_f32_16x16x32_bf16 v[122:125], v[176:179], v[168:171], v[122:125]
	v_mfma_f32_16x16x32_bf16 v[118:121], v[184:187], v[160:163], v[118:121]
	v_mfma_f32_16x16x32_bf16 v[114:117], v[184:187], v[168:171], v[114:117]
	v_mfma_f32_16x16x32_bf16 v[110:113], v[192:195], v[160:163], v[110:113]
	v_mfma_f32_16x16x32_bf16 v[106:109], v[192:195], v[168:171], v[106:109]
	s_waitcnt lgkmcnt(0)
	v_mfma_f32_16x16x32_bf16 v[102:105], v[200:203], v[160:163], v[102:105]
	v_mfma_f32_16x16x32_bf16 v[98:101], v[200:203], v[168:171], v[98:101]
	s_barrier
	s_add_i32 s3, s2, 0xfff80000
	s_add_i32 m0, s100, 0x18000
	ds_read_b128 v[204:207], v134
	ds_read_b128 v[208:211], v134 offset:1024
	ds_read_b128 v[212:215], v134 offset:2048
	buffer_load_dwordx4 v136, s[4:7], s3 offen lds
	s_add_i32 m0, s100, 0x1a000
	ds_read_b128 v[216:219], v134 offset:3072
	buffer_load_dwordx4 v135, s[4:7], s3 offen lds
	s_barrier
	s_waitcnt lgkmcnt(1)
	v_mfma_f32_16x16x32_bf16 v[94:97], v[172:175], v[204:207], v[94:97]
	v_mfma_f32_16x16x32_bf16 v[90:93], v[172:175], v[212:215], v[90:93]
	v_mfma_f32_16x16x32_bf16 v[86:89], v[180:183], v[204:207], v[86:89]
	v_mfma_f32_16x16x32_bf16 v[82:85], v[180:183], v[212:215], v[82:85]
	v_mfma_f32_16x16x32_bf16 v[78:81], v[188:191], v[204:207], v[78:81]
	v_mfma_f32_16x16x32_bf16 v[74:77], v[188:191], v[212:215], v[74:77]
	v_mfma_f32_16x16x32_bf16 v[70:73], v[196:199], v[204:207], v[70:73]
	v_mfma_f32_16x16x32_bf16 v[66:69], v[196:199], v[212:215], v[66:69]
	v_mfma_f32_16x16x32_bf16 v[94:97], v[176:179], v[208:211], v[94:97]
	s_waitcnt lgkmcnt(0)
	v_mfma_f32_16x16x32_bf16 v[90:93], v[176:179], v[216:219], v[90:93]
	v_mfma_f32_16x16x32_bf16 v[86:89], v[184:187], v[208:211], v[86:89]
	v_mfma_f32_16x16x32_bf16 v[82:85], v[184:187], v[216:219], v[82:85]
	v_mfma_f32_16x16x32_bf16 v[78:81], v[192:195], v[208:211], v[78:81]
	v_mfma_f32_16x16x32_bf16 v[74:77], v[192:195], v[216:219], v[74:77]
	v_mfma_f32_16x16x32_bf16 v[70:73], v[200:203], v[208:211], v[70:73]
	v_mfma_f32_16x16x32_bf16 v[66:69], v[200:203], v[216:219], v[66:69]
	s_add_i32 m0, s100, 0x8000
	s_barrier
	ds_read_b128 v[172:175], v133 offset:49152
	ds_read_b128 v[176:179], v133 offset:50176
	ds_read_b128 v[180:183], v132 offset:49152
	ds_read_b128 v[184:187], v132 offset:50176
	ds_read_b128 v[188:191], v131 offset:49152
	ds_read_b128 v[192:195], v131 offset:50176
	ds_read_b128 v[196:199], v130 offset:49152
	buffer_load_dwordx4 v136, s[88:91], s3 offen lds
	s_add_i32 m0, s100, 0xa000
	ds_read_b128 v[200:203], v130 offset:50176
	buffer_load_dwordx4 v135, s[88:91], s3 offen lds
	s_barrier
	s_waitcnt lgkmcnt(1)
	v_mfma_f32_16x16x32_bf16 v[62:65], v[172:175], v[156:159], v[62:65]
	v_mfma_f32_16x16x32_bf16 v[58:61], v[172:175], v[164:167], v[58:61]
	v_mfma_f32_16x16x32_bf16 v[54:57], v[180:183], v[156:159], v[54:57]
	v_mfma_f32_16x16x32_bf16 v[50:53], v[180:183], v[164:167], v[50:53]
	v_mfma_f32_16x16x32_bf16 v[46:49], v[188:191], v[156:159], v[46:49]
	v_mfma_f32_16x16x32_bf16 v[42:45], v[188:191], v[164:167], v[42:45]
	v_mfma_f32_16x16x32_bf16 v[38:41], v[196:199], v[156:159], v[38:41]
	v_mfma_f32_16x16x32_bf16 v[34:37], v[196:199], v[164:167], v[34:37]
	v_mfma_f32_16x16x32_bf16 v[62:65], v[176:179], v[160:163], v[62:65]
	v_mfma_f32_16x16x32_bf16 v[58:61], v[176:179], v[168:171], v[58:61]
	v_mfma_f32_16x16x32_bf16 v[54:57], v[184:187], v[160:163], v[54:57]
	v_mfma_f32_16x16x32_bf16 v[50:53], v[184:187], v[168:171], v[50:53]
	v_mfma_f32_16x16x32_bf16 v[46:49], v[192:195], v[160:163], v[46:49]
	v_mfma_f32_16x16x32_bf16 v[42:45], v[192:195], v[168:171], v[42:45]
	s_waitcnt lgkmcnt(0)
	v_mfma_f32_16x16x32_bf16 v[38:41], v[200:203], v[160:163], v[38:41]
	v_mfma_f32_16x16x32_bf16 v[34:37], v[200:203], v[168:171], v[34:37]
	s_barrier
; #define WAIT_V(n) asm volatile("s_waitcnt vmcnt(" #n ")" ::: "memory")
; #define WAIT_L(n) asm volatile("s_waitcnt lgkmcnt(" #n ")" ::: "memory")
; #define BAR __builtin_amdgcn_s_barrier()
; __device__ __forceinline__ void mainloop_8phase(const u16* __restrict__ A, const u16* __restrict__ Bt, int K,
;                                                 f32x4 (&acc)[2][2][4][2], int wid_s, int ld) {
;     ...
;     STAGE(SB(1, 1), Bt, bcol + G_HALF, t + 3);
;     WAIT_V(6); BAR; MMA(1, 1, At, B1); BAR;
;   }
;   { LDB(B0, 0, 0); LDA(At, 0, 0); STAGE(SA(1, 1), A, brow + G_HALF, nt - 1);
;     BAR; WAIT_L(0); MMA(0, 0, At, B0); BAR;
;     LDB(B1, 0, 1); BAR; WAIT_L(0); MMA(0, 1, At, B1); BAR;
	s_add_i32 m0, s100, 0x1c000
	s_nop 0
	buffer_load_dwordx4 v136, s[4:7], s2 offen lds
	s_add_i32 m0, s100, 0x1e000
	s_nop 0
	buffer_load_dwordx4 v135, s[4:7], s2 offen lds
	s_waitcnt vmcnt(6)
	s_barrier
	v_mfma_f32_16x16x32_bf16 v[30:33], v[172:175], v[204:207], v[30:33]
	v_mfma_f32_16x16x32_bf16 v[26:29], v[172:175], v[212:215], v[26:29]
	v_mfma_f32_16x16x32_bf16 v[22:25], v[180:183], v[204:207], v[22:25]
	v_mfma_f32_16x16x32_bf16 v[18:21], v[180:183], v[212:215], v[18:21]
	v_mfma_f32_16x16x32_bf16 v[14:17], v[188:191], v[204:207], v[14:17]
	v_mfma_f32_16x16x32_bf16 v[10:13], v[188:191], v[212:215], v[10:13]
	v_mfma_f32_16x16x32_bf16 v[6:9], v[196:199], v[204:207], v[6:9]
	v_mfma_f32_16x16x32_bf16 v[2:5], v[196:199], v[212:215], v[2:5]
	v_mfma_f32_16x16x32_bf16 v[30:33], v[176:179], v[208:211], v[30:33]
	v_mfma_f32_16x16x32_bf16 v[26:29], v[176:179], v[216:219], v[26:29]
	v_mfma_f32_16x16x32_bf16 v[22:25], v[184:187], v[208:211], v[22:25]
	v_mfma_f32_16x16x32_bf16 v[18:21], v[184:187], v[216:219], v[18:21]
	v_mfma_f32_16x16x32_bf16 v[14:17], v[192:195], v[208:211], v[14:17]
	v_mfma_f32_16x16x32_bf16 v[10:13], v[192:195], v[216:219], v[10:13]
	v_mfma_f32_16x16x32_bf16 v[6:9], v[200:203], v[208:211], v[6:9]
	v_mfma_f32_16x16x32_bf16 v[2:5], v[200:203], v[216:219], v[2:5]
	s_add_i32 s1, s1, 2
	s_addk_i32 s2, 0x100
	s_cmp_lt_u32 s1, 28
	s_barrier
	s_cbranch_scc1 .LBB0_342
	v_readfirstlane_b32 s1, v145
	s_mov_b32 m0, s1
	s_mov_b32 s2, 0x80f80
	v_readfirstlane_b32 s1, v144
	ds_read_b128 v[138:141], v155
	ds_read_b128 v[148:151], v155 offset:1024
	ds_read_b128 v[156:159], v155 offset:2048
	ds_read_b128 v[152:155], v155 offset:3072
	ds_read_b128 v[160:163], v133
	ds_read_b128 v[164:167], v133 offset:1024
	ds_read_b128 v[168:171], v132
	ds_read_b128 v[172:175], v132 offset:1024
	ds_read_b128 v[176:179], v131
	ds_read_b128 v[180:183], v131 offset:1024
	ds_read_b128 v[184:187], v130
	ds_read_b128 v[188:191], v130 offset:1024
	buffer_load_dwordx4 v136, s[88:91], s2 offen lds
	s_mov_b32 m0, s1
	s_nop 0
	buffer_load_dwordx4 v135, s[88:91], s2 offen lds
	s_barrier
	s_waitcnt lgkmcnt(0)
	v_mfma_f32_16x16x32_bf16 v[126:129], v[160:163], v[138:141], v[126:129]
	v_mfma_f32_16x16x32_bf16 v[118:121], v[168:171], v[138:141], v[118:121]
	v_mfma_f32_16x16x32_bf16 v[110:113], v[176:179], v[138:141], v[110:113]
	v_mfma_f32_16x16x32_bf16 v[102:105], v[184:187], v[138:141], v[102:105]
	v_mfma_f32_16x16x32_bf16 v[126:129], v[164:167], v[148:151], v[126:129]
	v_mfma_f32_16x16x32_bf16 v[122:125], v[160:163], v[156:159], v[122:125]
	v_mfma_f32_16x16x32_bf16 v[118:121], v[172:175], v[148:151], v[118:121]
	v_mfma_f32_16x16x32_bf16 v[114:117], v[168:171], v[156:159], v[114:117]
	v_mfma_f32_16x16x32_bf16 v[110:113], v[180:183], v[148:151], v[110:113]
	v_mfma_f32_16x16x32_bf16 v[106:109], v[176:179], v[156:159], v[106:109]
	v_mfma_f32_16x16x32_bf16 v[102:105], v[188:191], v[148:151], v[102:105]
	v_mfma_f32_16x16x32_bf16 v[98:101], v[184:187], v[156:159], v[98:101]
	v_mfma_f32_16x16x32_bf16 v[142:145], v[164:167], v[152:155], v[122:125]
	v_mfma_f32_16x16x32_bf16 v[192:195], v[172:175], v[152:155], v[114:117]
	v_mfma_f32_16x16x32_bf16 v[196:199], v[180:183], v[152:155], v[106:109]
	v_mfma_f32_16x16x32_bf16 v[200:203], v[188:191], v[152:155], v[98:101]
	s_barrier
	s_nop 1
	ds_read_b128 v[98:101], v147
	ds_read_b128 v[106:109], v147 offset:1024
	ds_read_b128 v[114:117], v147 offset:2048
	ds_read_b128 v[122:125], v147 offset:3072
	s_barrier
	s_waitcnt lgkmcnt(0)
	v_mfma_f32_16x16x32_bf16 v[94:97], v[160:163], v[98:101], v[94:97]
	v_mfma_f32_16x16x32_bf16 v[90:93], v[160:163], v[114:117], v[90:93]
	v_mfma_f32_16x16x32_bf16 v[86:89], v[168:171], v[98:101], v[86:89]
	v_mfma_f32_16x16x32_bf16 v[82:85], v[168:171], v[114:117], v[82:85]
	v_mfma_f32_16x16x32_bf16 v[78:81], v[176:179], v[98:101], v[78:81]
	v_mfma_f32_16x16x32_bf16 v[74:77], v[176:179], v[114:117], v[74:77]
	v_mfma_f32_16x16x32_bf16 v[70:73], v[184:187], v[98:101], v[70:73]
	v_mfma_f32_16x16x32_bf16 v[66:69], v[184:187], v[114:117], v[66:69]
	v_mfma_f32_16x16x32_bf16 v[94:97], v[164:167], v[106:109], v[94:97]
	v_mfma_f32_16x16x32_bf16 v[90:93], v[164:167], v[122:125], v[90:93]
	v_mfma_f32_16x16x32_bf16 v[86:89], v[172:175], v[106:109], v[86:89]
	v_mfma_f32_16x16x32_bf16 v[82:85], v[172:175], v[122:125], v[82:85]
	v_mfma_f32_16x16x32_bf16 v[78:81], v[180:183], v[106:109], v[78:81]
	v_mfma_f32_16x16x32_bf16 v[74:77], v[180:183], v[122:125], v[74:77]
	v_mfma_f32_16x16x32_bf16 v[70:73], v[188:191], v[106:109], v[70:73]
	v_mfma_f32_16x16x32_bf16 v[66:69], v[188:191], v[122:125], v[66:69]
	s_barrier
	ds_read_b128 v[160:163], v133 offset:16384
	ds_read_b128 v[164:167], v133 offset:17408
	ds_read_b128 v[168:171], v132 offset:16384
	ds_read_b128 v[172:175], v132 offset:17408
	ds_read_b128 v[176:179], v131 offset:16384
	ds_read_b128 v[180:183], v131 offset:17408
	ds_read_b128 v[184:187], v130 offset:16384
	ds_read_b128 v[188:191], v130 offset:17408
	s_waitcnt vmcnt(4)
	s_barrier
; #define WAIT_V(n) asm volatile("s_waitcnt vmcnt(" #n ")" ::: "memory")
; #define WAIT_L(n) asm volatile("s_waitcnt lgkmcnt(" #n ")" ::: "memory")
; #define BAR __builtin_amdgcn_s_barrier()
; __device__ __forceinline__ void mainloop_8phase(const u16* __restrict__ A, const u16* __restrict__ Bt, int K,
;                                                 f32x4 (&acc)[2][2][4][2], int wid_s, int ld) {
;     ...
;     LDA(At, 0, 1); WAIT_V(4); BAR; WAIT_L(0); MMA(1, 0, At, B0); MMA(1, 1, At, B1); BAR; }
;   { LDB(B0, 1, 0); LDA(At, 1, 0); WAIT_V(2); BAR; WAIT_L(0); MMA(0, 0, At, B0); BAR;
	s_waitcnt lgkmcnt(0)
	v_mfma_f32_16x16x32_bf16 v[62:65], v[160:163], v[138:141], v[62:65]
	v_mfma_f32_16x16x32_bf16 v[58:61], v[160:163], v[156:159], v[58:61]
	v_mfma_f32_16x16x32_bf16 v[54:57], v[168:171], v[138:141], v[54:57]
	v_mfma_f32_16x16x32_bf16 v[50:53], v[168:171], v[156:159], v[50:53]
	v_mfma_f32_16x16x32_bf16 v[46:49], v[176:179], v[138:141], v[46:49]
	v_mfma_f32_16x16x32_bf16 v[42:45], v[176:179], v[156:159], v[42:45]
	v_mfma_f32_16x16x32_bf16 v[38:41], v[184:187], v[138:141], v[38:41]
	v_mfma_f32_16x16x32_bf16 v[34:37], v[184:187], v[156:159], v[34:37]
	v_mfma_f32_16x16x32_bf16 v[204:207], v[164:167], v[148:151], v[62:65]
	v_mfma_f32_16x16x32_bf16 v[208:211], v[164:167], v[152:155], v[58:61]
	v_mfma_f32_16x16x32_bf16 v[212:215], v[172:175], v[148:151], v[54:57]
	v_mfma_f32_16x16x32_bf16 v[216:219], v[172:175], v[152:155], v[50:53]
	v_mfma_f32_16x16x32_bf16 v[220:223], v[180:183], v[148:151], v[46:49]
	v_mfma_f32_16x16x32_bf16 v[224:227], v[180:183], v[152:155], v[42:45]
	v_mfma_f32_16x16x32_bf16 v[138:141], v[188:191], v[148:151], v[38:41]
	v_mfma_f32_16x16x32_bf16 v[146:149], v[188:191], v[152:155], v[34:37]
	v_mfma_f32_16x16x32_bf16 v[30:33], v[160:163], v[98:101], v[30:33]
	v_mfma_f32_16x16x32_bf16 v[22:25], v[168:171], v[98:101], v[22:25]
	v_mfma_f32_16x16x32_bf16 v[14:17], v[176:179], v[98:101], v[14:17]
	v_mfma_f32_16x16x32_bf16 v[6:9], v[184:187], v[98:101], v[6:9]
	v_mfma_f32_16x16x32_bf16 v[30:33], v[164:167], v[106:109], v[30:33]
	v_mfma_f32_16x16x32_bf16 v[26:29], v[160:163], v[114:117], v[26:29]
	v_mfma_f32_16x16x32_bf16 v[22:25], v[172:175], v[106:109], v[22:25]
	v_mfma_f32_16x16x32_bf16 v[18:21], v[168:171], v[114:117], v[18:21]
	v_mfma_f32_16x16x32_bf16 v[14:17], v[180:183], v[106:109], v[14:17]
	v_mfma_f32_16x16x32_bf16 v[10:13], v[176:179], v[114:117], v[10:13]
	v_mfma_f32_16x16x32_bf16 v[6:9], v[188:191], v[106:109], v[6:9]
	v_mfma_f32_16x16x32_bf16 v[2:5], v[184:187], v[114:117], v[2:5]
	v_mfma_f32_16x16x32_bf16 v[150:153], v[164:167], v[122:125], v[26:29]
	v_mfma_f32_16x16x32_bf16 v[154:157], v[172:175], v[122:125], v[18:21]
	v_mfma_f32_16x16x32_bf16 v[158:161], v[180:183], v[122:125], v[10:13]
	v_mfma_f32_16x16x32_bf16 v[162:165], v[188:191], v[122:125], v[2:5]
	s_barrier
	s_nop 1
	ds_read_b128 v[2:5], v137
	ds_read_b128 v[166:169], v137 offset:1024
	ds_read_b128 v[170:173], v137 offset:2048
	ds_read_b128 v[174:177], v137 offset:3072
	ds_read_b128 v[10:13], v133 offset:32768
	ds_read_b128 v[18:21], v133 offset:33792
	ds_read_b128 v[26:29], v132 offset:32768
	ds_read_b128 v[38:41], v132 offset:33792
	ds_read_b128 v[46:49], v131 offset:32768
	ds_read_b128 v[178:181], v131 offset:33792
	ds_read_b128 v[182:185], v130 offset:32768
	ds_read_b128 v[186:189], v130 offset:33792
	s_waitcnt vmcnt(2)
	s_barrier
	s_waitcnt lgkmcnt(0)
	v_mfma_f32_16x16x32_bf16 v[34:37], v[10:13], v[2:5], v[126:129]
	v_mfma_f32_16x16x32_bf16 v[122:125], v[18:21], v[166:169], v[34:37]
	v_mfma_f32_16x16x32_bf16 v[34:37], v[10:13], v[170:173], v[142:145]
	v_mfma_f32_16x16x32_bf16 v[58:61], v[18:21], v[174:177], v[34:37]
	v_mfma_f32_16x16x32_bf16 v[34:37], v[26:29], v[2:5], v[118:121]
	v_mfma_f32_16x16x32_bf16 v[114:117], v[38:41], v[166:169], v[34:37]
	v_mfma_f32_16x16x32_bf16 v[34:37], v[26:29], v[170:173], v[192:195]
	v_mfma_f32_16x16x32_bf16 v[50:53], v[38:41], v[174:177], v[34:37]
	v_mfma_f32_16x16x32_bf16 v[34:37], v[46:49], v[2:5], v[110:113]
	v_mfma_f32_16x16x32_bf16 v[106:109], v[178:181], v[166:169], v[34:37]
	v_mfma_f32_16x16x32_bf16 v[34:37], v[46:49], v[170:173], v[196:199]
	v_mfma_f32_16x16x32_bf16 v[42:45], v[178:181], v[174:177], v[34:37]
	v_mfma_f32_16x16x32_bf16 v[34:37], v[182:185], v[2:5], v[102:105]
	v_mfma_f32_16x16x32_bf16 v[98:101], v[186:189], v[166:169], v[34:37]
	v_mfma_f32_16x16x32_bf16 v[34:37], v[182:185], v[170:173], v[200:203]
	v_mfma_f32_16x16x32_bf16 v[34:37], v[186:189], v[174:177], v[34:37]
	s_barrier
; #define WAIT_V(n) asm volatile("s_waitcnt vmcnt(" #n ")" ::: "memory")
; #define WAIT_L(n) asm volatile("s_waitcnt lgkmcnt(" #n ")" ::: "memory")
; #define BAR __builtin_amdgcn_s_barrier()
; __device__ __forceinline__ void mainloop_8phase(const u16* __restrict__ A, const u16* __restrict__ Bt, int K,
;                                                 f32x4 (&acc)[2][2][4][2], int wid_s, int ld) {
;     ...
;     LDB(B1, 1, 1); WAIT_V(0); BAR; WAIT_L(0); MMA(0, 1, At, B1); BAR;
;     LDA(At, 1, 1); BAR; WAIT_L(0); MMA(1, 0, At, B0); MMA(1, 1, At, B1); BAR; }
;   if (wr == 0) BAR;
	ds_read_b128 v[142:145], v134
	ds_read_b128 v[190:193], v134 offset:1024
	ds_read_b128 v[194:197], v134 offset:2048
	ds_read_b128 v[134:137], v134 offset:3072
	s_waitcnt vmcnt(0)
	s_barrier
	s_waitcnt lgkmcnt(0)
	v_mfma_f32_16x16x32_bf16 v[54:57], v[10:13], v[142:145], v[94:97]
	v_mfma_f32_16x16x32_bf16 v[10:13], v[10:13], v[194:197], v[90:93]
	v_mfma_f32_16x16x32_bf16 v[62:65], v[18:21], v[134:137], v[10:13]
	v_mfma_f32_16x16x32_bf16 v[10:13], v[26:29], v[142:145], v[86:89]
	v_mfma_f32_16x16x32_bf16 v[118:121], v[38:41], v[190:193], v[10:13]
	v_mfma_f32_16x16x32_bf16 v[10:13], v[26:29], v[194:197], v[82:85]
	v_mfma_f32_16x16x32_bf16 v[126:129], v[18:21], v[190:193], v[54:57]
	v_mfma_f32_16x16x32_bf16 v[54:57], v[38:41], v[134:137], v[10:13]
	v_mfma_f32_16x16x32_bf16 v[10:13], v[46:49], v[142:145], v[78:81]
	v_mfma_f32_16x16x32_bf16 v[110:113], v[178:181], v[190:193], v[10:13]
	v_mfma_f32_16x16x32_bf16 v[10:13], v[46:49], v[194:197], v[74:77]
	v_mfma_f32_16x16x32_bf16 v[46:49], v[178:181], v[134:137], v[10:13]
	v_mfma_f32_16x16x32_bf16 v[10:13], v[182:185], v[142:145], v[70:73]
	v_mfma_f32_16x16x32_bf16 v[102:105], v[186:189], v[190:193], v[10:13]
	v_mfma_f32_16x16x32_bf16 v[10:13], v[182:185], v[194:197], v[66:69]
	v_mfma_f32_16x16x32_bf16 v[38:41], v[186:189], v[134:137], v[10:13]
	s_barrier
	ds_read_b128 v[66:69], v133 offset:49152
	ds_read_b128 v[78:81], v133 offset:50176
	ds_read_b128 v[178:181], v132 offset:49152
	ds_read_b128 v[182:185], v132 offset:50176
	ds_read_b128 v[186:189], v131 offset:49152
	ds_read_b128 v[198:201], v131 offset:50176
	ds_read_b128 v[228:231], v130 offset:49152
	ds_read_b128 v[130:133], v130 offset:50176
	s_barrier
	s_waitcnt lgkmcnt(0)
	v_mfma_f32_16x16x32_bf16 v[10:13], v[66:69], v[2:5], v[204:207]
	v_mfma_f32_16x16x32_bf16 v[90:93], v[78:81], v[166:169], v[10:13]
	v_mfma_f32_16x16x32_bf16 v[10:13], v[66:69], v[170:173], v[208:211]
	v_mfma_f32_16x16x32_bf16 v[26:29], v[78:81], v[174:177], v[10:13]
	v_mfma_f32_16x16x32_bf16 v[10:13], v[178:181], v[2:5], v[212:215]
	v_mfma_f32_16x16x32_bf16 v[82:85], v[182:185], v[166:169], v[10:13]
	v_mfma_f32_16x16x32_bf16 v[10:13], v[178:181], v[170:173], v[216:219]
	v_mfma_f32_16x16x32_bf16 v[18:21], v[182:185], v[174:177], v[10:13]
	v_mfma_f32_16x16x32_bf16 v[10:13], v[186:189], v[2:5], v[220:223]
	v_mfma_f32_16x16x32_bf16 v[2:5], v[228:231], v[2:5], v[138:141]
	v_mfma_f32_16x16x32_bf16 v[74:77], v[198:201], v[166:169], v[10:13]
	v_mfma_f32_16x16x32_bf16 v[10:13], v[186:189], v[170:173], v[224:227]
	v_mfma_f32_16x16x32_bf16 v[70:73], v[130:133], v[166:169], v[2:5]
	v_mfma_f32_16x16x32_bf16 v[2:5], v[228:231], v[170:173], v[146:149]
	v_mfma_f32_16x16x32_bf16 v[10:13], v[198:201], v[174:177], v[10:13]
	v_mfma_f32_16x16x32_bf16 v[2:5], v[130:133], v[174:177], v[2:5]
	v_mfma_f32_16x16x32_bf16 v[30:33], v[66:69], v[142:145], v[30:33]
	v_mfma_f32_16x16x32_bf16 v[94:97], v[78:81], v[190:193], v[30:33]
	v_mfma_f32_16x16x32_bf16 v[30:33], v[66:69], v[194:197], v[150:153]
	v_mfma_f32_16x16x32_bf16 v[22:25], v[178:181], v[142:145], v[22:25]
	v_mfma_f32_16x16x32_bf16 v[14:17], v[186:189], v[142:145], v[14:17]
	v_mfma_f32_16x16x32_bf16 v[6:9], v[228:231], v[142:145], v[6:9]
	v_mfma_f32_16x16x32_bf16 v[30:33], v[78:81], v[134:137], v[30:33]
	v_mfma_f32_16x16x32_bf16 v[86:89], v[182:185], v[190:193], v[22:25]
	v_mfma_f32_16x16x32_bf16 v[22:25], v[178:181], v[194:197], v[154:157]
	v_mfma_f32_16x16x32_bf16 v[78:81], v[198:201], v[190:193], v[14:17]
	v_mfma_f32_16x16x32_bf16 v[14:17], v[186:189], v[194:197], v[158:161]
	v_mfma_f32_16x16x32_bf16 v[66:69], v[130:133], v[190:193], v[6:9]
	v_mfma_f32_16x16x32_bf16 v[6:9], v[228:231], v[194:197], v[162:165]
	v_mfma_f32_16x16x32_bf16 v[22:25], v[182:185], v[134:137], v[22:25]
	v_mfma_f32_16x16x32_bf16 v[14:17], v[198:201], v[134:137], v[14:17]
	v_mfma_f32_16x16x32_bf16 v[6:9], v[130:133], v[134:137], v[6:9]
	s_movk_i32 s1, 0x100
	v_cmp_gt_u32_e32 vcc, s1, v0
	s_barrier
	s_and_saveexec_b64 s[2:3], vcc
	s_cbranch_execz .LBB0_345
	s_barrier

; #define WAIT_V(n) asm volatile("s_waitcnt vmcnt(" #n ")" ::: "memory")
; #define WAIT_L(n) asm volatile("s_waitcnt lgkmcnt(" #n ")" ::: "memory")
; #define BAR __builtin_amdgcn_s_barrier()
; #define SCHED __builtin_amdgcn_sched_barrier(0)
; __device__ __forceinline__ void mainloop_8phase(const u16* __restrict__ A, const u16* __restrict__ Bt, int K,
;                                                 f32x4 (&acc)[2][2][4][2], int wid_s, int ld) {
;     ...
;     LDB(B0, 0, 0); SCHED; LDA(At, 0, 0); STAGE(SA(1, 1), A, brow + G_HALF, t + 1);
;     WAIT_L(8); BAR; WAIT_L(0); MMA(0, 0, At, B0); BAR; SCHED;
;     LDB(B1, 0, 1); STAGE(SB(0, 0), Bt, bcol, t + 2);
;     BAR; WAIT_L(0); MMA(0, 1, At, B1); BAR;
;     LDA(At, 0, 1); STAGE(SA(0, 0), A, brow, t + 2);
;     BAR; WAIT_L(0); MMA(1, 0, At, B0); BAR; SCHED;
;     STAGE(SB(0, 1), Bt, bcol + G_HALF, t + 2);
;     WAIT_V(6); BAR; MMA(1, 1, At, B1); BAR;
.LBB0_565:
	ds_read_b128 v[158:161], v156
	ds_read_b128 v[162:165], v156 offset:1024
	ds_read_b128 v[166:169], v156 offset:2048
	ds_read_b128 v[170:173], v156 offset:3072
	s_add_i32 s15, s27, s3
	s_add_i32 s6, s15, 0x80
	s_add_i32 m0, s100, 0xc000
	ds_read_b128 v[174:177], v134
	ds_read_b128 v[178:181], v134 offset:1024
	ds_read_b128 v[182:185], v133
	ds_read_b128 v[186:189], v133 offset:1024
	ds_read_b128 v[190:193], v132
	ds_read_b128 v[194:197], v132 offset:1024
	ds_read_b128 v[198:201], v131
	buffer_load_dwordx4 v137, s[76:79], s6 offen lds
	s_add_i32 m0, s100, 0xe000
	ds_read_b128 v[202:205], v131 offset:1024
	buffer_load_dwordx4 v138, s[76:79], s6 offen lds
	s_waitcnt lgkmcnt(8)
	s_barrier
	s_waitcnt lgkmcnt(1)
	v_mfma_f32_16x16x32_bf16 v[126:129], v[174:177], v[158:161], v[126:129]
	v_mfma_f32_16x16x32_bf16 v[122:125], v[174:177], v[166:169], v[122:125]
	v_mfma_f32_16x16x32_bf16 v[118:121], v[182:185], v[158:161], v[118:121]
	v_mfma_f32_16x16x32_bf16 v[114:117], v[182:185], v[166:169], v[114:117]
	v_mfma_f32_16x16x32_bf16 v[110:113], v[190:193], v[158:161], v[110:113]
	v_mfma_f32_16x16x32_bf16 v[106:109], v[190:193], v[166:169], v[106:109]
	v_mfma_f32_16x16x32_bf16 v[102:105], v[198:201], v[158:161], v[102:105]
	v_mfma_f32_16x16x32_bf16 v[98:101], v[198:201], v[166:169], v[98:101]
	v_mfma_f32_16x16x32_bf16 v[126:129], v[178:181], v[162:165], v[126:129]
	v_mfma_f32_16x16x32_bf16 v[122:125], v[178:181], v[170:173], v[122:125]
	v_mfma_f32_16x16x32_bf16 v[118:121], v[186:189], v[162:165], v[118:121]
	v_mfma_f32_16x16x32_bf16 v[114:117], v[186:189], v[170:173], v[114:117]
	v_mfma_f32_16x16x32_bf16 v[110:113], v[194:197], v[162:165], v[110:113]
	v_mfma_f32_16x16x32_bf16 v[106:109], v[194:197], v[170:173], v[106:109]
	s_waitcnt lgkmcnt(0)
	v_mfma_f32_16x16x32_bf16 v[102:105], v[202:205], v[162:165], v[102:105]
	v_mfma_f32_16x16x32_bf16 v[98:101], v[202:205], v[170:173], v[98:101]
	s_barrier
	s_add_i32 s14, s3, 0x100
	s_mov_b32 s6, s78
	s_mov_b32 s7, s79
	s_add_i32 m0, s100, 0x10000
	ds_read_b128 v[206:209], v148
	ds_read_b128 v[210:213], v148 offset:1024
	ds_read_b128 v[214:217], v148 offset:2048
	ds_read_b128 v[218:221], v148 offset:3072
	buffer_load_dwordx4 v137, s[4:7], s14 offen lds
	s_add_i32 m0, s100, 0x12000
	s_add_i32 s2, s2, 2
	buffer_load_dwordx4 v138, s[4:7], s14 offen lds
	s_barrier
	s_waitcnt lgkmcnt(0)
	v_mfma_f32_16x16x32_bf16 v[94:97], v[174:177], v[206:209], v[94:97]
	v_mfma_f32_16x16x32_bf16 v[90:93], v[174:177], v[214:217], v[90:93]
	v_mfma_f32_16x16x32_bf16 v[86:89], v[182:185], v[206:209], v[86:89]
	v_mfma_f32_16x16x32_bf16 v[82:85], v[182:185], v[214:217], v[82:85]
	v_mfma_f32_16x16x32_bf16 v[78:81], v[190:193], v[206:209], v[78:81]
	v_mfma_f32_16x16x32_bf16 v[74:77], v[190:193], v[214:217], v[74:77]
	v_mfma_f32_16x16x32_bf16 v[70:73], v[198:201], v[206:209], v[70:73]
	v_mfma_f32_16x16x32_bf16 v[66:69], v[198:201], v[214:217], v[66:69]
	v_mfma_f32_16x16x32_bf16 v[94:97], v[178:181], v[210:213], v[94:97]
	v_mfma_f32_16x16x32_bf16 v[90:93], v[178:181], v[218:221], v[90:93]
	v_mfma_f32_16x16x32_bf16 v[86:89], v[186:189], v[210:213], v[86:89]
	v_mfma_f32_16x16x32_bf16 v[82:85], v[186:189], v[218:221], v[82:85]
	v_mfma_f32_16x16x32_bf16 v[78:81], v[194:197], v[210:213], v[78:81]
	v_mfma_f32_16x16x32_bf16 v[74:77], v[194:197], v[218:221], v[74:77]
	v_mfma_f32_16x16x32_bf16 v[70:73], v[202:205], v[210:213], v[70:73]
	v_mfma_f32_16x16x32_bf16 v[66:69], v[202:205], v[218:221], v[66:69]
	s_mov_b32 m0, s100
	s_barrier
	ds_read_b128 v[174:177], v134 offset:16384
	ds_read_b128 v[178:181], v134 offset:17408
	ds_read_b128 v[182:185], v133 offset:16384
	ds_read_b128 v[186:189], v133 offset:17408
	ds_read_b128 v[190:193], v132 offset:16384
	ds_read_b128 v[194:197], v132 offset:17408
	ds_read_b128 v[198:201], v131 offset:16384
	buffer_load_dwordx4 v137, s[76:79], s14 offen lds
	s_add_i32 m0, s100, 0x2000
	ds_read_b128 v[202:205], v131 offset:17408
	buffer_load_dwordx4 v138, s[76:79], s14 offen lds
	s_barrier
	s_waitcnt lgkmcnt(1)
	v_mfma_f32_16x16x32_bf16 v[62:65], v[174:177], v[158:161], v[62:65]
	v_mfma_f32_16x16x32_bf16 v[58:61], v[174:177], v[166:169], v[58:61]
	v_mfma_f32_16x16x32_bf16 v[54:57], v[182:185], v[158:161], v[54:57]
	v_mfma_f32_16x16x32_bf16 v[50:53], v[182:185], v[166:169], v[50:53]
	v_mfma_f32_16x16x32_bf16 v[46:49], v[190:193], v[158:161], v[46:49]
	v_mfma_f32_16x16x32_bf16 v[42:45], v[190:193], v[166:169], v[42:45]
	v_mfma_f32_16x16x32_bf16 v[38:41], v[198:201], v[158:161], v[38:41]
	v_mfma_f32_16x16x32_bf16 v[34:37], v[198:201], v[166:169], v[34:37]
	v_mfma_f32_16x16x32_bf16 v[62:65], v[178:181], v[162:165], v[62:65]
	v_mfma_f32_16x16x32_bf16 v[58:61], v[178:181], v[170:173], v[58:61]
	v_mfma_f32_16x16x32_bf16 v[54:57], v[186:189], v[162:165], v[54:57]
	v_mfma_f32_16x16x32_bf16 v[50:53], v[186:189], v[170:173], v[50:53]
	v_mfma_f32_16x16x32_bf16 v[46:49], v[194:197], v[162:165], v[46:49]
	v_mfma_f32_16x16x32_bf16 v[42:45], v[194:197], v[170:173], v[42:45]
	s_waitcnt lgkmcnt(0)
	v_mfma_f32_16x16x32_bf16 v[38:41], v[202:205], v[162:165], v[38:41]
	v_mfma_f32_16x16x32_bf16 v[34:37], v[202:205], v[170:173], v[34:37]
	s_barrier
	s_add_i32 m0, s100, 0x14000
	s_add_i32 s34, s15, 0x100
	buffer_load_dwordx4 v137, s[4:7], s34 offen lds
	s_add_i32 m0, s100, 0x16000
	s_nop 0
	buffer_load_dwordx4 v138, s[4:7], s34 offen lds
	s_waitcnt vmcnt(6)
	s_barrier
; #define WAIT_V(n) asm volatile("s_waitcnt vmcnt(" #n ")" ::: "memory")
; #define WAIT_L(n) asm volatile("s_waitcnt lgkmcnt(" #n ")" ::: "memory")
; #define BAR __builtin_amdgcn_s_barrier()
; #define SCHED __builtin_amdgcn_sched_barrier(0)
; __device__ __forceinline__ void mainloop_8phase(const u16* __restrict__ A, const u16* __restrict__ Bt, int K,
;                                                 f32x4 (&acc)[2][2][4][2], int wid_s, int ld) {
;     ...
;     WAIT_V(6); BAR; MMA(1, 1, At, B1); BAR;
;     LDB(B0, 1, 0); SCHED; LDA(At, 1, 0); STAGE(SA(0, 1), A, brow + G_HALF, t + 2);
;     WAIT_L(8); BAR; WAIT_L(0); MMA(0, 0, At, B0); BAR; SCHED;
;     LDB(B1, 1, 1); STAGE(SB(1, 0), Bt, bcol, t + 3);
;     BAR; WAIT_L(0); MMA(0, 1, At, B1); BAR;
;     LDA(At, 1, 1); STAGE(SA(1, 0), A, brow, t + 3);
;     BAR; WAIT_L(0); MMA(1, 0, At, B0); BAR; SCHED;
	v_mfma_f32_16x16x32_bf16 v[30:33], v[174:177], v[206:209], v[30:33]
	v_mfma_f32_16x16x32_bf16 v[26:29], v[174:177], v[214:217], v[26:29]
	v_mfma_f32_16x16x32_bf16 v[22:25], v[182:185], v[206:209], v[22:25]
	v_mfma_f32_16x16x32_bf16 v[18:21], v[182:185], v[214:217], v[18:21]
	v_mfma_f32_16x16x32_bf16 v[14:17], v[190:193], v[206:209], v[14:17]
	v_mfma_f32_16x16x32_bf16 v[10:13], v[190:193], v[214:217], v[10:13]
	v_mfma_f32_16x16x32_bf16 v[6:9], v[198:201], v[206:209], v[6:9]
	v_mfma_f32_16x16x32_bf16 v[2:5], v[198:201], v[214:217], v[2:5]
	v_mfma_f32_16x16x32_bf16 v[30:33], v[178:181], v[210:213], v[30:33]
	v_mfma_f32_16x16x32_bf16 v[26:29], v[178:181], v[218:221], v[26:29]
	v_mfma_f32_16x16x32_bf16 v[22:25], v[186:189], v[210:213], v[22:25]
	v_mfma_f32_16x16x32_bf16 v[18:21], v[186:189], v[218:221], v[18:21]
	v_mfma_f32_16x16x32_bf16 v[14:17], v[194:197], v[210:213], v[14:17]
	v_mfma_f32_16x16x32_bf16 v[10:13], v[194:197], v[218:221], v[10:13]
	v_mfma_f32_16x16x32_bf16 v[6:9], v[202:205], v[210:213], v[6:9]
	v_mfma_f32_16x16x32_bf16 v[2:5], v[202:205], v[218:221], v[2:5]
	s_barrier
	ds_read_b128 v[158:161], v136
	ds_read_b128 v[162:165], v136 offset:1024
	ds_read_b128 v[166:169], v136 offset:2048
	ds_read_b128 v[170:173], v136 offset:3072
	s_add_i32 m0, s100, 0x4000
	ds_read_b128 v[174:177], v134 offset:32768
	ds_read_b128 v[178:181], v134 offset:33792
	ds_read_b128 v[182:185], v133 offset:32768
	ds_read_b128 v[186:189], v133 offset:33792
	ds_read_b128 v[190:193], v132 offset:32768
	ds_read_b128 v[194:197], v132 offset:33792
	ds_read_b128 v[198:201], v131 offset:32768
	buffer_load_dwordx4 v137, s[76:79], s34 offen lds
	s_add_i32 m0, s100, 0x6000
	ds_read_b128 v[202:205], v131 offset:33792
	buffer_load_dwordx4 v138, s[76:79], s34 offen lds
	s_waitcnt lgkmcnt(8)
	s_barrier
	s_waitcnt lgkmcnt(1)
	v_mfma_f32_16x16x32_bf16 v[126:129], v[174:177], v[158:161], v[126:129]
	v_mfma_f32_16x16x32_bf16 v[122:125], v[174:177], v[166:169], v[122:125]
	v_mfma_f32_16x16x32_bf16 v[118:121], v[182:185], v[158:161], v[118:121]
	v_mfma_f32_16x16x32_bf16 v[114:117], v[182:185], v[166:169], v[114:117]
	v_mfma_f32_16x16x32_bf16 v[110:113], v[190:193], v[158:161], v[110:113]
	v_mfma_f32_16x16x32_bf16 v[106:109], v[190:193], v[166:169], v[106:109]
	v_mfma_f32_16x16x32_bf16 v[102:105], v[198:201], v[158:161], v[102:105]
	v_mfma_f32_16x16x32_bf16 v[98:101], v[198:201], v[166:169], v[98:101]
	v_mfma_f32_16x16x32_bf16 v[126:129], v[178:181], v[162:165], v[126:129]
	v_mfma_f32_16x16x32_bf16 v[122:125], v[178:181], v[170:173], v[122:125]
	v_mfma_f32_16x16x32_bf16 v[118:121], v[186:189], v[162:165], v[118:121]
	v_mfma_f32_16x16x32_bf16 v[114:117], v[186:189], v[170:173], v[114:117]
	v_mfma_f32_16x16x32_bf16 v[110:113], v[194:197], v[162:165], v[110:113]
	v_mfma_f32_16x16x32_bf16 v[106:109], v[194:197], v[170:173], v[106:109]
	s_waitcnt lgkmcnt(0)
	v_mfma_f32_16x16x32_bf16 v[102:105], v[202:205], v[162:165], v[102:105]
	v_mfma_f32_16x16x32_bf16 v[98:101], v[202:205], v[170:173], v[98:101]
	s_barrier
	s_addk_i32 s3, 0x180
	s_add_i32 m0, s100, 0x18000
	ds_read_b128 v[206:209], v135
	ds_read_b128 v[210:213], v135 offset:1024
	ds_read_b128 v[214:217], v135 offset:2048
	buffer_load_dwordx4 v137, s[4:7], s3 offen lds
	s_add_i32 m0, s100, 0x1a000
	ds_read_b128 v[218:221], v135 offset:3072
	buffer_load_dwordx4 v138, s[4:7], s3 offen lds
	s_barrier
	s_waitcnt lgkmcnt(1)
	v_mfma_f32_16x16x32_bf16 v[94:97], v[174:177], v[206:209], v[94:97]
	v_mfma_f32_16x16x32_bf16 v[90:93], v[174:177], v[214:217], v[90:93]
	v_mfma_f32_16x16x32_bf16 v[86:89], v[182:185], v[206:209], v[86:89]
	v_mfma_f32_16x16x32_bf16 v[82:85], v[182:185], v[214:217], v[82:85]
	v_mfma_f32_16x16x32_bf16 v[78:81], v[190:193], v[206:209], v[78:81]
	v_mfma_f32_16x16x32_bf16 v[74:77], v[190:193], v[214:217], v[74:77]
	v_mfma_f32_16x16x32_bf16 v[70:73], v[198:201], v[206:209], v[70:73]
	v_mfma_f32_16x16x32_bf16 v[66:69], v[198:201], v[214:217], v[66:69]
	v_mfma_f32_16x16x32_bf16 v[94:97], v[178:181], v[210:213], v[94:97]
	s_waitcnt lgkmcnt(0)
	v_mfma_f32_16x16x32_bf16 v[90:93], v[178:181], v[218:221], v[90:93]
	v_mfma_f32_16x16x32_bf16 v[86:89], v[186:189], v[210:213], v[86:89]
	v_mfma_f32_16x16x32_bf16 v[82:85], v[186:189], v[218:221], v[82:85]
	v_mfma_f32_16x16x32_bf16 v[78:81], v[194:197], v[210:213], v[78:81]
	v_mfma_f32_16x16x32_bf16 v[74:77], v[194:197], v[218:221], v[74:77]
	v_mfma_f32_16x16x32_bf16 v[70:73], v[202:205], v[210:213], v[70:73]
	v_mfma_f32_16x16x32_bf16 v[66:69], v[202:205], v[218:221], v[66:69]
	s_add_i32 m0, s100, 0x8000
	s_barrier
	ds_read_b128 v[174:177], v134 offset:49152
	ds_read_b128 v[178:181], v134 offset:50176
	ds_read_b128 v[182:185], v133 offset:49152
	ds_read_b128 v[186:189], v133 offset:50176
	ds_read_b128 v[190:193], v132 offset:49152
	ds_read_b128 v[194:197], v132 offset:50176
	ds_read_b128 v[198:201], v131 offset:49152
	buffer_load_dwordx4 v137, s[76:79], s3 offen lds
	s_add_i32 m0, s100, 0xa000
	ds_read_b128 v[202:205], v131 offset:50176
	buffer_load_dwordx4 v138, s[76:79], s3 offen lds
	s_barrier
	s_waitcnt lgkmcnt(1)
	v_mfma_f32_16x16x32_bf16 v[62:65], v[174:177], v[158:161], v[62:65]
	v_mfma_f32_16x16x32_bf16 v[58:61], v[174:177], v[166:169], v[58:61]
	v_mfma_f32_16x16x32_bf16 v[54:57], v[182:185], v[158:161], v[54:57]
	v_mfma_f32_16x16x32_bf16 v[50:53], v[182:185], v[166:169], v[50:53]
	v_mfma_f32_16x16x32_bf16 v[46:49], v[190:193], v[158:161], v[46:49]
	v_mfma_f32_16x16x32_bf16 v[42:45], v[190:193], v[166:169], v[42:45]
	v_mfma_f32_16x16x32_bf16 v[38:41], v[198:201], v[158:161], v[38:41]
	v_mfma_f32_16x16x32_bf16 v[34:37], v[198:201], v[166:169], v[34:37]
	v_mfma_f32_16x16x32_bf16 v[62:65], v[178:181], v[162:165], v[62:65]
	v_mfma_f32_16x16x32_bf16 v[58:61], v[178:181], v[170:173], v[58:61]
	v_mfma_f32_16x16x32_bf16 v[54:57], v[186:189], v[162:165], v[54:57]
	v_mfma_f32_16x16x32_bf16 v[50:53], v[186:189], v[170:173], v[50:53]
	v_mfma_f32_16x16x32_bf16 v[46:49], v[194:197], v[162:165], v[46:49]
	v_mfma_f32_16x16x32_bf16 v[42:45], v[194:197], v[170:173], v[42:45]
	s_waitcnt lgkmcnt(0)
	v_mfma_f32_16x16x32_bf16 v[38:41], v[202:205], v[162:165], v[38:41]
	v_mfma_f32_16x16x32_bf16 v[34:37], v[202:205], v[170:173], v[34:37]
	s_barrier
; #define WAIT_V(n) asm volatile("s_waitcnt vmcnt(" #n ")" ::: "memory")
; #define WAIT_L(n) asm volatile("s_waitcnt lgkmcnt(" #n ")" ::: "memory")
; #define BAR __builtin_amdgcn_s_barrier()
; __device__ __forceinline__ void mainloop_8phase(const u16* __restrict__ A, const u16* __restrict__ Bt, int K,
;                                                 f32x4 (&acc)[2][2][4][2], int wid_s, int ld) {
;     ...
;     STAGE(SB(1, 1), Bt, bcol + G_HALF, t + 3);
;     WAIT_V(6); BAR; MMA(1, 1, At, B1); BAR;
;   }
;   { LDB(B0, 0, 0); LDA(At, 0, 0); STAGE(SA(1, 1), A, brow + G_HALF, nt - 1);
;     BAR; WAIT_L(0); MMA(0, 0, At, B0); BAR;
;     LDB(B1, 0, 1); BAR; WAIT_L(0); MMA(0, 1, At, B1); BAR;
	s_addk_i32 s15, 0x180
	s_add_i32 m0, s100, 0x1c000
	s_nop 0
	buffer_load_dwordx4 v137, s[4:7], s15 offen lds
	s_add_i32 m0, s100, 0x1e000
	s_nop 0
	buffer_load_dwordx4 v138, s[4:7], s15 offen lds
	s_waitcnt vmcnt(6)
	s_barrier
	v_mfma_f32_16x16x32_bf16 v[30:33], v[174:177], v[206:209], v[30:33]
	v_mfma_f32_16x16x32_bf16 v[26:29], v[174:177], v[214:217], v[26:29]
	v_mfma_f32_16x16x32_bf16 v[22:25], v[182:185], v[206:209], v[22:25]
	v_mfma_f32_16x16x32_bf16 v[18:21], v[182:185], v[214:217], v[18:21]
	v_mfma_f32_16x16x32_bf16 v[14:17], v[190:193], v[206:209], v[14:17]
	v_mfma_f32_16x16x32_bf16 v[10:13], v[190:193], v[214:217], v[10:13]
	v_mfma_f32_16x16x32_bf16 v[6:9], v[198:201], v[206:209], v[6:9]
	v_mfma_f32_16x16x32_bf16 v[2:5], v[198:201], v[214:217], v[2:5]
	v_mfma_f32_16x16x32_bf16 v[30:33], v[178:181], v[210:213], v[30:33]
	v_mfma_f32_16x16x32_bf16 v[26:29], v[178:181], v[218:221], v[26:29]
	v_mfma_f32_16x16x32_bf16 v[22:25], v[186:189], v[210:213], v[22:25]
	v_mfma_f32_16x16x32_bf16 v[18:21], v[186:189], v[218:221], v[18:21]
	v_mfma_f32_16x16x32_bf16 v[14:17], v[194:197], v[210:213], v[14:17]
	v_mfma_f32_16x16x32_bf16 v[10:13], v[194:197], v[218:221], v[10:13]
	v_mfma_f32_16x16x32_bf16 v[6:9], v[202:205], v[210:213], v[6:9]
	v_mfma_f32_16x16x32_bf16 v[2:5], v[202:205], v[218:221], v[2:5]
	s_cmp_lt_u32 s2, s29
	s_mov_b32 s3, s14
	s_barrier
	s_cbranch_scc1 .LBB0_565
	v_readfirstlane_b32 s2, v146
	s_mov_b32 m0, s2
	v_readfirstlane_b32 s2, v145
	ds_read_b128 v[140:143], v156
	ds_read_b128 v[150:153], v156 offset:1024
	ds_read_b128 v[158:161], v156 offset:2048
	ds_read_b128 v[154:157], v156 offset:3072
	ds_read_b128 v[162:165], v134
	ds_read_b128 v[166:169], v134 offset:1024
	ds_read_b128 v[170:173], v133
	ds_read_b128 v[174:177], v133 offset:1024
	ds_read_b128 v[178:181], v132
	ds_read_b128 v[182:185], v132 offset:1024
	ds_read_b128 v[186:189], v131
	ds_read_b128 v[190:193], v131 offset:1024
	buffer_load_dwordx4 v137, s[76:79], s30 offen lds
	s_mov_b32 m0, s2
	s_nop 0
	buffer_load_dwordx4 v138, s[76:79], s30 offen lds
	s_barrier
	s_waitcnt lgkmcnt(0)
	v_mfma_f32_16x16x32_bf16 v[126:129], v[162:165], v[140:143], v[126:129]
	v_mfma_f32_16x16x32_bf16 v[118:121], v[170:173], v[140:143], v[118:121]
	v_mfma_f32_16x16x32_bf16 v[110:113], v[178:181], v[140:143], v[110:113]
	v_mfma_f32_16x16x32_bf16 v[102:105], v[186:189], v[140:143], v[102:105]
	v_mfma_f32_16x16x32_bf16 v[126:129], v[166:169], v[150:153], v[126:129]
	v_mfma_f32_16x16x32_bf16 v[122:125], v[162:165], v[158:161], v[122:125]
	v_mfma_f32_16x16x32_bf16 v[118:121], v[174:177], v[150:153], v[118:121]
	v_mfma_f32_16x16x32_bf16 v[114:117], v[170:173], v[158:161], v[114:117]
	v_mfma_f32_16x16x32_bf16 v[110:113], v[182:185], v[150:153], v[110:113]
	v_mfma_f32_16x16x32_bf16 v[106:109], v[178:181], v[158:161], v[106:109]
	v_mfma_f32_16x16x32_bf16 v[102:105], v[190:193], v[150:153], v[102:105]
	v_mfma_f32_16x16x32_bf16 v[98:101], v[186:189], v[158:161], v[98:101]
	v_mfma_f32_16x16x32_bf16 v[144:147], v[166:169], v[154:157], v[122:125]
	v_mfma_f32_16x16x32_bf16 v[194:197], v[174:177], v[154:157], v[114:117]
	v_mfma_f32_16x16x32_bf16 v[198:201], v[182:185], v[154:157], v[106:109]
	v_mfma_f32_16x16x32_bf16 v[202:205], v[190:193], v[154:157], v[98:101]
	s_barrier
	s_nop 1
	ds_read_b128 v[98:101], v148
	ds_read_b128 v[106:109], v148 offset:1024
	ds_read_b128 v[114:117], v148 offset:2048
	ds_read_b128 v[122:125], v148 offset:3072
	s_barrier
	s_waitcnt lgkmcnt(0)
	v_mfma_f32_16x16x32_bf16 v[94:97], v[162:165], v[98:101], v[94:97]
	v_mfma_f32_16x16x32_bf16 v[86:89], v[170:173], v[98:101], v[86:89]
	v_mfma_f32_16x16x32_bf16 v[78:81], v[178:181], v[98:101], v[78:81]
	v_mfma_f32_16x16x32_bf16 v[70:73], v[186:189], v[98:101], v[70:73]
	v_mfma_f32_16x16x32_bf16 v[94:97], v[166:169], v[106:109], v[94:97]
	v_mfma_f32_16x16x32_bf16 v[90:93], v[162:165], v[114:117], v[90:93]
	v_mfma_f32_16x16x32_bf16 v[86:89], v[174:177], v[106:109], v[86:89]
	v_mfma_f32_16x16x32_bf16 v[82:85], v[170:173], v[114:117], v[82:85]
	v_mfma_f32_16x16x32_bf16 v[78:81], v[182:185], v[106:109], v[78:81]
	v_mfma_f32_16x16x32_bf16 v[74:77], v[178:181], v[114:117], v[74:77]
	v_mfma_f32_16x16x32_bf16 v[70:73], v[190:193], v[106:109], v[70:73]
	v_mfma_f32_16x16x32_bf16 v[66:69], v[186:189], v[114:117], v[66:69]
	v_mfma_f32_16x16x32_bf16 v[162:165], v[166:169], v[122:125], v[90:93]
	v_mfma_f32_16x16x32_bf16 v[166:169], v[174:177], v[122:125], v[82:85]
	v_mfma_f32_16x16x32_bf16 v[170:173], v[182:185], v[122:125], v[74:77]
	v_mfma_f32_16x16x32_bf16 v[174:177], v[190:193], v[122:125], v[66:69]
	s_barrier
	s_nop 0
	ds_read_b128 v[66:69], v134 offset:16384
	ds_read_b128 v[74:77], v134 offset:17408
	ds_read_b128 v[82:85], v133 offset:16384
	ds_read_b128 v[90:93], v133 offset:17408
	ds_read_b128 v[178:181], v132 offset:16384
	ds_read_b128 v[182:185], v132 offset:17408
	ds_read_b128 v[186:189], v131 offset:16384
	ds_read_b128 v[190:193], v131 offset:17408
	s_waitcnt vmcnt(4)
	s_barrier
; #define WAIT_V(n) asm volatile("s_waitcnt vmcnt(" #n ")" ::: "memory")
; #define WAIT_L(n) asm volatile("s_waitcnt lgkmcnt(" #n ")" ::: "memory")
; #define BAR __builtin_amdgcn_s_barrier()
; __device__ __forceinline__ void mainloop_8phase(const u16* __restrict__ A, const u16* __restrict__ Bt, int K,
;                                                 f32x4 (&acc)[2][2][4][2], int wid_s, int ld) {
;     ...
;     LDA(At, 0, 1); WAIT_V(4); BAR; WAIT_L(0); MMA(1, 0, At, B0); MMA(1, 1, At, B1); BAR; }
;   { LDB(B0, 1, 0); LDA(At, 1, 0); WAIT_V(2); BAR; WAIT_L(0); MMA(0, 0, At, B0); BAR;
	s_waitcnt lgkmcnt(0)
	v_mfma_f32_16x16x32_bf16 v[62:65], v[66:69], v[140:143], v[62:65]
	v_mfma_f32_16x16x32_bf16 v[54:57], v[82:85], v[140:143], v[54:57]
	v_mfma_f32_16x16x32_bf16 v[46:49], v[178:181], v[140:143], v[46:49]
	v_mfma_f32_16x16x32_bf16 v[38:41], v[186:189], v[140:143], v[38:41]
	v_mfma_f32_16x16x32_bf16 v[62:65], v[74:77], v[150:153], v[62:65]
	v_mfma_f32_16x16x32_bf16 v[58:61], v[66:69], v[158:161], v[58:61]
	v_mfma_f32_16x16x32_bf16 v[54:57], v[90:93], v[150:153], v[54:57]
	v_mfma_f32_16x16x32_bf16 v[50:53], v[82:85], v[158:161], v[50:53]
	v_mfma_f32_16x16x32_bf16 v[46:49], v[182:185], v[150:153], v[46:49]
	v_mfma_f32_16x16x32_bf16 v[42:45], v[178:181], v[158:161], v[42:45]
	v_mfma_f32_16x16x32_bf16 v[38:41], v[190:193], v[150:153], v[38:41]
	v_mfma_f32_16x16x32_bf16 v[34:37], v[186:189], v[158:161], v[34:37]
	v_mfma_f32_16x16x32_bf16 v[206:209], v[74:77], v[154:157], v[58:61]
	v_mfma_f32_16x16x32_bf16 v[210:213], v[90:93], v[154:157], v[50:53]
	v_mfma_f32_16x16x32_bf16 v[214:217], v[182:185], v[154:157], v[42:45]
	v_mfma_f32_16x16x32_bf16 v[138:141], v[190:193], v[154:157], v[34:37]
	v_mfma_f32_16x16x32_bf16 v[30:33], v[66:69], v[98:101], v[30:33]
	v_mfma_f32_16x16x32_bf16 v[22:25], v[82:85], v[98:101], v[22:25]
	v_mfma_f32_16x16x32_bf16 v[14:17], v[178:181], v[98:101], v[14:17]
	v_mfma_f32_16x16x32_bf16 v[6:9], v[186:189], v[98:101], v[6:9]
	v_mfma_f32_16x16x32_bf16 v[30:33], v[74:77], v[106:109], v[30:33]
	v_mfma_f32_16x16x32_bf16 v[26:29], v[66:69], v[114:117], v[26:29]
	v_mfma_f32_16x16x32_bf16 v[22:25], v[90:93], v[106:109], v[22:25]
	v_mfma_f32_16x16x32_bf16 v[18:21], v[82:85], v[114:117], v[18:21]
	v_mfma_f32_16x16x32_bf16 v[14:17], v[182:185], v[106:109], v[14:17]
	v_mfma_f32_16x16x32_bf16 v[10:13], v[178:181], v[114:117], v[10:13]
	v_mfma_f32_16x16x32_bf16 v[6:9], v[190:193], v[106:109], v[6:9]
	v_mfma_f32_16x16x32_bf16 v[2:5], v[186:189], v[114:117], v[2:5]
	v_mfma_f32_16x16x32_bf16 v[148:151], v[74:77], v[122:125], v[26:29]
	v_mfma_f32_16x16x32_bf16 v[152:155], v[90:93], v[122:125], v[18:21]
	v_mfma_f32_16x16x32_bf16 v[156:159], v[182:185], v[122:125], v[10:13]
	v_mfma_f32_16x16x32_bf16 v[178:181], v[190:193], v[122:125], v[2:5]
	s_barrier
	s_nop 1
	ds_read_b128 v[2:5], v136
	ds_read_b128 v[10:13], v136 offset:1024
	ds_read_b128 v[18:21], v136 offset:2048
	ds_read_b128 v[26:29], v136 offset:3072
	ds_read_b128 v[34:37], v134 offset:32768
	ds_read_b128 v[42:45], v134 offset:33792
	ds_read_b128 v[50:53], v133 offset:32768
	ds_read_b128 v[58:61], v133 offset:33792
	ds_read_b128 v[66:69], v132 offset:32768
	ds_read_b128 v[182:185], v132 offset:33792
	ds_read_b128 v[186:189], v131 offset:32768
	ds_read_b128 v[190:193], v131 offset:33792
	s_waitcnt vmcnt(2)
	s_barrier
	s_waitcnt lgkmcnt(0)
	v_mfma_f32_16x16x32_bf16 v[74:77], v[34:37], v[2:5], v[126:129]
	v_mfma_f32_16x16x32_bf16 v[122:125], v[42:45], v[10:13], v[74:77]
	v_mfma_f32_16x16x32_bf16 v[74:77], v[34:37], v[18:21], v[144:147]
	v_mfma_f32_16x16x32_bf16 v[126:129], v[42:45], v[26:29], v[74:77]
	v_mfma_f32_16x16x32_bf16 v[74:77], v[50:53], v[2:5], v[118:121]
	v_mfma_f32_16x16x32_bf16 v[114:117], v[58:61], v[10:13], v[74:77]
	v_mfma_f32_16x16x32_bf16 v[74:77], v[50:53], v[18:21], v[194:197]
	v_mfma_f32_16x16x32_bf16 v[118:121], v[58:61], v[26:29], v[74:77]
	v_mfma_f32_16x16x32_bf16 v[74:77], v[66:69], v[2:5], v[110:113]
	v_mfma_f32_16x16x32_bf16 v[106:109], v[182:185], v[10:13], v[74:77]
	v_mfma_f32_16x16x32_bf16 v[74:77], v[66:69], v[18:21], v[198:201]
	v_mfma_f32_16x16x32_bf16 v[110:113], v[182:185], v[26:29], v[74:77]
	v_mfma_f32_16x16x32_bf16 v[74:77], v[186:189], v[2:5], v[102:105]
	v_mfma_f32_16x16x32_bf16 v[98:101], v[190:193], v[10:13], v[74:77]
	v_mfma_f32_16x16x32_bf16 v[74:77], v[186:189], v[18:21], v[202:205]
	v_mfma_f32_16x16x32_bf16 v[102:105], v[190:193], v[26:29], v[74:77]
	s_barrier
; #define WAIT_V(n) asm volatile("s_waitcnt vmcnt(" #n ")" ::: "memory")
; #define WAIT_L(n) asm volatile("s_waitcnt lgkmcnt(" #n ")" ::: "memory")
; #define BAR __builtin_amdgcn_s_barrier()
; __device__ __forceinline__ void mainloop_8phase(const u16* __restrict__ A, const u16* __restrict__ Bt, int K,
;                                                 f32x4 (&acc)[2][2][4][2], int wid_s, int ld) {
;     ...
;     LDB(B1, 1, 1); WAIT_V(0); BAR; WAIT_L(0); MMA(0, 1, At, B1); BAR;
;     LDA(At, 1, 1); BAR; WAIT_L(0); MMA(1, 0, At, B0); MMA(1, 1, At, B1); BAR; }
;   if (wr == 0) BAR;
	ds_read_b128 v[142:145], v135
	ds_read_b128 v[194:197], v135 offset:1024
	ds_read_b128 v[198:201], v135 offset:2048
	ds_read_b128 v[202:205], v135 offset:3072
	s_waitcnt vmcnt(0)
	s_barrier
	s_waitcnt lgkmcnt(0)
	v_mfma_f32_16x16x32_bf16 v[74:77], v[34:37], v[142:145], v[94:97]
	v_mfma_f32_16x16x32_bf16 v[34:37], v[34:37], v[198:201], v[162:165]
	v_mfma_f32_16x16x32_bf16 v[94:97], v[42:45], v[202:205], v[34:37]
	v_mfma_f32_16x16x32_bf16 v[34:37], v[50:53], v[142:145], v[86:89]
	v_mfma_f32_16x16x32_bf16 v[82:85], v[58:61], v[194:197], v[34:37]
	v_mfma_f32_16x16x32_bf16 v[34:37], v[50:53], v[198:201], v[166:169]
	v_mfma_f32_16x16x32_bf16 v[86:89], v[58:61], v[202:205], v[34:37]
	v_mfma_f32_16x16x32_bf16 v[34:37], v[66:69], v[142:145], v[78:81]
	v_mfma_f32_16x16x32_bf16 v[90:93], v[42:45], v[194:197], v[74:77]
	v_mfma_f32_16x16x32_bf16 v[74:77], v[182:185], v[194:197], v[34:37]
	v_mfma_f32_16x16x32_bf16 v[34:37], v[66:69], v[198:201], v[170:173]
	v_mfma_f32_16x16x32_bf16 v[78:81], v[182:185], v[202:205], v[34:37]
	v_mfma_f32_16x16x32_bf16 v[34:37], v[186:189], v[142:145], v[70:73]
	v_mfma_f32_16x16x32_bf16 v[66:69], v[190:193], v[194:197], v[34:37]
	v_mfma_f32_16x16x32_bf16 v[34:37], v[186:189], v[198:201], v[174:177]
	v_mfma_f32_16x16x32_bf16 v[70:73], v[190:193], v[202:205], v[34:37]
	s_barrier
	ds_read_b128 v[160:163], v134 offset:49152
	ds_read_b128 v[134:137], v134 offset:50176
	ds_read_b128 v[164:167], v133 offset:49152
	ds_read_b128 v[168:171], v133 offset:50176
	ds_read_b128 v[172:175], v132 offset:49152
	ds_read_b128 v[182:185], v132 offset:50176
	ds_read_b128 v[186:189], v131 offset:49152
	ds_read_b128 v[190:193], v131 offset:50176
	s_barrier
	s_waitcnt lgkmcnt(0)
	v_mfma_f32_16x16x32_bf16 v[34:37], v[160:163], v[2:5], v[62:65]
	v_mfma_f32_16x16x32_bf16 v[58:61], v[134:137], v[10:13], v[34:37]
	v_mfma_f32_16x16x32_bf16 v[34:37], v[160:163], v[18:21], v[206:209]
	v_mfma_f32_16x16x32_bf16 v[62:65], v[134:137], v[26:29], v[34:37]
	v_mfma_f32_16x16x32_bf16 v[34:37], v[164:167], v[2:5], v[54:57]
	v_mfma_f32_16x16x32_bf16 v[50:53], v[168:171], v[10:13], v[34:37]
	v_mfma_f32_16x16x32_bf16 v[34:37], v[164:167], v[18:21], v[210:213]
	v_mfma_f32_16x16x32_bf16 v[54:57], v[168:171], v[26:29], v[34:37]
	v_mfma_f32_16x16x32_bf16 v[34:37], v[172:175], v[2:5], v[46:49]
	v_mfma_f32_16x16x32_bf16 v[42:45], v[182:185], v[10:13], v[34:37]
	v_mfma_f32_16x16x32_bf16 v[34:37], v[172:175], v[18:21], v[214:217]
	v_mfma_f32_16x16x32_bf16 v[2:5], v[186:189], v[2:5], v[38:41]
	v_mfma_f32_16x16x32_bf16 v[46:49], v[182:185], v[26:29], v[34:37]
	v_mfma_f32_16x16x32_bf16 v[34:37], v[190:193], v[10:13], v[2:5]
	v_mfma_f32_16x16x32_bf16 v[2:5], v[186:189], v[18:21], v[138:141]
	v_mfma_f32_16x16x32_bf16 v[38:41], v[190:193], v[26:29], v[2:5]
	v_mfma_f32_16x16x32_bf16 v[2:5], v[160:163], v[142:145], v[30:33]
	v_mfma_f32_16x16x32_bf16 v[26:29], v[134:137], v[194:197], v[2:5]
	v_mfma_f32_16x16x32_bf16 v[2:5], v[160:163], v[198:201], v[148:151]
	v_mfma_f32_16x16x32_bf16 v[30:33], v[134:137], v[202:205], v[2:5]
	v_mfma_f32_16x16x32_bf16 v[2:5], v[164:167], v[142:145], v[22:25]
	v_mfma_f32_16x16x32_bf16 v[18:21], v[168:171], v[194:197], v[2:5]
	v_mfma_f32_16x16x32_bf16 v[2:5], v[164:167], v[198:201], v[152:155]
	v_mfma_f32_16x16x32_bf16 v[22:25], v[168:171], v[202:205], v[2:5]
	v_mfma_f32_16x16x32_bf16 v[2:5], v[172:175], v[142:145], v[14:17]
	v_mfma_f32_16x16x32_bf16 v[10:13], v[182:185], v[194:197], v[2:5]
	v_mfma_f32_16x16x32_bf16 v[2:5], v[172:175], v[198:201], v[156:159]
	v_mfma_f32_16x16x32_bf16 v[14:17], v[182:185], v[202:205], v[2:5]
	v_mfma_f32_16x16x32_bf16 v[2:5], v[186:189], v[142:145], v[6:9]
	v_mfma_f32_16x16x32_bf16 v[6:9], v[186:189], v[198:201], v[178:181]
	v_mfma_f32_16x16x32_bf16 v[2:5], v[190:193], v[194:197], v[2:5]
	v_mfma_f32_16x16x32_bf16 v[6:9], v[190:193], v[202:205], v[6:9]
	s_movk_i32 s2, 0x100
	v_cmp_gt_u32_e32 vcc, s2, v0
	s_barrier
	s_and_saveexec_b64 s[2:3], vcc
	s_cbranch_execz .LBB0_568
	s_barrier
